# shortened half-to-half hand-off: s_setprio 1 hoisted before the load segment's waits, redundant lgkmcnt(0) after the barrier dropped, s_setprio 0 moved behind the MFMA block's closing barrier
# speedup vs baseline: 1.0240x; 1.0240x over previous
;     __device__ __forceinline__ bool next(int i, Unit& u) const { if (!base.next(i >> 1, u)) return false; if (i & 1) { u.pm += 64; u.pn += 8; } return true; }
; #define PG8_STAGE(bufoff, gbase, voff) do { _Pragma("unroll") for (int _i = 0; _i < 2; ++_i) \
;         __builtin_amdgcn_global_load_lds((const unsigned*)((const char*)(gbase) + (voff)[_i]), (PG8_LAS unsigned*)(lds + (bufoff) + ldsw + _i * 8192), 16, 0, 0); } while (0)
; #define PG8_LDA(dst, b, h) do { _Pragma("unroll") for (int m = 0; m < 4; ++m) _Pragma("unroll") for (int k = 0; k < 2; ++k) dst[m][k] = *(const PG8_LAS bf16x8*)(lds + PG8_SA(b, h) + aoff + m * 2048 + k * 1024); } while (0)
; #define PG8_LDB(dst, b, h) do { _Pragma("unroll") for (int n = 0; n < 2; ++n) _Pragma("unroll") for (int k = 0; k < 2; ++k) dst[n][k] = *(const PG8_LAS bf16x8*)(lds + PG8_SB(b, h) + boff + n * 2048 + k * 1024); } while (0)
; #define PG8_WAIT_V(n) asm volatile("s_waitcnt vmcnt(" #n ")" ::: "memory")
; #define PG8_BAR __builtin_amdgcn_s_barrier()
; template <class Epi, class Sched, bool ALIGN_EPI = false, bool SP2 = false>
; __device__ __forceinline__ void gemm_phase(PG8_LAS unsigned char* lds, const Gemm g, const Sched& S, const Epi& E) {
;     ...
;         const bool has_next = S.next(ui + 1, nxt);
;         const char* nA = has_next ? (const char*)g.A + (size_t)nxt.pm * tstep : cA; const char* nB = has_next ? (const char*)g.Bt + (size_t)nxt.pn * tstep : cB;
;         for (int t = 0; t < nt; t += 2) {
;             const bool last = (t == nt - 2);
;             const char* a1 = cA + (size_t)(t + 1) * kstep;
;             const char* a2 = last ? nA : cA + (size_t)(t + 2) * kstep; const char* b2 = last ? nB : cB + (size_t)(t + 2) * kstep;
;             const char* a3 = a2 + kstep; const char* b3 = b2 + kstep;
;             if (last && has_next) S.a_ready(nxt);
;             if constexpr (SP2) {
;             PG8_LDB(B0, 0, 0); PG8_LDB(B1, 0, 1); PG8_SCHED; PG8_LDA(At, 0, 0); PG8_STAGE(PG8_SA(1, 1), a1 + hstep, voffA);
;             PG8_WAIT_V(8); PG8_WAIT_L(0); PG8_BAR; PG8_MMA(0, 0, At, B0); PG8_MMA(0, 1, At, B1); PG8_BAR; PG8_SCHED;
;             PG8_LDA(At, 0, 1); PG8_STAGE(PG8_SB(0, 0), b2, voffB); PG8_STAGE(PG8_SB(0, 1), b2 + hstep, voffB); PG8_STAGE(PG8_SA(0, 0), a2, voffA);
;             PG8_WAIT_V(8); PG8_WAIT_L(0); PG8_BAR; PG8_MMA(1, 0, At, B0); PG8_MMA(1, 1, At, B1); PG8_BAR; PG8_SCHED;
.LBB0_204:
	s_ashr_i32 s21, s20, 31
	s_lshl_b64 s[24:25], s[20:21], 20
	v_readlane_b32 s26, v236, 50
	v_readlane_b32 s27, v236, 51
	s_add_u32 s24, s26, s24
	s_addc_u32 s25, s27, s25
	s_and_b64 s[26:27], s[8:9], exec
	s_cselect_b32 s1, s25, s5
	s_cselect_b32 s3, s24, s4
	s_ashr_i32 s23, s22, 31
	s_lshl_b64 s[26:27], s[22:23], 20
	s_add_u32 s26, s10, s26
	s_addc_u32 s27, s11, s27
	s_and_b64 s[28:29], s[8:9], exec
	s_cselect_b32 s21, s27, s7
	s_cselect_b32 s23, s26, s6
	s_add_u32 s4, s4, 0x80080
	s_addc_u32 s5, s5, 0
	s_add_u32 s33, s6, 0x100
	s_addc_u32 s50, s7, 0
	s_mov_b32 s51, -2
	s_waitcnt vmcnt(0)
	ds_read_b128 v[128:131], v190
	ds_read_b128 v[132:135], v190 offset:1024
	ds_read_b128 v[136:139], v190 offset:2048
	ds_read_b128 v[140:143], v190 offset:3072
	ds_read_b128 v[144:147], v191
	ds_read_b128 v[148:151], v191 offset:1024
	ds_read_b128 v[152:155], v191 offset:2048
	ds_read_b128 v[156:159], v191 offset:3072
	s_add_u32 s6, s4, 0xfff80080
	s_addc_u32 s7, s5, -1
	s_cmp_eq_u32 s51, 28
	s_cselect_b32 s29, s1, s7
	s_cselect_b32 s28, s3, s6
	s_cselect_b32 s7, s21, s50
	s_cselect_b32 s6, s23, s33
	v_lshl_add_u64 v[184:185], s[4:5], 0, v[172:173]
	s_add_i32 m0, s31, 0xc000
	ds_read_b128 v[180:183], v192
	ds_read_b128 v[194:197], v192 offset:1024
	ds_read_b128 v[198:201], v192 offset:2048
	ds_read_b128 v[202:205], v192 offset:3072
	ds_read_b128 v[206:209], v192 offset:4096
	ds_read_b128 v[210:213], v192 offset:5120
	ds_read_b128 v[214:217], v192 offset:6144
	ds_read_b128 v[218:221], v192 offset:7168
	global_load_lds_dwordx4 v[184:185], off
	v_lshl_add_u64 v[184:185], s[4:5], 0, v[174:175]
	s_add_i32 m0, s31, 0xe000
	s_nop 0
	global_load_lds_dwordx4 v[184:185], off
	s_setprio 1
	s_waitcnt vmcnt(8)
	s_waitcnt lgkmcnt(0)
	s_barrier
	v_mfma_f32_16x16x32_bf16 v[124:127], v[128:131], v[180:183], 0
	v_mfma_f32_16x16x32_bf16 v[120:123], v[136:139], v[180:183], 0
	v_mfma_f32_16x16x32_bf16 v[108:111], v[128:131], v[198:201], 0
	v_mfma_f32_16x16x32_bf16 v[104:107], v[136:139], v[198:201], 0
	v_mfma_f32_16x16x32_bf16 v[92:95], v[128:131], v[206:209], 0
	v_mfma_f32_16x16x32_bf16 v[88:91], v[136:139], v[206:209], 0
	v_mfma_f32_16x16x32_bf16 v[76:79], v[128:131], v[214:217], 0
	v_mfma_f32_16x16x32_bf16 v[72:75], v[136:139], v[214:217], 0
	v_mfma_f32_16x16x32_bf16 v[124:127], v[132:135], v[194:197], v[124:127]
	v_mfma_f32_16x16x32_bf16 v[120:123], v[140:143], v[194:197], v[120:123]
	v_mfma_f32_16x16x32_bf16 v[108:111], v[132:135], v[202:205], v[108:111]
	v_mfma_f32_16x16x32_bf16 v[104:107], v[140:143], v[202:205], v[104:107]
	v_mfma_f32_16x16x32_bf16 v[92:95], v[132:135], v[210:213], v[92:95]
	v_mfma_f32_16x16x32_bf16 v[88:91], v[140:143], v[210:213], v[88:91]
	v_mfma_f32_16x16x32_bf16 v[76:79], v[132:135], v[218:221], v[76:79]
	v_mfma_f32_16x16x32_bf16 v[72:75], v[140:143], v[218:221], v[72:75]
	s_setprio 0
	s_setprio 1
	v_mfma_f32_16x16x32_bf16 v[116:119], v[144:147], v[180:183], 0
	v_mfma_f32_16x16x32_bf16 v[112:115], v[152:155], v[180:183], 0
	v_mfma_f32_16x16x32_bf16 v[100:103], v[144:147], v[198:201], 0
	v_mfma_f32_16x16x32_bf16 v[96:99], v[152:155], v[198:201], 0
	v_mfma_f32_16x16x32_bf16 v[84:87], v[144:147], v[206:209], 0
	v_mfma_f32_16x16x32_bf16 v[80:83], v[152:155], v[206:209], 0
	v_mfma_f32_16x16x32_bf16 v[68:71], v[144:147], v[214:217], 0
	v_mfma_f32_16x16x32_bf16 v[64:67], v[152:155], v[214:217], 0
	v_mfma_f32_16x16x32_bf16 v[116:119], v[148:151], v[194:197], v[116:119]
	v_mfma_f32_16x16x32_bf16 v[112:115], v[156:159], v[194:197], v[112:115]
	v_mfma_f32_16x16x32_bf16 v[100:103], v[148:151], v[202:205], v[100:103]
	v_mfma_f32_16x16x32_bf16 v[96:99], v[156:159], v[202:205], v[96:99]
	v_mfma_f32_16x16x32_bf16 v[84:87], v[148:151], v[210:213], v[84:87]
	v_mfma_f32_16x16x32_bf16 v[80:83], v[156:159], v[210:213], v[80:83]
	v_mfma_f32_16x16x32_bf16 v[68:71], v[148:151], v[218:221], v[68:71]
	v_mfma_f32_16x16x32_bf16 v[64:67], v[156:159], v[218:221], v[64:67]
	s_barrier
	s_setprio 0
	s_add_i32 s52, s43, s30
	v_lshl_add_u64 v[184:185], s[6:7], 0, v[164:165]
	s_mov_b32 m0, s52
	ds_read_b128 v[180:183], v192 offset:16384
	ds_read_b128 v[194:197], v192 offset:17408
	ds_read_b128 v[198:201], v192 offset:18432
	ds_read_b128 v[202:205], v192 offset:19456
	ds_read_b128 v[206:209], v192 offset:20480
	ds_read_b128 v[210:213], v192 offset:21504
	ds_read_b128 v[214:217], v192 offset:22528
	ds_read_b128 v[218:221], v192 offset:23552
	global_load_lds_dwordx4 v[184:185], off
	s_add_i32 m0, s52, 0x2000
	s_add_u32 s52, s6, 0x80000
	v_lshl_add_u64 v[222:223], s[6:7], 0, v[168:169]
	s_addc_u32 s53, s7, 0
	s_add_i32 s54, s44, s30
	global_load_lds_dwordx4 v[222:223], off
	v_lshl_add_u64 v[224:225], s[52:53], 0, v[164:165]
	s_mov_b32 m0, s54
	v_lshl_add_u64 v[226:227], s[28:29], 0, v[166:167]
	global_load_lds_dwordx4 v[224:225], off
	v_lshl_add_u64 v[224:225], s[52:53], 0, v[168:169]
	s_add_i32 m0, s54, 0x2000
	s_nop 0
	global_load_lds_dwordx4 v[224:225], off
	v_lshl_add_u64 v[224:225], s[28:29], 0, v[162:163]
	s_mov_b32 m0, s31
	s_nop 0
	global_load_lds_dwordx4 v[224:225], off
	s_mov_b32 m0, s34
	s_nop 0
	global_load_lds_dwordx4 v[226:227], off
	s_setprio 1
	s_waitcnt vmcnt(8)
	s_waitcnt lgkmcnt(0)
	s_barrier
; #define PG8_STAGE(bufoff, gbase, voff) do { _Pragma("unroll") for (int _i = 0; _i < 2; ++_i) \
;         __builtin_amdgcn_global_load_lds((const unsigned*)((const char*)(gbase) + (voff)[_i]), (PG8_LAS unsigned*)(lds + (bufoff) + ldsw + _i * 8192), 16, 0, 0); } while (0)
; #define PG8_LDA(dst, b, h) do { _Pragma("unroll") for (int m = 0; m < 4; ++m) _Pragma("unroll") for (int k = 0; k < 2; ++k) dst[m][k] = *(const PG8_LAS bf16x8*)(lds + PG8_SA(b, h) + aoff + m * 2048 + k * 1024); } while (0)
; #define PG8_LDB(dst, b, h) do { _Pragma("unroll") for (int n = 0; n < 2; ++n) _Pragma("unroll") for (int k = 0; k < 2; ++k) dst[n][k] = *(const PG8_LAS bf16x8*)(lds + PG8_SB(b, h) + boff + n * 2048 + k * 1024); } while (0)
; #define PG8_MMA(ai, bj, At, Bt) do { __builtin_amdgcn_s_setprio(1); _Pragma("unroll") for (int m = 0; m < 4; ++m) _Pragma("unroll") for (int n = 0; n < 2; ++n) _Pragma("unroll") for (int k = 0; k < 2; ++k) \
;         acc[ai][bj][m][n] = __builtin_amdgcn_mfma_f32_16x16x32_bf16(Bt[n][k], At[m][k], acc[ai][bj][m][n], 0, 0, 0); __builtin_amdgcn_s_setprio(0); } while (0)
; #define PG8_WAIT_V(n) asm volatile("s_waitcnt vmcnt(" #n ")" ::: "memory")
; #define PG8_WAIT_L(n) asm volatile("s_waitcnt lgkmcnt(" #n ")" ::: "memory")
; #define PG8_BAR __builtin_amdgcn_s_barrier()
; #define PG8_SCHED __builtin_amdgcn_sched_barrier(0)
; template <class Epi, class Sched, bool ALIGN_EPI = false, bool SP2 = false>
; __device__ __forceinline__ void gemm_phase(PG8_LAS unsigned char* lds, const Gemm g, const Sched& S, const Epi& E) {
;     ...
;             PG8_WAIT_V(8); PG8_WAIT_L(0); PG8_BAR; PG8_MMA(1, 0, At, B0); PG8_MMA(1, 1, At, B1); PG8_BAR; PG8_SCHED;
;             PG8_LDB(B0, 1, 0); PG8_LDB(B1, 1, 1); PG8_SCHED; PG8_LDA(At, 1, 0); PG8_STAGE(PG8_SA(0, 1), a2 + hstep, voffA);
;             PG8_WAIT_V(8); PG8_WAIT_L(0); PG8_BAR; PG8_MMA(0, 0, At, B0); PG8_MMA(0, 1, At, B1); PG8_BAR; PG8_SCHED;
	v_mfma_f32_16x16x32_bf16 v[60:63], v[128:131], v[180:183], 0
	v_mfma_f32_16x16x32_bf16 v[56:59], v[136:139], v[180:183], 0
	v_mfma_f32_16x16x32_bf16 v[44:47], v[128:131], v[198:201], 0
	v_mfma_f32_16x16x32_bf16 v[40:43], v[136:139], v[198:201], 0
	v_mfma_f32_16x16x32_bf16 v[28:31], v[128:131], v[206:209], 0
	v_mfma_f32_16x16x32_bf16 v[24:27], v[136:139], v[206:209], 0
	v_mfma_f32_16x16x32_bf16 v[12:15], v[128:131], v[214:217], 0
	v_mfma_f32_16x16x32_bf16 v[8:11], v[136:139], v[214:217], 0
	v_mfma_f32_16x16x32_bf16 v[60:63], v[132:135], v[194:197], v[60:63]
	v_mfma_f32_16x16x32_bf16 v[56:59], v[140:143], v[194:197], v[56:59]
	v_mfma_f32_16x16x32_bf16 v[44:47], v[132:135], v[202:205], v[44:47]
	v_mfma_f32_16x16x32_bf16 v[40:43], v[140:143], v[202:205], v[40:43]
	v_mfma_f32_16x16x32_bf16 v[28:31], v[132:135], v[210:213], v[28:31]
	v_mfma_f32_16x16x32_bf16 v[24:27], v[140:143], v[210:213], v[24:27]
	v_mfma_f32_16x16x32_bf16 v[12:15], v[132:135], v[218:221], v[12:15]
	v_mfma_f32_16x16x32_bf16 v[8:11], v[140:143], v[218:221], v[8:11]
	s_setprio 0
	s_setprio 1
	v_mfma_f32_16x16x32_bf16 v[52:55], v[144:147], v[180:183], 0
	v_mfma_f32_16x16x32_bf16 v[48:51], v[152:155], v[180:183], 0
	v_mfma_f32_16x16x32_bf16 v[36:39], v[144:147], v[198:201], 0
	v_mfma_f32_16x16x32_bf16 v[32:35], v[152:155], v[198:201], 0
	v_mfma_f32_16x16x32_bf16 v[20:23], v[144:147], v[206:209], 0
	v_mfma_f32_16x16x32_bf16 v[16:19], v[152:155], v[206:209], 0
	v_mfma_f32_16x16x32_bf16 v[4:7], v[144:147], v[214:217], 0
	v_mfma_f32_16x16x32_bf16 v[0:3], v[152:155], v[214:217], 0
	v_mfma_f32_16x16x32_bf16 v[52:55], v[148:151], v[194:197], v[52:55]
	v_mfma_f32_16x16x32_bf16 v[48:51], v[156:159], v[194:197], v[48:51]
	v_mfma_f32_16x16x32_bf16 v[36:39], v[148:151], v[202:205], v[36:39]
	v_mfma_f32_16x16x32_bf16 v[32:35], v[156:159], v[202:205], v[32:35]
	v_mfma_f32_16x16x32_bf16 v[20:23], v[148:151], v[210:213], v[20:23]
	v_mfma_f32_16x16x32_bf16 v[16:19], v[156:159], v[210:213], v[16:19]
	v_mfma_f32_16x16x32_bf16 v[4:7], v[148:151], v[218:221], v[4:7]
	v_mfma_f32_16x16x32_bf16 v[0:3], v[156:159], v[218:221], v[0:3]
	s_barrier
	s_setprio 0
	s_add_i32 s52, 0, 0x18000
	s_add_i32 s53, 0, 0x1c000
	v_add_u32_e32 v140, s52, v188
	v_add_u32_e32 v156, s53, v188
	ds_read_b128 v[128:131], v140
	ds_read_b128 v[132:135], v140 offset:1024
	ds_read_b128 v[136:139], v140 offset:2048
	ds_read_b128 v[140:143], v140 offset:3072
	ds_read_b128 v[144:147], v156
	ds_read_b128 v[148:151], v156 offset:1024
	ds_read_b128 v[152:155], v156 offset:2048
	ds_read_b128 v[156:159], v156 offset:3072
	s_add_u32 s28, s28, 0x80000
	s_addc_u32 s29, s29, 0
	s_mov_b32 m0, s35
	v_lshl_add_u64 v[228:229], s[28:29], 0, v[162:163]
	ds_read_b128 v[180:183], v192 offset:32768
	ds_read_b128 v[194:197], v192 offset:33792
	ds_read_b128 v[198:201], v192 offset:34816
	ds_read_b128 v[202:205], v192 offset:35840
	ds_read_b128 v[206:209], v192 offset:36864
	ds_read_b128 v[210:213], v192 offset:37888
	ds_read_b128 v[214:217], v192 offset:38912
	ds_read_b128 v[218:221], v192 offset:39936
	global_load_lds_dwordx4 v[228:229], off
	v_lshl_add_u64 v[228:229], s[28:29], 0, v[166:167]
	s_mov_b32 m0, s36
	s_nop 0
	global_load_lds_dwordx4 v[228:229], off
	s_setprio 1
	s_waitcnt vmcnt(8)
	s_waitcnt lgkmcnt(0)
	s_barrier
	v_mfma_f32_16x16x32_bf16 v[124:127], v[128:131], v[180:183], v[124:127]
	v_mfma_f32_16x16x32_bf16 v[120:123], v[136:139], v[180:183], v[120:123]
	v_mfma_f32_16x16x32_bf16 v[108:111], v[128:131], v[198:201], v[108:111]
	v_mfma_f32_16x16x32_bf16 v[104:107], v[136:139], v[198:201], v[104:107]
	v_mfma_f32_16x16x32_bf16 v[92:95], v[128:131], v[206:209], v[92:95]
	v_mfma_f32_16x16x32_bf16 v[88:91], v[136:139], v[206:209], v[88:91]
	v_mfma_f32_16x16x32_bf16 v[76:79], v[128:131], v[214:217], v[76:79]
	v_mfma_f32_16x16x32_bf16 v[72:75], v[136:139], v[214:217], v[72:75]
	v_mfma_f32_16x16x32_bf16 v[124:127], v[132:135], v[194:197], v[124:127]
	v_mfma_f32_16x16x32_bf16 v[120:123], v[140:143], v[194:197], v[120:123]
	v_mfma_f32_16x16x32_bf16 v[108:111], v[132:135], v[202:205], v[108:111]
	v_mfma_f32_16x16x32_bf16 v[104:107], v[140:143], v[202:205], v[104:107]
	v_mfma_f32_16x16x32_bf16 v[92:95], v[132:135], v[210:213], v[92:95]
	v_mfma_f32_16x16x32_bf16 v[88:91], v[140:143], v[210:213], v[88:91]
	v_mfma_f32_16x16x32_bf16 v[76:79], v[132:135], v[218:221], v[76:79]
	v_mfma_f32_16x16x32_bf16 v[72:75], v[140:143], v[218:221], v[72:75]
	s_setprio 0
	s_setprio 1
	v_mfma_f32_16x16x32_bf16 v[116:119], v[144:147], v[180:183], v[116:119]
	v_mfma_f32_16x16x32_bf16 v[112:115], v[152:155], v[180:183], v[112:115]
	v_mfma_f32_16x16x32_bf16 v[100:103], v[144:147], v[198:201], v[100:103]
	v_mfma_f32_16x16x32_bf16 v[96:99], v[152:155], v[198:201], v[96:99]
	v_mfma_f32_16x16x32_bf16 v[84:87], v[144:147], v[206:209], v[84:87]
	v_mfma_f32_16x16x32_bf16 v[80:83], v[152:155], v[206:209], v[80:83]
	v_mfma_f32_16x16x32_bf16 v[68:71], v[144:147], v[214:217], v[68:71]
	v_mfma_f32_16x16x32_bf16 v[64:67], v[152:155], v[214:217], v[64:67]
	v_mfma_f32_16x16x32_bf16 v[116:119], v[148:151], v[194:197], v[116:119]
	v_mfma_f32_16x16x32_bf16 v[112:115], v[156:159], v[194:197], v[112:115]
	v_mfma_f32_16x16x32_bf16 v[100:103], v[148:151], v[202:205], v[100:103]
	v_mfma_f32_16x16x32_bf16 v[96:99], v[156:159], v[202:205], v[96:99]
	v_mfma_f32_16x16x32_bf16 v[84:87], v[148:151], v[210:213], v[84:87]
	v_mfma_f32_16x16x32_bf16 v[80:83], v[156:159], v[210:213], v[80:83]
	v_mfma_f32_16x16x32_bf16 v[68:71], v[148:151], v[218:221], v[68:71]
	v_mfma_f32_16x16x32_bf16 v[64:67], v[156:159], v[218:221], v[64:67]
	s_barrier
; #define PG8_STAGE(bufoff, gbase, voff) do { _Pragma("unroll") for (int _i = 0; _i < 2; ++_i) \
;         __builtin_amdgcn_global_load_lds((const unsigned*)((const char*)(gbase) + (voff)[_i]), (PG8_LAS unsigned*)(lds + (bufoff) + ldsw + _i * 8192), 16, 0, 0); } while (0)
; #define PG8_LDA(dst, b, h) do { _Pragma("unroll") for (int m = 0; m < 4; ++m) _Pragma("unroll") for (int k = 0; k < 2; ++k) dst[m][k] = *(const PG8_LAS bf16x8*)(lds + PG8_SA(b, h) + aoff + m * 2048 + k * 1024); } while (0)
; #define PG8_LDB(dst, b, h) do { _Pragma("unroll") for (int n = 0; n < 2; ++n) _Pragma("unroll") for (int k = 0; k < 2; ++k) dst[n][k] = *(const PG8_LAS bf16x8*)(lds + PG8_SB(b, h) + boff + n * 2048 + k * 1024); } while (0)
; #define PG8_MMA(ai, bj, At, Bt) do { __builtin_amdgcn_s_setprio(1); _Pragma("unroll") for (int m = 0; m < 4; ++m) _Pragma("unroll") for (int n = 0; n < 2; ++n) _Pragma("unroll") for (int k = 0; k < 2; ++k) \
;         acc[ai][bj][m][n] = __builtin_amdgcn_mfma_f32_16x16x32_bf16(Bt[n][k], At[m][k], acc[ai][bj][m][n], 0, 0, 0); __builtin_amdgcn_s_setprio(0); } while (0)
; #define PG8_WAIT_V(n) asm volatile("s_waitcnt vmcnt(" #n ")" ::: "memory")
; #define PG8_WAIT_L(n) asm volatile("s_waitcnt lgkmcnt(" #n ")" ::: "memory")
; #define PG8_BAR __builtin_amdgcn_s_barrier()
; #define PG8_SCHED __builtin_amdgcn_sched_barrier(0)
; template <class Epi, class Sched, bool ALIGN_EPI = false, bool SP2 = false>
; __device__ __forceinline__ void gemm_phase(PG8_LAS unsigned char* lds, const Gemm g, const Sched& S, const Epi& E) {
;     ...
;         for (int t = 0; t < nt; t += 2) {
;             const bool last = (t == nt - 2);
;             const char* a1 = cA + (size_t)(t + 1) * kstep;
;             const char* a2 = last ? nA : cA + (size_t)(t + 2) * kstep; const char* b2 = last ? nB : cB + (size_t)(t + 2) * kstep;
;             const char* a3 = a2 + kstep; const char* b3 = b2 + kstep;
;             if (last && has_next) S.a_ready(nxt);
;             if constexpr (SP2) {
;             PG8_LDB(B0, 0, 0); PG8_LDB(B1, 0, 1); PG8_SCHED; PG8_LDA(At, 0, 0); PG8_STAGE(PG8_SA(1, 1), a1 + hstep, voffA);
;     ...
;             PG8_LDA(At, 1, 1); PG8_STAGE(PG8_SB(1, 0), b3, voffB); PG8_STAGE(PG8_SB(1, 1), b3 + hstep, voffB); PG8_STAGE(PG8_SA(1, 0), a3, voffA);
;             PG8_WAIT_V(8); PG8_WAIT_L(0); PG8_BAR; PG8_MMA(1, 0, At, B0); PG8_MMA(1, 1, At, B1); PG8_BAR; PG8_SCHED;
	s_setprio 0
	s_add_i32 s28, s52, s30
	v_lshl_add_u64 v[184:185], v[184:185], 0, s[16:17]
	s_mov_b32 m0, s28
	ds_read_b128 v[180:183], v192 offset:49152
	ds_read_b128 v[194:197], v192 offset:50176
	ds_read_b128 v[198:201], v192 offset:51200
	ds_read_b128 v[202:205], v192 offset:52224
	ds_read_b128 v[206:209], v192 offset:53248
	ds_read_b128 v[210:213], v192 offset:54272
	ds_read_b128 v[214:217], v192 offset:55296
	ds_read_b128 v[218:221], v192 offset:56320
	global_load_lds_dwordx4 v[184:185], off
	s_add_i32 m0, s28, 0x2000
	s_add_u32 s6, s6, 0x80080
	v_lshl_add_u64 v[184:185], v[222:223], 0, s[16:17]
	s_addc_u32 s7, s7, 0
	s_add_i32 s28, s53, s30
	global_load_lds_dwordx4 v[184:185], off
	v_lshl_add_u64 v[184:185], s[6:7], 0, v[164:165]
	s_mov_b32 m0, s28
	s_nop 0
	global_load_lds_dwordx4 v[184:185], off
	v_lshl_add_u64 v[184:185], s[6:7], 0, v[168:169]
	s_add_i32 m0, s28, 0x2000
	s_nop 0
	global_load_lds_dwordx4 v[184:185], off
	v_lshl_add_u64 v[184:185], v[224:225], 0, s[16:17]
	s_mov_b32 m0, s38
	s_nop 0
	global_load_lds_dwordx4 v[184:185], off
	v_lshl_add_u64 v[184:185], v[226:227], 0, s[16:17]
	s_mov_b32 m0, s39
	s_nop 0
	global_load_lds_dwordx4 v[184:185], off
	s_setprio 1
	s_waitcnt vmcnt(8)
	s_waitcnt lgkmcnt(0)
	s_barrier
	v_mfma_f32_16x16x32_bf16 v[60:63], v[128:131], v[180:183], v[60:63]
	v_mfma_f32_16x16x32_bf16 v[56:59], v[136:139], v[180:183], v[56:59]
	v_mfma_f32_16x16x32_bf16 v[44:47], v[128:131], v[198:201], v[44:47]
	v_mfma_f32_16x16x32_bf16 v[40:43], v[136:139], v[198:201], v[40:43]
	v_mfma_f32_16x16x32_bf16 v[28:31], v[128:131], v[206:209], v[28:31]
	v_mfma_f32_16x16x32_bf16 v[24:27], v[136:139], v[206:209], v[24:27]
	v_mfma_f32_16x16x32_bf16 v[12:15], v[128:131], v[214:217], v[12:15]
	v_mfma_f32_16x16x32_bf16 v[8:11], v[136:139], v[214:217], v[8:11]
	v_mfma_f32_16x16x32_bf16 v[60:63], v[132:135], v[194:197], v[60:63]
	v_mfma_f32_16x16x32_bf16 v[56:59], v[140:143], v[194:197], v[56:59]
	v_mfma_f32_16x16x32_bf16 v[44:47], v[132:135], v[202:205], v[44:47]
	v_mfma_f32_16x16x32_bf16 v[40:43], v[140:143], v[202:205], v[40:43]
	v_mfma_f32_16x16x32_bf16 v[28:31], v[132:135], v[210:213], v[28:31]
	v_mfma_f32_16x16x32_bf16 v[24:27], v[140:143], v[210:213], v[24:27]
	v_mfma_f32_16x16x32_bf16 v[12:15], v[132:135], v[218:221], v[12:15]
	v_mfma_f32_16x16x32_bf16 v[8:11], v[140:143], v[218:221], v[8:11]
	s_setprio 0
	s_setprio 1
	v_mfma_f32_16x16x32_bf16 v[52:55], v[144:147], v[180:183], v[52:55]
	v_mfma_f32_16x16x32_bf16 v[48:51], v[152:155], v[180:183], v[48:51]
	v_mfma_f32_16x16x32_bf16 v[36:39], v[144:147], v[198:201], v[36:39]
	v_mfma_f32_16x16x32_bf16 v[32:35], v[152:155], v[198:201], v[32:35]
	v_mfma_f32_16x16x32_bf16 v[20:23], v[144:147], v[206:209], v[20:23]
	v_mfma_f32_16x16x32_bf16 v[16:19], v[152:155], v[206:209], v[16:19]
	v_mfma_f32_16x16x32_bf16 v[4:7], v[144:147], v[214:217], v[4:7]
	v_mfma_f32_16x16x32_bf16 v[0:3], v[152:155], v[214:217], v[0:3]
	v_mfma_f32_16x16x32_bf16 v[52:55], v[148:151], v[194:197], v[52:55]
	v_mfma_f32_16x16x32_bf16 v[48:51], v[156:159], v[194:197], v[48:51]
	v_mfma_f32_16x16x32_bf16 v[36:39], v[148:151], v[202:205], v[36:39]
	v_mfma_f32_16x16x32_bf16 v[32:35], v[156:159], v[202:205], v[32:35]
	v_mfma_f32_16x16x32_bf16 v[20:23], v[148:151], v[210:213], v[20:23]
	v_mfma_f32_16x16x32_bf16 v[16:19], v[156:159], v[210:213], v[16:19]
	v_mfma_f32_16x16x32_bf16 v[4:7], v[148:151], v[218:221], v[4:7]
	v_mfma_f32_16x16x32_bf16 v[0:3], v[156:159], v[218:221], v[0:3]
	s_barrier
	s_setprio 0
	s_add_i32 s51, s51, 2
	s_add_u32 s4, s4, 0x100
	s_addc_u32 s5, s5, 0
	s_add_u32 s33, s33, 0x100
	s_addc_u32 s50, s50, 0
	s_cmp_gt_u32 s51, 29
.LBB0_205:
	ds_read_b128 v[128:131], v190
	ds_read_b128 v[132:135], v190 offset:1024
	ds_read_b128 v[136:139], v190 offset:2048
	ds_read_b128 v[140:143], v190 offset:3072
	ds_read_b128 v[144:147], v191
	ds_read_b128 v[148:151], v191 offset:1024
	ds_read_b128 v[152:155], v191 offset:2048
	ds_read_b128 v[156:159], v191 offset:3072
	s_add_u32 s6, s4, 0xfff80080
	s_addc_u32 s7, s5, -1
	s_cmp_eq_u32 s51, 28
	s_cselect_b32 s29, s1, s7
	s_cselect_b32 s28, s3, s6
	s_cselect_b32 s7, s21, s50
	s_cselect_b32 s6, s23, s33
	v_lshl_add_u64 v[184:185], s[4:5], 0, v[172:173]
	s_add_i32 m0, s31, 0xc000
	ds_read_b128 v[180:183], v192
	ds_read_b128 v[194:197], v192 offset:1024
	ds_read_b128 v[198:201], v192 offset:2048
	ds_read_b128 v[202:205], v192 offset:3072
	ds_read_b128 v[206:209], v192 offset:4096
	ds_read_b128 v[210:213], v192 offset:5120
	ds_read_b128 v[214:217], v192 offset:6144
	ds_read_b128 v[218:221], v192 offset:7168
	global_load_lds_dwordx4 v[184:185], off
	v_lshl_add_u64 v[184:185], s[4:5], 0, v[174:175]
	s_add_i32 m0, s31, 0xe000
	s_nop 0
	global_load_lds_dwordx4 v[184:185], off
	s_setprio 1
	s_waitcnt vmcnt(8)
	s_waitcnt lgkmcnt(0)
	s_barrier
; #define PG8_STAGE(bufoff, gbase, voff) do { _Pragma("unroll") for (int _i = 0; _i < 2; ++_i) \
;         __builtin_amdgcn_global_load_lds((const unsigned*)((const char*)(gbase) + (voff)[_i]), (PG8_LAS unsigned*)(lds + (bufoff) + ldsw + _i * 8192), 16, 0, 0); } while (0)
; #define PG8_LDA(dst, b, h) do { _Pragma("unroll") for (int m = 0; m < 4; ++m) _Pragma("unroll") for (int k = 0; k < 2; ++k) dst[m][k] = *(const PG8_LAS bf16x8*)(lds + PG8_SA(b, h) + aoff + m * 2048 + k * 1024); } while (0)
; #define PG8_LDB(dst, b, h) do { _Pragma("unroll") for (int n = 0; n < 2; ++n) _Pragma("unroll") for (int k = 0; k < 2; ++k) dst[n][k] = *(const PG8_LAS bf16x8*)(lds + PG8_SB(b, h) + boff + n * 2048 + k * 1024); } while (0)
; #define PG8_MMA(ai, bj, At, Bt) do { __builtin_amdgcn_s_setprio(1); _Pragma("unroll") for (int m = 0; m < 4; ++m) _Pragma("unroll") for (int n = 0; n < 2; ++n) _Pragma("unroll") for (int k = 0; k < 2; ++k) \
;         acc[ai][bj][m][n] = __builtin_amdgcn_mfma_f32_16x16x32_bf16(Bt[n][k], At[m][k], acc[ai][bj][m][n], 0, 0, 0); __builtin_amdgcn_s_setprio(0); } while (0)
; #define PG8_WAIT_V(n) asm volatile("s_waitcnt vmcnt(" #n ")" ::: "memory")
; #define PG8_WAIT_L(n) asm volatile("s_waitcnt lgkmcnt(" #n ")" ::: "memory")
; #define PG8_BAR __builtin_amdgcn_s_barrier()
; #define PG8_SCHED __builtin_amdgcn_sched_barrier(0)
; template <class Epi, class Sched, bool ALIGN_EPI = false, bool SP2 = false>
; __device__ __forceinline__ void gemm_phase(PG8_LAS unsigned char* lds, const Gemm g, const Sched& S, const Epi& E) {
;     ...
;             PG8_LDB(B0, 0, 0); PG8_LDB(B1, 0, 1); PG8_SCHED; PG8_LDA(At, 0, 0); PG8_STAGE(PG8_SA(1, 1), a1 + hstep, voffA);
;             PG8_WAIT_V(8); PG8_WAIT_L(0); PG8_BAR; PG8_MMA(0, 0, At, B0); PG8_MMA(0, 1, At, B1); PG8_BAR; PG8_SCHED;
;             PG8_LDA(At, 0, 1); PG8_STAGE(PG8_SB(0, 0), b2, voffB); PG8_STAGE(PG8_SB(0, 1), b2 + hstep, voffB); PG8_STAGE(PG8_SA(0, 0), a2, voffA);
;             PG8_WAIT_V(8); PG8_WAIT_L(0); PG8_BAR; PG8_MMA(1, 0, At, B0); PG8_MMA(1, 1, At, B1); PG8_BAR; PG8_SCHED;
	v_mfma_f32_16x16x32_bf16 v[124:127], v[128:131], v[180:183], v[124:127]
	v_mfma_f32_16x16x32_bf16 v[120:123], v[136:139], v[180:183], v[120:123]
	v_mfma_f32_16x16x32_bf16 v[108:111], v[128:131], v[198:201], v[108:111]
	v_mfma_f32_16x16x32_bf16 v[104:107], v[136:139], v[198:201], v[104:107]
	v_mfma_f32_16x16x32_bf16 v[92:95], v[128:131], v[206:209], v[92:95]
	v_mfma_f32_16x16x32_bf16 v[88:91], v[136:139], v[206:209], v[88:91]
	v_mfma_f32_16x16x32_bf16 v[76:79], v[128:131], v[214:217], v[76:79]
	v_mfma_f32_16x16x32_bf16 v[72:75], v[136:139], v[214:217], v[72:75]
	v_mfma_f32_16x16x32_bf16 v[124:127], v[132:135], v[194:197], v[124:127]
	v_mfma_f32_16x16x32_bf16 v[120:123], v[140:143], v[194:197], v[120:123]
	v_mfma_f32_16x16x32_bf16 v[108:111], v[132:135], v[202:205], v[108:111]
	v_mfma_f32_16x16x32_bf16 v[104:107], v[140:143], v[202:205], v[104:107]
	v_mfma_f32_16x16x32_bf16 v[92:95], v[132:135], v[210:213], v[92:95]
	v_mfma_f32_16x16x32_bf16 v[88:91], v[140:143], v[210:213], v[88:91]
	v_mfma_f32_16x16x32_bf16 v[76:79], v[132:135], v[218:221], v[76:79]
	v_mfma_f32_16x16x32_bf16 v[72:75], v[140:143], v[218:221], v[72:75]
	s_setprio 0
	s_setprio 1
	v_mfma_f32_16x16x32_bf16 v[116:119], v[144:147], v[180:183], v[116:119]
	v_mfma_f32_16x16x32_bf16 v[112:115], v[152:155], v[180:183], v[112:115]
	v_mfma_f32_16x16x32_bf16 v[100:103], v[144:147], v[198:201], v[100:103]
	v_mfma_f32_16x16x32_bf16 v[96:99], v[152:155], v[198:201], v[96:99]
	v_mfma_f32_16x16x32_bf16 v[84:87], v[144:147], v[206:209], v[84:87]
	v_mfma_f32_16x16x32_bf16 v[80:83], v[152:155], v[206:209], v[80:83]
	v_mfma_f32_16x16x32_bf16 v[68:71], v[144:147], v[214:217], v[68:71]
	v_mfma_f32_16x16x32_bf16 v[64:67], v[152:155], v[214:217], v[64:67]
	v_mfma_f32_16x16x32_bf16 v[116:119], v[148:151], v[194:197], v[116:119]
	v_mfma_f32_16x16x32_bf16 v[112:115], v[156:159], v[194:197], v[112:115]
	v_mfma_f32_16x16x32_bf16 v[100:103], v[148:151], v[202:205], v[100:103]
	v_mfma_f32_16x16x32_bf16 v[96:99], v[156:159], v[202:205], v[96:99]
	v_mfma_f32_16x16x32_bf16 v[84:87], v[148:151], v[210:213], v[84:87]
	v_mfma_f32_16x16x32_bf16 v[80:83], v[156:159], v[210:213], v[80:83]
	v_mfma_f32_16x16x32_bf16 v[68:71], v[148:151], v[218:221], v[68:71]
	v_mfma_f32_16x16x32_bf16 v[64:67], v[156:159], v[218:221], v[64:67]
	s_barrier
	s_setprio 0
	s_add_i32 s52, s43, s30
	v_lshl_add_u64 v[184:185], s[6:7], 0, v[164:165]
	s_mov_b32 m0, s52
	ds_read_b128 v[180:183], v192 offset:16384
	ds_read_b128 v[194:197], v192 offset:17408
	ds_read_b128 v[198:201], v192 offset:18432
	ds_read_b128 v[202:205], v192 offset:19456
	ds_read_b128 v[206:209], v192 offset:20480
	ds_read_b128 v[210:213], v192 offset:21504
	ds_read_b128 v[214:217], v192 offset:22528
	ds_read_b128 v[218:221], v192 offset:23552
	global_load_lds_dwordx4 v[184:185], off
	s_add_i32 m0, s52, 0x2000
	s_add_u32 s52, s6, 0x80000
	v_lshl_add_u64 v[222:223], s[6:7], 0, v[168:169]
	s_addc_u32 s53, s7, 0
	s_add_i32 s54, s44, s30
	global_load_lds_dwordx4 v[222:223], off
	v_lshl_add_u64 v[224:225], s[52:53], 0, v[164:165]
	s_mov_b32 m0, s54
	v_lshl_add_u64 v[226:227], s[28:29], 0, v[166:167]
	global_load_lds_dwordx4 v[224:225], off
	v_lshl_add_u64 v[224:225], s[52:53], 0, v[168:169]
	s_add_i32 m0, s54, 0x2000
	s_nop 0
	global_load_lds_dwordx4 v[224:225], off
	v_lshl_add_u64 v[224:225], s[28:29], 0, v[162:163]
	s_mov_b32 m0, s31
	s_nop 0
	global_load_lds_dwordx4 v[224:225], off
	s_mov_b32 m0, s34
	s_nop 0
	global_load_lds_dwordx4 v[226:227], off
	s_setprio 1
	s_waitcnt vmcnt(8)
	s_waitcnt lgkmcnt(0)
	s_barrier
	v_mfma_f32_16x16x32_bf16 v[60:63], v[128:131], v[180:183], v[60:63]
	v_mfma_f32_16x16x32_bf16 v[56:59], v[136:139], v[180:183], v[56:59]
	v_mfma_f32_16x16x32_bf16 v[44:47], v[128:131], v[198:201], v[44:47]
	v_mfma_f32_16x16x32_bf16 v[40:43], v[136:139], v[198:201], v[40:43]
	v_mfma_f32_16x16x32_bf16 v[28:31], v[128:131], v[206:209], v[28:31]
	v_mfma_f32_16x16x32_bf16 v[24:27], v[136:139], v[206:209], v[24:27]
	v_mfma_f32_16x16x32_bf16 v[12:15], v[128:131], v[214:217], v[12:15]
	v_mfma_f32_16x16x32_bf16 v[8:11], v[136:139], v[214:217], v[8:11]
	v_mfma_f32_16x16x32_bf16 v[60:63], v[132:135], v[194:197], v[60:63]
	v_mfma_f32_16x16x32_bf16 v[56:59], v[140:143], v[194:197], v[56:59]
	v_mfma_f32_16x16x32_bf16 v[44:47], v[132:135], v[202:205], v[44:47]
	v_mfma_f32_16x16x32_bf16 v[40:43], v[140:143], v[202:205], v[40:43]
	v_mfma_f32_16x16x32_bf16 v[28:31], v[132:135], v[210:213], v[28:31]
	v_mfma_f32_16x16x32_bf16 v[24:27], v[140:143], v[210:213], v[24:27]
	v_mfma_f32_16x16x32_bf16 v[12:15], v[132:135], v[218:221], v[12:15]
	v_mfma_f32_16x16x32_bf16 v[8:11], v[140:143], v[218:221], v[8:11]
	s_setprio 0
	s_setprio 1
	v_mfma_f32_16x16x32_bf16 v[52:55], v[144:147], v[180:183], v[52:55]
	v_mfma_f32_16x16x32_bf16 v[48:51], v[152:155], v[180:183], v[48:51]
	v_mfma_f32_16x16x32_bf16 v[36:39], v[144:147], v[198:201], v[36:39]
	v_mfma_f32_16x16x32_bf16 v[32:35], v[152:155], v[198:201], v[32:35]
	v_mfma_f32_16x16x32_bf16 v[20:23], v[144:147], v[206:209], v[20:23]
	v_mfma_f32_16x16x32_bf16 v[16:19], v[152:155], v[206:209], v[16:19]
	v_mfma_f32_16x16x32_bf16 v[4:7], v[144:147], v[214:217], v[4:7]
	v_mfma_f32_16x16x32_bf16 v[0:3], v[152:155], v[214:217], v[0:3]
	v_mfma_f32_16x16x32_bf16 v[52:55], v[148:151], v[194:197], v[52:55]
	v_mfma_f32_16x16x32_bf16 v[48:51], v[156:159], v[194:197], v[48:51]
	v_mfma_f32_16x16x32_bf16 v[36:39], v[148:151], v[202:205], v[36:39]
	v_mfma_f32_16x16x32_bf16 v[32:35], v[156:159], v[202:205], v[32:35]
	v_mfma_f32_16x16x32_bf16 v[20:23], v[148:151], v[210:213], v[20:23]
	v_mfma_f32_16x16x32_bf16 v[16:19], v[156:159], v[210:213], v[16:19]
	v_mfma_f32_16x16x32_bf16 v[4:7], v[148:151], v[218:221], v[4:7]
	v_mfma_f32_16x16x32_bf16 v[0:3], v[156:159], v[218:221], v[0:3]
	s_barrier
; #define PG8_STAGE(bufoff, gbase, voff) do { _Pragma("unroll") for (int _i = 0; _i < 2; ++_i) \
;         __builtin_amdgcn_global_load_lds((const unsigned*)((const char*)(gbase) + (voff)[_i]), (PG8_LAS unsigned*)(lds + (bufoff) + ldsw + _i * 8192), 16, 0, 0); } while (0)
; #define PG8_LDA(dst, b, h) do { _Pragma("unroll") for (int m = 0; m < 4; ++m) _Pragma("unroll") for (int k = 0; k < 2; ++k) dst[m][k] = *(const PG8_LAS bf16x8*)(lds + PG8_SA(b, h) + aoff + m * 2048 + k * 1024); } while (0)
; #define PG8_LDB(dst, b, h) do { _Pragma("unroll") for (int n = 0; n < 2; ++n) _Pragma("unroll") for (int k = 0; k < 2; ++k) dst[n][k] = *(const PG8_LAS bf16x8*)(lds + PG8_SB(b, h) + boff + n * 2048 + k * 1024); } while (0)
; #define PG8_MMA(ai, bj, At, Bt) do { __builtin_amdgcn_s_setprio(1); _Pragma("unroll") for (int m = 0; m < 4; ++m) _Pragma("unroll") for (int n = 0; n < 2; ++n) _Pragma("unroll") for (int k = 0; k < 2; ++k) \
;         acc[ai][bj][m][n] = __builtin_amdgcn_mfma_f32_16x16x32_bf16(Bt[n][k], At[m][k], acc[ai][bj][m][n], 0, 0, 0); __builtin_amdgcn_s_setprio(0); } while (0)
; #define PG8_WAIT_V(n) asm volatile("s_waitcnt vmcnt(" #n ")" ::: "memory")
; #define PG8_WAIT_L(n) asm volatile("s_waitcnt lgkmcnt(" #n ")" ::: "memory")
; #define PG8_BAR __builtin_amdgcn_s_barrier()
; #define PG8_SCHED __builtin_amdgcn_sched_barrier(0)
; template <class Epi, class Sched, bool ALIGN_EPI = false, bool SP2 = false>
; __device__ __forceinline__ void gemm_phase(PG8_LAS unsigned char* lds, const Gemm g, const Sched& S, const Epi& E) {
;     ...
;             PG8_LDB(B0, 1, 0); PG8_LDB(B1, 1, 1); PG8_SCHED; PG8_LDA(At, 1, 0); PG8_STAGE(PG8_SA(0, 1), a2 + hstep, voffA);
;             PG8_WAIT_V(8); PG8_WAIT_L(0); PG8_BAR; PG8_MMA(0, 0, At, B0); PG8_MMA(0, 1, At, B1); PG8_BAR; PG8_SCHED;
	s_setprio 0
	s_add_i32 s52, 0, 0x18000
	s_add_i32 s53, 0, 0x1c000
	v_add_u32_e32 v140, s52, v188
	v_add_u32_e32 v156, s53, v188
	ds_read_b128 v[128:131], v140
	ds_read_b128 v[132:135], v140 offset:1024
	ds_read_b128 v[136:139], v140 offset:2048
	ds_read_b128 v[140:143], v140 offset:3072
	ds_read_b128 v[144:147], v156
	ds_read_b128 v[148:151], v156 offset:1024
	ds_read_b128 v[152:155], v156 offset:2048
	ds_read_b128 v[156:159], v156 offset:3072
	s_add_u32 s28, s28, 0x80000
	s_addc_u32 s29, s29, 0
	s_mov_b32 m0, s35
	v_lshl_add_u64 v[228:229], s[28:29], 0, v[162:163]
	ds_read_b128 v[180:183], v192 offset:32768
	ds_read_b128 v[194:197], v192 offset:33792
	ds_read_b128 v[198:201], v192 offset:34816
	ds_read_b128 v[202:205], v192 offset:35840
	ds_read_b128 v[206:209], v192 offset:36864
	ds_read_b128 v[210:213], v192 offset:37888
	ds_read_b128 v[214:217], v192 offset:38912
	ds_read_b128 v[218:221], v192 offset:39936
	global_load_lds_dwordx4 v[228:229], off
	v_lshl_add_u64 v[228:229], s[28:29], 0, v[166:167]
	s_mov_b32 m0, s36
	s_nop 0
	global_load_lds_dwordx4 v[228:229], off
	s_setprio 1
	s_waitcnt vmcnt(8)
	s_waitcnt lgkmcnt(0)
	s_barrier
	v_mfma_f32_16x16x32_bf16 v[124:127], v[128:131], v[180:183], v[124:127]
	v_mfma_f32_16x16x32_bf16 v[120:123], v[136:139], v[180:183], v[120:123]
	v_mfma_f32_16x16x32_bf16 v[108:111], v[128:131], v[198:201], v[108:111]
	v_mfma_f32_16x16x32_bf16 v[104:107], v[136:139], v[198:201], v[104:107]
	v_mfma_f32_16x16x32_bf16 v[92:95], v[128:131], v[206:209], v[92:95]
	v_mfma_f32_16x16x32_bf16 v[88:91], v[136:139], v[206:209], v[88:91]
	v_mfma_f32_16x16x32_bf16 v[76:79], v[128:131], v[214:217], v[76:79]
	v_mfma_f32_16x16x32_bf16 v[72:75], v[136:139], v[214:217], v[72:75]
	v_mfma_f32_16x16x32_bf16 v[124:127], v[132:135], v[194:197], v[124:127]
	v_mfma_f32_16x16x32_bf16 v[120:123], v[140:143], v[194:197], v[120:123]
	v_mfma_f32_16x16x32_bf16 v[108:111], v[132:135], v[202:205], v[108:111]
	v_mfma_f32_16x16x32_bf16 v[104:107], v[140:143], v[202:205], v[104:107]
	v_mfma_f32_16x16x32_bf16 v[92:95], v[132:135], v[210:213], v[92:95]
	v_mfma_f32_16x16x32_bf16 v[88:91], v[140:143], v[210:213], v[88:91]
	v_mfma_f32_16x16x32_bf16 v[76:79], v[132:135], v[218:221], v[76:79]
	v_mfma_f32_16x16x32_bf16 v[72:75], v[140:143], v[218:221], v[72:75]
	s_setprio 0
	s_setprio 1
	v_mfma_f32_16x16x32_bf16 v[116:119], v[144:147], v[180:183], v[116:119]
	v_mfma_f32_16x16x32_bf16 v[112:115], v[152:155], v[180:183], v[112:115]
	v_mfma_f32_16x16x32_bf16 v[100:103], v[144:147], v[198:201], v[100:103]
	v_mfma_f32_16x16x32_bf16 v[96:99], v[152:155], v[198:201], v[96:99]
	v_mfma_f32_16x16x32_bf16 v[84:87], v[144:147], v[206:209], v[84:87]
	v_mfma_f32_16x16x32_bf16 v[80:83], v[152:155], v[206:209], v[80:83]
	v_mfma_f32_16x16x32_bf16 v[68:71], v[144:147], v[214:217], v[68:71]
	v_mfma_f32_16x16x32_bf16 v[64:67], v[152:155], v[214:217], v[64:67]
	v_mfma_f32_16x16x32_bf16 v[116:119], v[148:151], v[194:197], v[116:119]
	v_mfma_f32_16x16x32_bf16 v[112:115], v[156:159], v[194:197], v[112:115]
	v_mfma_f32_16x16x32_bf16 v[100:103], v[148:151], v[202:205], v[100:103]
	v_mfma_f32_16x16x32_bf16 v[96:99], v[156:159], v[202:205], v[96:99]
	v_mfma_f32_16x16x32_bf16 v[84:87], v[148:151], v[210:213], v[84:87]
	v_mfma_f32_16x16x32_bf16 v[80:83], v[156:159], v[210:213], v[80:83]
	v_mfma_f32_16x16x32_bf16 v[68:71], v[148:151], v[218:221], v[68:71]
	v_mfma_f32_16x16x32_bf16 v[64:67], v[156:159], v[218:221], v[64:67]
	s_barrier
; #define PG8_STAGE(bufoff, gbase, voff) do { _Pragma("unroll") for (int _i = 0; _i < 2; ++_i) \
;         __builtin_amdgcn_global_load_lds((const unsigned*)((const char*)(gbase) + (voff)[_i]), (PG8_LAS unsigned*)(lds + (bufoff) + ldsw + _i * 8192), 16, 0, 0); } while (0)
; #define PG8_LDA(dst, b, h) do { _Pragma("unroll") for (int m = 0; m < 4; ++m) _Pragma("unroll") for (int k = 0; k < 2; ++k) dst[m][k] = *(const PG8_LAS bf16x8*)(lds + PG8_SA(b, h) + aoff + m * 2048 + k * 1024); } while (0)
; #define PG8_MMA(ai, bj, At, Bt) do { __builtin_amdgcn_s_setprio(1); _Pragma("unroll") for (int m = 0; m < 4; ++m) _Pragma("unroll") for (int n = 0; n < 2; ++n) _Pragma("unroll") for (int k = 0; k < 2; ++k) \
;         acc[ai][bj][m][n] = __builtin_amdgcn_mfma_f32_16x16x32_bf16(Bt[n][k], At[m][k], acc[ai][bj][m][n], 0, 0, 0); __builtin_amdgcn_s_setprio(0); } while (0)
; #define PG8_WAIT_V(n) asm volatile("s_waitcnt vmcnt(" #n ")" ::: "memory")
; #define PG8_WAIT_L(n) asm volatile("s_waitcnt lgkmcnt(" #n ")" ::: "memory")
; #define PG8_BAR __builtin_amdgcn_s_barrier()
; #define PG8_SCHED __builtin_amdgcn_sched_barrier(0)
; template <class Epi, class Sched, bool ALIGN_EPI = false, bool SP2 = false>
; __device__ __forceinline__ void gemm_phase(PG8_LAS unsigned char* lds, const Gemm g, const Sched& S, const Epi& E) {
;     ...
;             PG8_LDA(At, 1, 1); PG8_STAGE(PG8_SB(1, 0), b3, voffB); PG8_STAGE(PG8_SB(1, 1), b3 + hstep, voffB); PG8_STAGE(PG8_SA(1, 0), a3, voffA);
;             PG8_WAIT_V(8); PG8_WAIT_L(0); PG8_BAR; PG8_MMA(1, 0, At, B0); PG8_MMA(1, 1, At, B1); PG8_BAR; PG8_SCHED;
;     ...
;         if constexpr (ALIGN_EPI) { if (wr == 0) PG8_BAR; }
	s_setprio 0
	s_add_i32 s28, s52, s30
	v_lshl_add_u64 v[184:185], v[184:185], 0, s[16:17]
	s_mov_b32 m0, s28
	ds_read_b128 v[180:183], v192 offset:49152
	ds_read_b128 v[194:197], v192 offset:50176
	ds_read_b128 v[198:201], v192 offset:51200
	ds_read_b128 v[202:205], v192 offset:52224
	ds_read_b128 v[206:209], v192 offset:53248
	ds_read_b128 v[210:213], v192 offset:54272
	ds_read_b128 v[214:217], v192 offset:55296
	ds_read_b128 v[218:221], v192 offset:56320
	global_load_lds_dwordx4 v[184:185], off
	s_add_i32 m0, s28, 0x2000
	s_add_u32 s6, s6, 0x80080
	v_lshl_add_u64 v[184:185], v[222:223], 0, s[16:17]
	s_addc_u32 s7, s7, 0
	s_add_i32 s28, s53, s30
	global_load_lds_dwordx4 v[184:185], off
	v_lshl_add_u64 v[184:185], s[6:7], 0, v[164:165]
	s_mov_b32 m0, s28
	s_nop 0
	global_load_lds_dwordx4 v[184:185], off
	v_lshl_add_u64 v[184:185], s[6:7], 0, v[168:169]
	s_add_i32 m0, s28, 0x2000
	s_nop 0
	global_load_lds_dwordx4 v[184:185], off
	v_lshl_add_u64 v[184:185], v[224:225], 0, s[16:17]
	s_mov_b32 m0, s38
	s_nop 0
	global_load_lds_dwordx4 v[184:185], off
	v_lshl_add_u64 v[184:185], v[226:227], 0, s[16:17]
	s_mov_b32 m0, s39
	s_nop 0
	global_load_lds_dwordx4 v[184:185], off
	s_setprio 1
	s_waitcnt vmcnt(8)
	s_waitcnt lgkmcnt(0)
	s_barrier
	v_mfma_f32_16x16x32_bf16 v[60:63], v[128:131], v[180:183], v[60:63]
	v_mfma_f32_16x16x32_bf16 v[56:59], v[136:139], v[180:183], v[56:59]
	v_mfma_f32_16x16x32_bf16 v[44:47], v[128:131], v[198:201], v[44:47]
	v_mfma_f32_16x16x32_bf16 v[40:43], v[136:139], v[198:201], v[40:43]
	v_mfma_f32_16x16x32_bf16 v[28:31], v[128:131], v[206:209], v[28:31]
	v_mfma_f32_16x16x32_bf16 v[24:27], v[136:139], v[206:209], v[24:27]
	v_mfma_f32_16x16x32_bf16 v[12:15], v[128:131], v[214:217], v[12:15]
	v_mfma_f32_16x16x32_bf16 v[8:11], v[136:139], v[214:217], v[8:11]
	v_mfma_f32_16x16x32_bf16 v[60:63], v[132:135], v[194:197], v[60:63]
	v_mfma_f32_16x16x32_bf16 v[56:59], v[140:143], v[194:197], v[56:59]
	v_mfma_f32_16x16x32_bf16 v[44:47], v[132:135], v[202:205], v[44:47]
	v_mfma_f32_16x16x32_bf16 v[40:43], v[140:143], v[202:205], v[40:43]
	v_mfma_f32_16x16x32_bf16 v[28:31], v[132:135], v[210:213], v[28:31]
	v_mfma_f32_16x16x32_bf16 v[24:27], v[140:143], v[210:213], v[24:27]
	v_mfma_f32_16x16x32_bf16 v[12:15], v[132:135], v[218:221], v[12:15]
	v_mfma_f32_16x16x32_bf16 v[8:11], v[140:143], v[218:221], v[8:11]
	s_setprio 0
	s_setprio 1
	v_mfma_f32_16x16x32_bf16 v[52:55], v[144:147], v[180:183], v[52:55]
	v_mfma_f32_16x16x32_bf16 v[48:51], v[152:155], v[180:183], v[48:51]
	v_mfma_f32_16x16x32_bf16 v[36:39], v[144:147], v[198:201], v[36:39]
	v_mfma_f32_16x16x32_bf16 v[32:35], v[152:155], v[198:201], v[32:35]
	v_mfma_f32_16x16x32_bf16 v[20:23], v[144:147], v[206:209], v[20:23]
	v_mfma_f32_16x16x32_bf16 v[16:19], v[152:155], v[206:209], v[16:19]
	v_mfma_f32_16x16x32_bf16 v[4:7], v[144:147], v[214:217], v[4:7]
	v_mfma_f32_16x16x32_bf16 v[0:3], v[152:155], v[214:217], v[0:3]
	v_mfma_f32_16x16x32_bf16 v[52:55], v[148:151], v[194:197], v[52:55]
	v_mfma_f32_16x16x32_bf16 v[48:51], v[156:159], v[194:197], v[48:51]
	v_mfma_f32_16x16x32_bf16 v[36:39], v[148:151], v[202:205], v[36:39]
	v_mfma_f32_16x16x32_bf16 v[32:35], v[156:159], v[202:205], v[32:35]
	v_mfma_f32_16x16x32_bf16 v[20:23], v[148:151], v[210:213], v[20:23]
	v_mfma_f32_16x16x32_bf16 v[16:19], v[156:159], v[210:213], v[16:19]
	v_mfma_f32_16x16x32_bf16 v[4:7], v[148:151], v[218:221], v[4:7]
	v_mfma_f32_16x16x32_bf16 v[0:3], v[156:159], v[218:221], v[0:3]
	s_barrier
	s_setprio 0
	s_add_i32 s51, s51, 2
	s_add_u32 s4, s4, 0x100
	s_addc_u32 s5, s5, 0
	s_add_u32 s33, s33, 0x100
	s_addc_u32 s50, s50, 0
	s_cmp_gt_u32 s51, 29
	s_cbranch_scc0 .LBB0_205
	s_and_b64 vcc, exec, s[18:19]
	s_cbranch_vccz .LBB0_208
	s_barrier

;     __device__ __forceinline__ bool next(int i, Unit& u) const { if (!base.next(i >> 1, u)) return false; if (i & 1) { u.pm += 64; u.pn += 8; } return true; }
; #define PG8_STAGE(bufoff, gbase, voff) do { _Pragma("unroll") for (int _i = 0; _i < 2; ++_i) \
;         __builtin_amdgcn_global_load_lds((const unsigned*)((const char*)(gbase) + (voff)[_i]), (PG8_LAS unsigned*)(lds + (bufoff) + ldsw + _i * 8192), 16, 0, 0); } while (0)
; #define PG8_LDA(dst, b, h) do { _Pragma("unroll") for (int m = 0; m < 4; ++m) _Pragma("unroll") for (int k = 0; k < 2; ++k) dst[m][k] = *(const PG8_LAS bf16x8*)(lds + PG8_SA(b, h) + aoff + m * 2048 + k * 1024); } while (0)
; #define PG8_LDB(dst, b, h) do { _Pragma("unroll") for (int n = 0; n < 2; ++n) _Pragma("unroll") for (int k = 0; k < 2; ++k) dst[n][k] = *(const PG8_LAS bf16x8*)(lds + PG8_SB(b, h) + boff + n * 2048 + k * 1024); } while (0)
; #define PG8_WAIT_V(n) asm volatile("s_waitcnt vmcnt(" #n ")" ::: "memory")
; #define PG8_BAR __builtin_amdgcn_s_barrier()
; template <class Epi, class Sched, bool ALIGN_EPI = false, bool SP2 = false>
; __device__ __forceinline__ void gemm_phase(PG8_LAS unsigned char* lds, const Gemm g, const Sched& S, const Epi& E) {
;     ...
;         const bool has_next = S.next(ui + 1, nxt);
;         const char* nA = has_next ? (const char*)g.A + (size_t)nxt.pm * tstep : cA; const char* nB = has_next ? (const char*)g.Bt + (size_t)nxt.pn * tstep : cB;
;         for (int t = 0; t < nt; t += 2) {
;             const bool last = (t == nt - 2);
;             const char* a1 = cA + (size_t)(t + 1) * kstep;
;             const char* a2 = last ? nA : cA + (size_t)(t + 2) * kstep; const char* b2 = last ? nB : cB + (size_t)(t + 2) * kstep;
;             const char* a3 = a2 + kstep; const char* b3 = b2 + kstep;
;             if (last && has_next) S.a_ready(nxt);
;             if constexpr (SP2) {
;             PG8_LDB(B0, 0, 0); PG8_LDB(B1, 0, 1); PG8_SCHED; PG8_LDA(At, 0, 0); PG8_STAGE(PG8_SA(1, 1), a1 + hstep, voffA);
;             PG8_WAIT_V(8); PG8_WAIT_L(0); PG8_BAR; PG8_MMA(0, 0, At, B0); PG8_MMA(0, 1, At, B1); PG8_BAR; PG8_SCHED;
;             PG8_LDA(At, 0, 1); PG8_STAGE(PG8_SB(0, 0), b2, voffB); PG8_STAGE(PG8_SB(0, 1), b2 + hstep, voffB); PG8_STAGE(PG8_SA(0, 0), a2, voffA);
;             PG8_WAIT_V(8); PG8_WAIT_L(0); PG8_BAR; PG8_MMA(1, 0, At, B0); PG8_MMA(1, 1, At, B1); PG8_BAR; PG8_SCHED;
.LBB0_571:
	s_bitcmp0_b32 s7, 0
	s_cselect_b64 s[16:17], -1, 0
	s_and_b64 s[16:17], s[16:17], s[4:5]
	s_add_i32 s7, s14, 64
	s_add_i32 s13, s12, 8
	s_and_b64 s[16:17], s[16:17], exec
	s_cselect_b32 s14, s7, s14
	s_cselect_b32 s12, s13, s12
	s_ashr_i32 s15, s14, 31
	s_lshl_b64 s[16:17], s[14:15], 19
	s_add_u32 s16, s29, s16
	s_addc_u32 s17, s30, s17
	s_and_b64 s[18:19], s[4:5], exec
	s_cselect_b32 s7, s17, s23
	s_cselect_b32 s15, s16, s22
	s_ashr_i32 s13, s12, 31
	s_lshl_b64 s[18:19], s[12:13], 19
	v_readlane_b32 s26, v236, 41
	v_readlane_b32 s27, v236, 42
	s_add_u32 s18, s26, s18
	s_addc_u32 s19, s27, s19
	s_and_b64 s[26:27], s[4:5], exec
	s_cselect_b32 s13, s19, s25
	s_cselect_b32 s21, s18, s24
	s_add_u32 s22, s22, 0x40080
	s_addc_u32 s23, s23, 0
	s_add_u32 s44, s24, 0x100
	s_addc_u32 s45, s25, 0
	s_mov_b32 s46, -2
	ds_read_b128 v[146:149], v159
	ds_read_b128 v[150:153], v159 offset:1024
	ds_read_b128 v[164:167], v159 offset:2048
	ds_read_b128 v[168:171], v159 offset:3072
	ds_read_b128 v[172:175], v161
	ds_read_b128 v[176:179], v161 offset:1024
	ds_read_b128 v[180:183], v161 offset:2048
	ds_read_b128 v[188:191], v161 offset:3072
	s_add_u32 s24, s22, 0xfffc0080
	s_addc_u32 s25, s23, -1
	s_cmp_eq_u32 s46, 12
	s_cselect_b32 s27, s7, s25
	s_cselect_b32 s26, s15, s24
	s_cselect_b32 s25, s13, s45
	s_cselect_b32 s24, s21, s44
	v_lshl_add_u64 v[154:155], s[22:23], 0, v[138:139]
	s_add_i32 m0, s31, 0xc000
	ds_read_b128 v[192:195], v162
	ds_read_b128 v[196:199], v162 offset:1024
	ds_read_b128 v[200:203], v162 offset:2048
	ds_read_b128 v[204:207], v162 offset:3072
	ds_read_b128 v[208:211], v162 offset:4096
	ds_read_b128 v[212:215], v162 offset:5120
	ds_read_b128 v[216:219], v162 offset:6144
	ds_read_b128 v[220:223], v162 offset:7168
	global_load_lds_dwordx4 v[154:155], off
	v_lshl_add_u64 v[154:155], s[22:23], 0, v[140:141]
	s_add_i32 m0, s31, 0xe000
	s_nop 0
	global_load_lds_dwordx4 v[154:155], off
	s_setprio 1
	s_waitcnt vmcnt(8)
	s_waitcnt lgkmcnt(0)
	s_barrier
	v_mfma_f32_16x16x32_bf16 v[124:127], v[146:149], v[192:195], 0
	v_mfma_f32_16x16x32_bf16 v[120:123], v[164:167], v[192:195], 0
	v_mfma_f32_16x16x32_bf16 v[108:111], v[146:149], v[200:203], 0
	v_mfma_f32_16x16x32_bf16 v[104:107], v[164:167], v[200:203], 0
	v_mfma_f32_16x16x32_bf16 v[92:95], v[146:149], v[208:211], 0
	v_mfma_f32_16x16x32_bf16 v[88:91], v[164:167], v[208:211], 0
	v_mfma_f32_16x16x32_bf16 v[76:79], v[146:149], v[216:219], 0
	v_mfma_f32_16x16x32_bf16 v[72:75], v[164:167], v[216:219], 0
	v_mfma_f32_16x16x32_bf16 v[124:127], v[150:153], v[196:199], v[124:127]
	v_mfma_f32_16x16x32_bf16 v[120:123], v[168:171], v[196:199], v[120:123]
	v_mfma_f32_16x16x32_bf16 v[108:111], v[150:153], v[204:207], v[108:111]
	v_mfma_f32_16x16x32_bf16 v[104:107], v[168:171], v[204:207], v[104:107]
	v_mfma_f32_16x16x32_bf16 v[92:95], v[150:153], v[212:215], v[92:95]
	v_mfma_f32_16x16x32_bf16 v[88:91], v[168:171], v[212:215], v[88:91]
	v_mfma_f32_16x16x32_bf16 v[76:79], v[150:153], v[220:223], v[76:79]
	v_mfma_f32_16x16x32_bf16 v[72:75], v[168:171], v[220:223], v[72:75]
	s_setprio 0
	s_setprio 1
	v_mfma_f32_16x16x32_bf16 v[116:119], v[172:175], v[192:195], 0
	v_mfma_f32_16x16x32_bf16 v[112:115], v[180:183], v[192:195], 0
	v_mfma_f32_16x16x32_bf16 v[100:103], v[172:175], v[200:203], 0
	v_mfma_f32_16x16x32_bf16 v[96:99], v[180:183], v[200:203], 0
	v_mfma_f32_16x16x32_bf16 v[84:87], v[172:175], v[208:211], 0
	v_mfma_f32_16x16x32_bf16 v[80:83], v[180:183], v[208:211], 0
	v_mfma_f32_16x16x32_bf16 v[68:71], v[172:175], v[216:219], 0
	v_mfma_f32_16x16x32_bf16 v[64:67], v[180:183], v[216:219], 0
	v_mfma_f32_16x16x32_bf16 v[116:119], v[176:179], v[196:199], v[116:119]
	v_mfma_f32_16x16x32_bf16 v[112:115], v[188:191], v[196:199], v[112:115]
	v_mfma_f32_16x16x32_bf16 v[100:103], v[176:179], v[204:207], v[100:103]
	v_mfma_f32_16x16x32_bf16 v[96:99], v[188:191], v[204:207], v[96:99]
	v_mfma_f32_16x16x32_bf16 v[84:87], v[176:179], v[212:215], v[84:87]
	v_mfma_f32_16x16x32_bf16 v[80:83], v[188:191], v[212:215], v[80:83]
	v_mfma_f32_16x16x32_bf16 v[68:71], v[176:179], v[220:223], v[68:71]
	v_mfma_f32_16x16x32_bf16 v[64:67], v[188:191], v[220:223], v[64:67]
	s_barrier
	s_setprio 0
	s_add_i32 s47, s39, s28
	v_lshl_add_u64 v[154:155], s[24:25], 0, v[130:131]
	s_mov_b32 m0, s47
	ds_read_b128 v[192:195], v162 offset:16384
	ds_read_b128 v[196:199], v162 offset:17408
	ds_read_b128 v[200:203], v162 offset:18432
	ds_read_b128 v[204:207], v162 offset:19456
	ds_read_b128 v[208:211], v162 offset:20480
	ds_read_b128 v[212:215], v162 offset:21504
	ds_read_b128 v[216:219], v162 offset:22528
	ds_read_b128 v[220:223], v162 offset:23552
	global_load_lds_dwordx4 v[154:155], off
	s_add_i32 m0, s47, 0x2000
	s_add_u32 s48, s24, 0x40000
	v_lshl_add_u64 v[184:185], s[24:25], 0, v[134:135]
	s_addc_u32 s49, s25, 0
	s_add_i32 s47, s40, s28
	global_load_lds_dwordx4 v[184:185], off
	v_lshl_add_u64 v[224:225], s[48:49], 0, v[130:131]
	s_mov_b32 m0, s47
	v_lshl_add_u64 v[226:227], s[26:27], 0, v[132:133]
	global_load_lds_dwordx4 v[224:225], off
	v_lshl_add_u64 v[224:225], s[48:49], 0, v[134:135]
	s_add_i32 m0, s47, 0x2000
	s_nop 0
	global_load_lds_dwordx4 v[224:225], off
	v_lshl_add_u64 v[224:225], s[26:27], 0, v[128:129]
	s_mov_b32 m0, s31
	s_nop 0
	global_load_lds_dwordx4 v[224:225], off
	s_mov_b32 m0, s33
	s_nop 0
	global_load_lds_dwordx4 v[226:227], off
	s_setprio 1
	s_waitcnt vmcnt(8)
	s_waitcnt lgkmcnt(0)
	s_barrier
; #define PG8_STAGE(bufoff, gbase, voff) do { _Pragma("unroll") for (int _i = 0; _i < 2; ++_i) \
;         __builtin_amdgcn_global_load_lds((const unsigned*)((const char*)(gbase) + (voff)[_i]), (PG8_LAS unsigned*)(lds + (bufoff) + ldsw + _i * 8192), 16, 0, 0); } while (0)
; #define PG8_LDA(dst, b, h) do { _Pragma("unroll") for (int m = 0; m < 4; ++m) _Pragma("unroll") for (int k = 0; k < 2; ++k) dst[m][k] = *(const PG8_LAS bf16x8*)(lds + PG8_SA(b, h) + aoff + m * 2048 + k * 1024); } while (0)
; #define PG8_LDB(dst, b, h) do { _Pragma("unroll") for (int n = 0; n < 2; ++n) _Pragma("unroll") for (int k = 0; k < 2; ++k) dst[n][k] = *(const PG8_LAS bf16x8*)(lds + PG8_SB(b, h) + boff + n * 2048 + k * 1024); } while (0)
; #define PG8_MMA(ai, bj, At, Bt) do { __builtin_amdgcn_s_setprio(1); _Pragma("unroll") for (int m = 0; m < 4; ++m) _Pragma("unroll") for (int n = 0; n < 2; ++n) _Pragma("unroll") for (int k = 0; k < 2; ++k) \
;         acc[ai][bj][m][n] = __builtin_amdgcn_mfma_f32_16x16x32_bf16(Bt[n][k], At[m][k], acc[ai][bj][m][n], 0, 0, 0); __builtin_amdgcn_s_setprio(0); } while (0)
; #define PG8_WAIT_V(n) asm volatile("s_waitcnt vmcnt(" #n ")" ::: "memory")
; #define PG8_WAIT_L(n) asm volatile("s_waitcnt lgkmcnt(" #n ")" ::: "memory")
; #define PG8_BAR __builtin_amdgcn_s_barrier()
; #define PG8_SCHED __builtin_amdgcn_sched_barrier(0)
; template <class Epi, class Sched, bool ALIGN_EPI = false, bool SP2 = false>
; __device__ __forceinline__ void gemm_phase(PG8_LAS unsigned char* lds, const Gemm g, const Sched& S, const Epi& E) {
;     ...
;             PG8_WAIT_V(8); PG8_WAIT_L(0); PG8_BAR; PG8_MMA(1, 0, At, B0); PG8_MMA(1, 1, At, B1); PG8_BAR; PG8_SCHED;
;             PG8_LDB(B0, 1, 0); PG8_LDB(B1, 1, 1); PG8_SCHED; PG8_LDA(At, 1, 0); PG8_STAGE(PG8_SA(0, 1), a2 + hstep, voffA);
;             PG8_WAIT_V(8); PG8_WAIT_L(0); PG8_BAR; PG8_MMA(0, 0, At, B0); PG8_MMA(0, 1, At, B1); PG8_BAR; PG8_SCHED;
	v_mfma_f32_16x16x32_bf16 v[60:63], v[146:149], v[192:195], 0
	v_mfma_f32_16x16x32_bf16 v[56:59], v[164:167], v[192:195], 0
	v_mfma_f32_16x16x32_bf16 v[44:47], v[146:149], v[200:203], 0
	v_mfma_f32_16x16x32_bf16 v[40:43], v[164:167], v[200:203], 0
	v_mfma_f32_16x16x32_bf16 v[28:31], v[146:149], v[208:211], 0
	v_mfma_f32_16x16x32_bf16 v[24:27], v[164:167], v[208:211], 0
	v_mfma_f32_16x16x32_bf16 v[12:15], v[146:149], v[216:219], 0
	v_mfma_f32_16x16x32_bf16 v[8:11], v[164:167], v[216:219], 0
	v_mfma_f32_16x16x32_bf16 v[60:63], v[150:153], v[196:199], v[60:63]
	v_mfma_f32_16x16x32_bf16 v[56:59], v[168:171], v[196:199], v[56:59]
	v_mfma_f32_16x16x32_bf16 v[44:47], v[150:153], v[204:207], v[44:47]
	v_mfma_f32_16x16x32_bf16 v[40:43], v[168:171], v[204:207], v[40:43]
	v_mfma_f32_16x16x32_bf16 v[28:31], v[150:153], v[212:215], v[28:31]
	v_mfma_f32_16x16x32_bf16 v[24:27], v[168:171], v[212:215], v[24:27]
	v_mfma_f32_16x16x32_bf16 v[12:15], v[150:153], v[220:223], v[12:15]
	v_mfma_f32_16x16x32_bf16 v[8:11], v[168:171], v[220:223], v[8:11]
	s_setprio 0
	s_setprio 1
	v_mfma_f32_16x16x32_bf16 v[52:55], v[172:175], v[192:195], 0
	v_mfma_f32_16x16x32_bf16 v[48:51], v[180:183], v[192:195], 0
	v_mfma_f32_16x16x32_bf16 v[36:39], v[172:175], v[200:203], 0
	v_mfma_f32_16x16x32_bf16 v[32:35], v[180:183], v[200:203], 0
	v_mfma_f32_16x16x32_bf16 v[20:23], v[172:175], v[208:211], 0
	v_mfma_f32_16x16x32_bf16 v[16:19], v[180:183], v[208:211], 0
	v_mfma_f32_16x16x32_bf16 v[4:7], v[172:175], v[216:219], 0
	v_mfma_f32_16x16x32_bf16 v[0:3], v[180:183], v[216:219], 0
	v_mfma_f32_16x16x32_bf16 v[52:55], v[176:179], v[196:199], v[52:55]
	v_mfma_f32_16x16x32_bf16 v[48:51], v[188:191], v[196:199], v[48:51]
	v_mfma_f32_16x16x32_bf16 v[36:39], v[176:179], v[204:207], v[36:39]
	v_mfma_f32_16x16x32_bf16 v[32:35], v[188:191], v[204:207], v[32:35]
	v_mfma_f32_16x16x32_bf16 v[20:23], v[176:179], v[212:215], v[20:23]
	v_mfma_f32_16x16x32_bf16 v[16:19], v[188:191], v[212:215], v[16:19]
	v_mfma_f32_16x16x32_bf16 v[4:7], v[176:179], v[220:223], v[4:7]
	v_mfma_f32_16x16x32_bf16 v[0:3], v[188:191], v[220:223], v[0:3]
	s_barrier
	s_setprio 0
	s_add_i32 s47, 0, 0x18000
	v_add_u32_e32 v136, s47, v157
	s_add_i32 s48, 0, 0x1c000
	ds_read_b128 v[146:149], v136
	ds_read_b128 v[150:153], v136 offset:1024
	ds_read_b128 v[164:167], v136 offset:2048
	ds_read_b128 v[168:171], v136 offset:3072
	v_add_u32_e32 v136, s48, v157
	ds_read_b128 v[172:175], v136
	ds_read_b128 v[176:179], v136 offset:1024
	ds_read_b128 v[180:183], v136 offset:2048
	ds_read_b128 v[188:191], v136 offset:3072
	s_add_u32 s26, s26, 0x40000
	s_addc_u32 s27, s27, 0
	s_mov_b32 m0, s34
	v_lshl_add_u64 v[228:229], s[26:27], 0, v[128:129]
	ds_read_b128 v[192:195], v162 offset:32768
	ds_read_b128 v[196:199], v162 offset:33792
	ds_read_b128 v[200:203], v162 offset:34816
	ds_read_b128 v[204:207], v162 offset:35840
	ds_read_b128 v[208:211], v162 offset:36864
	ds_read_b128 v[212:215], v162 offset:37888
	ds_read_b128 v[216:219], v162 offset:38912
	ds_read_b128 v[220:223], v162 offset:39936
	global_load_lds_dwordx4 v[228:229], off
	v_lshl_add_u64 v[228:229], s[26:27], 0, v[132:133]
	s_mov_b32 m0, s35
	s_nop 0
	global_load_lds_dwordx4 v[228:229], off
	s_setprio 1
	s_waitcnt vmcnt(8)
	s_waitcnt lgkmcnt(0)
	s_barrier
	v_mfma_f32_16x16x32_bf16 v[124:127], v[146:149], v[192:195], v[124:127]
	v_mfma_f32_16x16x32_bf16 v[120:123], v[164:167], v[192:195], v[120:123]
	v_mfma_f32_16x16x32_bf16 v[108:111], v[146:149], v[200:203], v[108:111]
	v_mfma_f32_16x16x32_bf16 v[104:107], v[164:167], v[200:203], v[104:107]
	v_mfma_f32_16x16x32_bf16 v[92:95], v[146:149], v[208:211], v[92:95]
	v_mfma_f32_16x16x32_bf16 v[88:91], v[164:167], v[208:211], v[88:91]
	v_mfma_f32_16x16x32_bf16 v[76:79], v[146:149], v[216:219], v[76:79]
	v_mfma_f32_16x16x32_bf16 v[72:75], v[164:167], v[216:219], v[72:75]
	v_mfma_f32_16x16x32_bf16 v[124:127], v[150:153], v[196:199], v[124:127]
	v_mfma_f32_16x16x32_bf16 v[120:123], v[168:171], v[196:199], v[120:123]
	v_mfma_f32_16x16x32_bf16 v[108:111], v[150:153], v[204:207], v[108:111]
	v_mfma_f32_16x16x32_bf16 v[104:107], v[168:171], v[204:207], v[104:107]
	v_mfma_f32_16x16x32_bf16 v[92:95], v[150:153], v[212:215], v[92:95]
	v_mfma_f32_16x16x32_bf16 v[88:91], v[168:171], v[212:215], v[88:91]
	v_mfma_f32_16x16x32_bf16 v[76:79], v[150:153], v[220:223], v[76:79]
	v_mfma_f32_16x16x32_bf16 v[72:75], v[168:171], v[220:223], v[72:75]
	s_setprio 0
	s_setprio 1
	v_mfma_f32_16x16x32_bf16 v[116:119], v[172:175], v[192:195], v[116:119]
	v_mfma_f32_16x16x32_bf16 v[112:115], v[180:183], v[192:195], v[112:115]
	v_mfma_f32_16x16x32_bf16 v[100:103], v[172:175], v[200:203], v[100:103]
	v_mfma_f32_16x16x32_bf16 v[96:99], v[180:183], v[200:203], v[96:99]
	v_mfma_f32_16x16x32_bf16 v[84:87], v[172:175], v[208:211], v[84:87]
	v_mfma_f32_16x16x32_bf16 v[80:83], v[180:183], v[208:211], v[80:83]
	v_mfma_f32_16x16x32_bf16 v[68:71], v[172:175], v[216:219], v[68:71]
	v_mfma_f32_16x16x32_bf16 v[64:67], v[180:183], v[216:219], v[64:67]
	v_mfma_f32_16x16x32_bf16 v[116:119], v[176:179], v[196:199], v[116:119]
	v_mfma_f32_16x16x32_bf16 v[112:115], v[188:191], v[196:199], v[112:115]
	v_mfma_f32_16x16x32_bf16 v[100:103], v[176:179], v[204:207], v[100:103]
	v_mfma_f32_16x16x32_bf16 v[96:99], v[188:191], v[204:207], v[96:99]
	v_mfma_f32_16x16x32_bf16 v[84:87], v[176:179], v[212:215], v[84:87]
	v_mfma_f32_16x16x32_bf16 v[80:83], v[188:191], v[212:215], v[80:83]
	v_mfma_f32_16x16x32_bf16 v[68:71], v[176:179], v[220:223], v[68:71]
	v_mfma_f32_16x16x32_bf16 v[64:67], v[188:191], v[220:223], v[64:67]
	s_barrier
; #define PG8_STAGE(bufoff, gbase, voff) do { _Pragma("unroll") for (int _i = 0; _i < 2; ++_i) \
;         __builtin_amdgcn_global_load_lds((const unsigned*)((const char*)(gbase) + (voff)[_i]), (PG8_LAS unsigned*)(lds + (bufoff) + ldsw + _i * 8192), 16, 0, 0); } while (0)
; #define PG8_LDA(dst, b, h) do { _Pragma("unroll") for (int m = 0; m < 4; ++m) _Pragma("unroll") for (int k = 0; k < 2; ++k) dst[m][k] = *(const PG8_LAS bf16x8*)(lds + PG8_SA(b, h) + aoff + m * 2048 + k * 1024); } while (0)
; #define PG8_LDB(dst, b, h) do { _Pragma("unroll") for (int n = 0; n < 2; ++n) _Pragma("unroll") for (int k = 0; k < 2; ++k) dst[n][k] = *(const PG8_LAS bf16x8*)(lds + PG8_SB(b, h) + boff + n * 2048 + k * 1024); } while (0)
; #define PG8_MMA(ai, bj, At, Bt) do { __builtin_amdgcn_s_setprio(1); _Pragma("unroll") for (int m = 0; m < 4; ++m) _Pragma("unroll") for (int n = 0; n < 2; ++n) _Pragma("unroll") for (int k = 0; k < 2; ++k) \
;         acc[ai][bj][m][n] = __builtin_amdgcn_mfma_f32_16x16x32_bf16(Bt[n][k], At[m][k], acc[ai][bj][m][n], 0, 0, 0); __builtin_amdgcn_s_setprio(0); } while (0)
; #define PG8_WAIT_V(n) asm volatile("s_waitcnt vmcnt(" #n ")" ::: "memory")
; #define PG8_WAIT_L(n) asm volatile("s_waitcnt lgkmcnt(" #n ")" ::: "memory")
; #define PG8_BAR __builtin_amdgcn_s_barrier()
; #define PG8_SCHED __builtin_amdgcn_sched_barrier(0)
; template <class Epi, class Sched, bool ALIGN_EPI = false, bool SP2 = false>
; __device__ __forceinline__ void gemm_phase(PG8_LAS unsigned char* lds, const Gemm g, const Sched& S, const Epi& E) {
;     ...
;         for (int t = 0; t < nt; t += 2) {
;             const bool last = (t == nt - 2);
;             const char* a1 = cA + (size_t)(t + 1) * kstep;
;             const char* a2 = last ? nA : cA + (size_t)(t + 2) * kstep; const char* b2 = last ? nB : cB + (size_t)(t + 2) * kstep;
;             const char* a3 = a2 + kstep; const char* b3 = b2 + kstep;
;             if (last && has_next) S.a_ready(nxt);
;             if constexpr (SP2) {
;             PG8_LDB(B0, 0, 0); PG8_LDB(B1, 0, 1); PG8_SCHED; PG8_LDA(At, 0, 0); PG8_STAGE(PG8_SA(1, 1), a1 + hstep, voffA);
;     ...
;             PG8_LDA(At, 1, 1); PG8_STAGE(PG8_SB(1, 0), b3, voffB); PG8_STAGE(PG8_SB(1, 1), b3 + hstep, voffB); PG8_STAGE(PG8_SA(1, 0), a3, voffA);
;             PG8_WAIT_V(8); PG8_WAIT_L(0); PG8_BAR; PG8_MMA(1, 0, At, B0); PG8_MMA(1, 1, At, B1); PG8_BAR; PG8_SCHED;
	s_setprio 0
	s_add_i32 s26, s47, s28
	v_lshl_add_u64 v[154:155], v[154:155], 0, s[8:9]
	s_mov_b32 m0, s26
	ds_read_b128 v[192:195], v162 offset:49152
	ds_read_b128 v[196:199], v162 offset:50176
	ds_read_b128 v[200:203], v162 offset:51200
	ds_read_b128 v[204:207], v162 offset:52224
	ds_read_b128 v[208:211], v162 offset:53248
	ds_read_b128 v[212:215], v162 offset:54272
	ds_read_b128 v[216:219], v162 offset:55296
	ds_read_b128 v[220:223], v162 offset:56320
	global_load_lds_dwordx4 v[154:155], off
	s_add_i32 m0, s26, 0x2000
	s_add_u32 s24, s24, 0x40080
	v_lshl_add_u64 v[154:155], v[184:185], 0, s[8:9]
	s_addc_u32 s25, s25, 0
	s_add_i32 s26, s48, s28
	global_load_lds_dwordx4 v[154:155], off
	v_lshl_add_u64 v[154:155], s[24:25], 0, v[130:131]
	s_mov_b32 m0, s26
	s_nop 0
	global_load_lds_dwordx4 v[154:155], off
	v_lshl_add_u64 v[154:155], s[24:25], 0, v[134:135]
	s_add_i32 m0, s26, 0x2000
	s_nop 0
	global_load_lds_dwordx4 v[154:155], off
	v_lshl_add_u64 v[154:155], v[224:225], 0, s[8:9]
	s_mov_b32 m0, s36
	s_nop 0
	global_load_lds_dwordx4 v[154:155], off
	v_lshl_add_u64 v[154:155], v[226:227], 0, s[8:9]
	s_mov_b32 m0, s37
	s_nop 0
	global_load_lds_dwordx4 v[154:155], off
	s_setprio 1
	s_waitcnt vmcnt(8)
	s_waitcnt lgkmcnt(0)
	s_barrier
	v_mfma_f32_16x16x32_bf16 v[60:63], v[146:149], v[192:195], v[60:63]
	v_mfma_f32_16x16x32_bf16 v[56:59], v[164:167], v[192:195], v[56:59]
	v_mfma_f32_16x16x32_bf16 v[44:47], v[146:149], v[200:203], v[44:47]
	v_mfma_f32_16x16x32_bf16 v[40:43], v[164:167], v[200:203], v[40:43]
	v_mfma_f32_16x16x32_bf16 v[28:31], v[146:149], v[208:211], v[28:31]
	v_mfma_f32_16x16x32_bf16 v[24:27], v[164:167], v[208:211], v[24:27]
	v_mfma_f32_16x16x32_bf16 v[12:15], v[146:149], v[216:219], v[12:15]
	v_mfma_f32_16x16x32_bf16 v[8:11], v[164:167], v[216:219], v[8:11]
	v_mfma_f32_16x16x32_bf16 v[60:63], v[150:153], v[196:199], v[60:63]
	v_mfma_f32_16x16x32_bf16 v[56:59], v[168:171], v[196:199], v[56:59]
	v_mfma_f32_16x16x32_bf16 v[44:47], v[150:153], v[204:207], v[44:47]
	v_mfma_f32_16x16x32_bf16 v[40:43], v[168:171], v[204:207], v[40:43]
	v_mfma_f32_16x16x32_bf16 v[28:31], v[150:153], v[212:215], v[28:31]
	v_mfma_f32_16x16x32_bf16 v[24:27], v[168:171], v[212:215], v[24:27]
	v_mfma_f32_16x16x32_bf16 v[12:15], v[150:153], v[220:223], v[12:15]
	v_mfma_f32_16x16x32_bf16 v[8:11], v[168:171], v[220:223], v[8:11]
	s_setprio 0
	s_setprio 1
	v_mfma_f32_16x16x32_bf16 v[52:55], v[172:175], v[192:195], v[52:55]
	v_mfma_f32_16x16x32_bf16 v[48:51], v[180:183], v[192:195], v[48:51]
	v_mfma_f32_16x16x32_bf16 v[36:39], v[172:175], v[200:203], v[36:39]
	v_mfma_f32_16x16x32_bf16 v[32:35], v[180:183], v[200:203], v[32:35]
	v_mfma_f32_16x16x32_bf16 v[20:23], v[172:175], v[208:211], v[20:23]
	v_mfma_f32_16x16x32_bf16 v[16:19], v[180:183], v[208:211], v[16:19]
	v_mfma_f32_16x16x32_bf16 v[4:7], v[172:175], v[216:219], v[4:7]
	v_mfma_f32_16x16x32_bf16 v[0:3], v[180:183], v[216:219], v[0:3]
	v_mfma_f32_16x16x32_bf16 v[52:55], v[176:179], v[196:199], v[52:55]
	v_mfma_f32_16x16x32_bf16 v[48:51], v[188:191], v[196:199], v[48:51]
	v_mfma_f32_16x16x32_bf16 v[36:39], v[176:179], v[204:207], v[36:39]
	v_mfma_f32_16x16x32_bf16 v[32:35], v[188:191], v[204:207], v[32:35]
	v_mfma_f32_16x16x32_bf16 v[20:23], v[176:179], v[212:215], v[20:23]
	v_mfma_f32_16x16x32_bf16 v[16:19], v[188:191], v[212:215], v[16:19]
	v_mfma_f32_16x16x32_bf16 v[4:7], v[176:179], v[220:223], v[4:7]
	v_mfma_f32_16x16x32_bf16 v[0:3], v[188:191], v[220:223], v[0:3]
	s_barrier
	s_setprio 0
	s_add_i32 s46, s46, 2
	s_add_u32 s22, s22, 0x100
	s_addc_u32 s23, s23, 0
	s_add_u32 s44, s44, 0x100
	s_addc_u32 s45, s45, 0
	s_cmp_gt_u32 s46, 13
.LBB0_572:
	ds_read_b128 v[146:149], v159
	ds_read_b128 v[150:153], v159 offset:1024
	ds_read_b128 v[164:167], v159 offset:2048
	ds_read_b128 v[168:171], v159 offset:3072
	ds_read_b128 v[172:175], v161
	ds_read_b128 v[176:179], v161 offset:1024
	ds_read_b128 v[180:183], v161 offset:2048
	ds_read_b128 v[188:191], v161 offset:3072
	s_add_u32 s24, s22, 0xfffc0080
	s_addc_u32 s25, s23, -1
	s_cmp_eq_u32 s46, 12
	s_cselect_b32 s27, s7, s25
	s_cselect_b32 s26, s15, s24
	s_cselect_b32 s25, s13, s45
	s_cselect_b32 s24, s21, s44
	v_lshl_add_u64 v[154:155], s[22:23], 0, v[138:139]
	s_add_i32 m0, s31, 0xc000
	ds_read_b128 v[192:195], v162
	ds_read_b128 v[196:199], v162 offset:1024
	ds_read_b128 v[200:203], v162 offset:2048
	ds_read_b128 v[204:207], v162 offset:3072
	ds_read_b128 v[208:211], v162 offset:4096
	ds_read_b128 v[212:215], v162 offset:5120
	ds_read_b128 v[216:219], v162 offset:6144
	ds_read_b128 v[220:223], v162 offset:7168
	global_load_lds_dwordx4 v[154:155], off
	v_lshl_add_u64 v[154:155], s[22:23], 0, v[140:141]
	s_add_i32 m0, s31, 0xe000
	s_nop 0
	global_load_lds_dwordx4 v[154:155], off
	s_setprio 1
	s_waitcnt vmcnt(8)
	s_waitcnt lgkmcnt(0)
	s_barrier
; #define PG8_STAGE(bufoff, gbase, voff) do { _Pragma("unroll") for (int _i = 0; _i < 2; ++_i) \
;         __builtin_amdgcn_global_load_lds((const unsigned*)((const char*)(gbase) + (voff)[_i]), (PG8_LAS unsigned*)(lds + (bufoff) + ldsw + _i * 8192), 16, 0, 0); } while (0)
; #define PG8_LDA(dst, b, h) do { _Pragma("unroll") for (int m = 0; m < 4; ++m) _Pragma("unroll") for (int k = 0; k < 2; ++k) dst[m][k] = *(const PG8_LAS bf16x8*)(lds + PG8_SA(b, h) + aoff + m * 2048 + k * 1024); } while (0)
; #define PG8_LDB(dst, b, h) do { _Pragma("unroll") for (int n = 0; n < 2; ++n) _Pragma("unroll") for (int k = 0; k < 2; ++k) dst[n][k] = *(const PG8_LAS bf16x8*)(lds + PG8_SB(b, h) + boff + n * 2048 + k * 1024); } while (0)
; #define PG8_MMA(ai, bj, At, Bt) do { __builtin_amdgcn_s_setprio(1); _Pragma("unroll") for (int m = 0; m < 4; ++m) _Pragma("unroll") for (int n = 0; n < 2; ++n) _Pragma("unroll") for (int k = 0; k < 2; ++k) \
;         acc[ai][bj][m][n] = __builtin_amdgcn_mfma_f32_16x16x32_bf16(Bt[n][k], At[m][k], acc[ai][bj][m][n], 0, 0, 0); __builtin_amdgcn_s_setprio(0); } while (0)
; #define PG8_WAIT_V(n) asm volatile("s_waitcnt vmcnt(" #n ")" ::: "memory")
; #define PG8_WAIT_L(n) asm volatile("s_waitcnt lgkmcnt(" #n ")" ::: "memory")
; #define PG8_BAR __builtin_amdgcn_s_barrier()
; #define PG8_SCHED __builtin_amdgcn_sched_barrier(0)
; template <class Epi, class Sched, bool ALIGN_EPI = false, bool SP2 = false>
; __device__ __forceinline__ void gemm_phase(PG8_LAS unsigned char* lds, const Gemm g, const Sched& S, const Epi& E) {
;     ...
;             PG8_LDB(B0, 0, 0); PG8_LDB(B1, 0, 1); PG8_SCHED; PG8_LDA(At, 0, 0); PG8_STAGE(PG8_SA(1, 1), a1 + hstep, voffA);
;             PG8_WAIT_V(8); PG8_WAIT_L(0); PG8_BAR; PG8_MMA(0, 0, At, B0); PG8_MMA(0, 1, At, B1); PG8_BAR; PG8_SCHED;
;             PG8_LDA(At, 0, 1); PG8_STAGE(PG8_SB(0, 0), b2, voffB); PG8_STAGE(PG8_SB(0, 1), b2 + hstep, voffB); PG8_STAGE(PG8_SA(0, 0), a2, voffA);
;             PG8_WAIT_V(8); PG8_WAIT_L(0); PG8_BAR; PG8_MMA(1, 0, At, B0); PG8_MMA(1, 1, At, B1); PG8_BAR; PG8_SCHED;
	v_mfma_f32_16x16x32_bf16 v[124:127], v[146:149], v[192:195], v[124:127]
	v_mfma_f32_16x16x32_bf16 v[120:123], v[164:167], v[192:195], v[120:123]
	v_mfma_f32_16x16x32_bf16 v[108:111], v[146:149], v[200:203], v[108:111]
	v_mfma_f32_16x16x32_bf16 v[104:107], v[164:167], v[200:203], v[104:107]
	v_mfma_f32_16x16x32_bf16 v[92:95], v[146:149], v[208:211], v[92:95]
	v_mfma_f32_16x16x32_bf16 v[88:91], v[164:167], v[208:211], v[88:91]
	v_mfma_f32_16x16x32_bf16 v[76:79], v[146:149], v[216:219], v[76:79]
	v_mfma_f32_16x16x32_bf16 v[72:75], v[164:167], v[216:219], v[72:75]
	v_mfma_f32_16x16x32_bf16 v[124:127], v[150:153], v[196:199], v[124:127]
	v_mfma_f32_16x16x32_bf16 v[120:123], v[168:171], v[196:199], v[120:123]
	v_mfma_f32_16x16x32_bf16 v[108:111], v[150:153], v[204:207], v[108:111]
	v_mfma_f32_16x16x32_bf16 v[104:107], v[168:171], v[204:207], v[104:107]
	v_mfma_f32_16x16x32_bf16 v[92:95], v[150:153], v[212:215], v[92:95]
	v_mfma_f32_16x16x32_bf16 v[88:91], v[168:171], v[212:215], v[88:91]
	v_mfma_f32_16x16x32_bf16 v[76:79], v[150:153], v[220:223], v[76:79]
	v_mfma_f32_16x16x32_bf16 v[72:75], v[168:171], v[220:223], v[72:75]
	s_setprio 0
	s_setprio 1
	v_mfma_f32_16x16x32_bf16 v[116:119], v[172:175], v[192:195], v[116:119]
	v_mfma_f32_16x16x32_bf16 v[112:115], v[180:183], v[192:195], v[112:115]
	v_mfma_f32_16x16x32_bf16 v[100:103], v[172:175], v[200:203], v[100:103]
	v_mfma_f32_16x16x32_bf16 v[96:99], v[180:183], v[200:203], v[96:99]
	v_mfma_f32_16x16x32_bf16 v[84:87], v[172:175], v[208:211], v[84:87]
	v_mfma_f32_16x16x32_bf16 v[80:83], v[180:183], v[208:211], v[80:83]
	v_mfma_f32_16x16x32_bf16 v[68:71], v[172:175], v[216:219], v[68:71]
	v_mfma_f32_16x16x32_bf16 v[64:67], v[180:183], v[216:219], v[64:67]
	v_mfma_f32_16x16x32_bf16 v[116:119], v[176:179], v[196:199], v[116:119]
	v_mfma_f32_16x16x32_bf16 v[112:115], v[188:191], v[196:199], v[112:115]
	v_mfma_f32_16x16x32_bf16 v[100:103], v[176:179], v[204:207], v[100:103]
	v_mfma_f32_16x16x32_bf16 v[96:99], v[188:191], v[204:207], v[96:99]
	v_mfma_f32_16x16x32_bf16 v[84:87], v[176:179], v[212:215], v[84:87]
	v_mfma_f32_16x16x32_bf16 v[80:83], v[188:191], v[212:215], v[80:83]
	v_mfma_f32_16x16x32_bf16 v[68:71], v[176:179], v[220:223], v[68:71]
	v_mfma_f32_16x16x32_bf16 v[64:67], v[188:191], v[220:223], v[64:67]
	s_barrier
	s_setprio 0
	s_add_i32 s47, s39, s28
	v_lshl_add_u64 v[154:155], s[24:25], 0, v[130:131]
	s_mov_b32 m0, s47
	ds_read_b128 v[192:195], v162 offset:16384
	ds_read_b128 v[196:199], v162 offset:17408
	ds_read_b128 v[200:203], v162 offset:18432
	ds_read_b128 v[204:207], v162 offset:19456
	ds_read_b128 v[208:211], v162 offset:20480
	ds_read_b128 v[212:215], v162 offset:21504
	ds_read_b128 v[216:219], v162 offset:22528
	ds_read_b128 v[220:223], v162 offset:23552
	global_load_lds_dwordx4 v[154:155], off
	s_add_i32 m0, s47, 0x2000
	s_add_u32 s48, s24, 0x40000
	v_lshl_add_u64 v[184:185], s[24:25], 0, v[134:135]
	s_addc_u32 s49, s25, 0
	s_add_i32 s47, s40, s28
	global_load_lds_dwordx4 v[184:185], off
	v_lshl_add_u64 v[224:225], s[48:49], 0, v[130:131]
	s_mov_b32 m0, s47
	v_lshl_add_u64 v[226:227], s[26:27], 0, v[132:133]
	global_load_lds_dwordx4 v[224:225], off
	v_lshl_add_u64 v[224:225], s[48:49], 0, v[134:135]
	s_add_i32 m0, s47, 0x2000
	s_nop 0
	global_load_lds_dwordx4 v[224:225], off
	v_lshl_add_u64 v[224:225], s[26:27], 0, v[128:129]
	s_mov_b32 m0, s31
	s_nop 0
	global_load_lds_dwordx4 v[224:225], off
	s_mov_b32 m0, s33
	s_nop 0
	global_load_lds_dwordx4 v[226:227], off
	s_setprio 1
	s_waitcnt vmcnt(8)
	s_waitcnt lgkmcnt(0)
	s_barrier
	v_mfma_f32_16x16x32_bf16 v[60:63], v[146:149], v[192:195], v[60:63]
	v_mfma_f32_16x16x32_bf16 v[56:59], v[164:167], v[192:195], v[56:59]
	v_mfma_f32_16x16x32_bf16 v[44:47], v[146:149], v[200:203], v[44:47]
	v_mfma_f32_16x16x32_bf16 v[40:43], v[164:167], v[200:203], v[40:43]
	v_mfma_f32_16x16x32_bf16 v[28:31], v[146:149], v[208:211], v[28:31]
	v_mfma_f32_16x16x32_bf16 v[24:27], v[164:167], v[208:211], v[24:27]
	v_mfma_f32_16x16x32_bf16 v[12:15], v[146:149], v[216:219], v[12:15]
	v_mfma_f32_16x16x32_bf16 v[8:11], v[164:167], v[216:219], v[8:11]
	v_mfma_f32_16x16x32_bf16 v[60:63], v[150:153], v[196:199], v[60:63]
	v_mfma_f32_16x16x32_bf16 v[56:59], v[168:171], v[196:199], v[56:59]
	v_mfma_f32_16x16x32_bf16 v[44:47], v[150:153], v[204:207], v[44:47]
	v_mfma_f32_16x16x32_bf16 v[40:43], v[168:171], v[204:207], v[40:43]
	v_mfma_f32_16x16x32_bf16 v[28:31], v[150:153], v[212:215], v[28:31]
	v_mfma_f32_16x16x32_bf16 v[24:27], v[168:171], v[212:215], v[24:27]
	v_mfma_f32_16x16x32_bf16 v[12:15], v[150:153], v[220:223], v[12:15]
	v_mfma_f32_16x16x32_bf16 v[8:11], v[168:171], v[220:223], v[8:11]
	s_setprio 0
	s_setprio 1
	v_mfma_f32_16x16x32_bf16 v[52:55], v[172:175], v[192:195], v[52:55]
	v_mfma_f32_16x16x32_bf16 v[48:51], v[180:183], v[192:195], v[48:51]
	v_mfma_f32_16x16x32_bf16 v[36:39], v[172:175], v[200:203], v[36:39]
	v_mfma_f32_16x16x32_bf16 v[32:35], v[180:183], v[200:203], v[32:35]
	v_mfma_f32_16x16x32_bf16 v[20:23], v[172:175], v[208:211], v[20:23]
	v_mfma_f32_16x16x32_bf16 v[16:19], v[180:183], v[208:211], v[16:19]
	v_mfma_f32_16x16x32_bf16 v[4:7], v[172:175], v[216:219], v[4:7]
	v_mfma_f32_16x16x32_bf16 v[0:3], v[180:183], v[216:219], v[0:3]
	v_mfma_f32_16x16x32_bf16 v[52:55], v[176:179], v[196:199], v[52:55]
	v_mfma_f32_16x16x32_bf16 v[48:51], v[188:191], v[196:199], v[48:51]
	v_mfma_f32_16x16x32_bf16 v[36:39], v[176:179], v[204:207], v[36:39]
	v_mfma_f32_16x16x32_bf16 v[32:35], v[188:191], v[204:207], v[32:35]
	v_mfma_f32_16x16x32_bf16 v[20:23], v[176:179], v[212:215], v[20:23]
	v_mfma_f32_16x16x32_bf16 v[16:19], v[188:191], v[212:215], v[16:19]
	v_mfma_f32_16x16x32_bf16 v[4:7], v[176:179], v[220:223], v[4:7]
	v_mfma_f32_16x16x32_bf16 v[0:3], v[188:191], v[220:223], v[0:3]
	s_barrier
; #define PG8_STAGE(bufoff, gbase, voff) do { _Pragma("unroll") for (int _i = 0; _i < 2; ++_i) \
;         __builtin_amdgcn_global_load_lds((const unsigned*)((const char*)(gbase) + (voff)[_i]), (PG8_LAS unsigned*)(lds + (bufoff) + ldsw + _i * 8192), 16, 0, 0); } while (0)
; #define PG8_LDA(dst, b, h) do { _Pragma("unroll") for (int m = 0; m < 4; ++m) _Pragma("unroll") for (int k = 0; k < 2; ++k) dst[m][k] = *(const PG8_LAS bf16x8*)(lds + PG8_SA(b, h) + aoff + m * 2048 + k * 1024); } while (0)
; #define PG8_LDB(dst, b, h) do { _Pragma("unroll") for (int n = 0; n < 2; ++n) _Pragma("unroll") for (int k = 0; k < 2; ++k) dst[n][k] = *(const PG8_LAS bf16x8*)(lds + PG8_SB(b, h) + boff + n * 2048 + k * 1024); } while (0)
; #define PG8_MMA(ai, bj, At, Bt) do { __builtin_amdgcn_s_setprio(1); _Pragma("unroll") for (int m = 0; m < 4; ++m) _Pragma("unroll") for (int n = 0; n < 2; ++n) _Pragma("unroll") for (int k = 0; k < 2; ++k) \
;         acc[ai][bj][m][n] = __builtin_amdgcn_mfma_f32_16x16x32_bf16(Bt[n][k], At[m][k], acc[ai][bj][m][n], 0, 0, 0); __builtin_amdgcn_s_setprio(0); } while (0)
; #define PG8_WAIT_V(n) asm volatile("s_waitcnt vmcnt(" #n ")" ::: "memory")
; #define PG8_WAIT_L(n) asm volatile("s_waitcnt lgkmcnt(" #n ")" ::: "memory")
; #define PG8_BAR __builtin_amdgcn_s_barrier()
; #define PG8_SCHED __builtin_amdgcn_sched_barrier(0)
; template <class Epi, class Sched, bool ALIGN_EPI = false, bool SP2 = false>
; __device__ __forceinline__ void gemm_phase(PG8_LAS unsigned char* lds, const Gemm g, const Sched& S, const Epi& E) {
;     ...
;             PG8_LDB(B0, 1, 0); PG8_LDB(B1, 1, 1); PG8_SCHED; PG8_LDA(At, 1, 0); PG8_STAGE(PG8_SA(0, 1), a2 + hstep, voffA);
;             PG8_WAIT_V(8); PG8_WAIT_L(0); PG8_BAR; PG8_MMA(0, 0, At, B0); PG8_MMA(0, 1, At, B1); PG8_BAR; PG8_SCHED;
	s_setprio 0
	s_add_i32 s47, 0, 0x18000
	v_add_u32_e32 v136, s47, v157
	s_add_i32 s48, 0, 0x1c000
	ds_read_b128 v[146:149], v136
	ds_read_b128 v[150:153], v136 offset:1024
	ds_read_b128 v[164:167], v136 offset:2048
	ds_read_b128 v[168:171], v136 offset:3072
	v_add_u32_e32 v136, s48, v157
	ds_read_b128 v[172:175], v136
	ds_read_b128 v[176:179], v136 offset:1024
	ds_read_b128 v[180:183], v136 offset:2048
	ds_read_b128 v[188:191], v136 offset:3072
	s_add_u32 s26, s26, 0x40000
	s_addc_u32 s27, s27, 0
	s_mov_b32 m0, s34
	v_lshl_add_u64 v[228:229], s[26:27], 0, v[128:129]
	ds_read_b128 v[192:195], v162 offset:32768
	ds_read_b128 v[196:199], v162 offset:33792
	ds_read_b128 v[200:203], v162 offset:34816
	ds_read_b128 v[204:207], v162 offset:35840
	ds_read_b128 v[208:211], v162 offset:36864
	ds_read_b128 v[212:215], v162 offset:37888
	ds_read_b128 v[216:219], v162 offset:38912
	ds_read_b128 v[220:223], v162 offset:39936
	global_load_lds_dwordx4 v[228:229], off
	v_lshl_add_u64 v[228:229], s[26:27], 0, v[132:133]
	s_mov_b32 m0, s35
	s_nop 0
	global_load_lds_dwordx4 v[228:229], off
	s_setprio 1
	s_waitcnt vmcnt(8)
	s_waitcnt lgkmcnt(0)
	s_barrier
	v_mfma_f32_16x16x32_bf16 v[124:127], v[146:149], v[192:195], v[124:127]
	v_mfma_f32_16x16x32_bf16 v[120:123], v[164:167], v[192:195], v[120:123]
	v_mfma_f32_16x16x32_bf16 v[108:111], v[146:149], v[200:203], v[108:111]
	v_mfma_f32_16x16x32_bf16 v[104:107], v[164:167], v[200:203], v[104:107]
	v_mfma_f32_16x16x32_bf16 v[92:95], v[146:149], v[208:211], v[92:95]
	v_mfma_f32_16x16x32_bf16 v[88:91], v[164:167], v[208:211], v[88:91]
	v_mfma_f32_16x16x32_bf16 v[76:79], v[146:149], v[216:219], v[76:79]
	v_mfma_f32_16x16x32_bf16 v[72:75], v[164:167], v[216:219], v[72:75]
	v_mfma_f32_16x16x32_bf16 v[124:127], v[150:153], v[196:199], v[124:127]
	v_mfma_f32_16x16x32_bf16 v[120:123], v[168:171], v[196:199], v[120:123]
	v_mfma_f32_16x16x32_bf16 v[108:111], v[150:153], v[204:207], v[108:111]
	v_mfma_f32_16x16x32_bf16 v[104:107], v[168:171], v[204:207], v[104:107]
	v_mfma_f32_16x16x32_bf16 v[92:95], v[150:153], v[212:215], v[92:95]
	v_mfma_f32_16x16x32_bf16 v[88:91], v[168:171], v[212:215], v[88:91]
	v_mfma_f32_16x16x32_bf16 v[76:79], v[150:153], v[220:223], v[76:79]
	v_mfma_f32_16x16x32_bf16 v[72:75], v[168:171], v[220:223], v[72:75]
	s_setprio 0
	s_setprio 1
	v_mfma_f32_16x16x32_bf16 v[116:119], v[172:175], v[192:195], v[116:119]
	v_mfma_f32_16x16x32_bf16 v[112:115], v[180:183], v[192:195], v[112:115]
	v_mfma_f32_16x16x32_bf16 v[100:103], v[172:175], v[200:203], v[100:103]
	v_mfma_f32_16x16x32_bf16 v[96:99], v[180:183], v[200:203], v[96:99]
	v_mfma_f32_16x16x32_bf16 v[84:87], v[172:175], v[208:211], v[84:87]
	v_mfma_f32_16x16x32_bf16 v[80:83], v[180:183], v[208:211], v[80:83]
	v_mfma_f32_16x16x32_bf16 v[68:71], v[172:175], v[216:219], v[68:71]
	v_mfma_f32_16x16x32_bf16 v[64:67], v[180:183], v[216:219], v[64:67]
	v_mfma_f32_16x16x32_bf16 v[116:119], v[176:179], v[196:199], v[116:119]
	v_mfma_f32_16x16x32_bf16 v[112:115], v[188:191], v[196:199], v[112:115]
	v_mfma_f32_16x16x32_bf16 v[100:103], v[176:179], v[204:207], v[100:103]
	v_mfma_f32_16x16x32_bf16 v[96:99], v[188:191], v[204:207], v[96:99]
	v_mfma_f32_16x16x32_bf16 v[84:87], v[176:179], v[212:215], v[84:87]
	v_mfma_f32_16x16x32_bf16 v[80:83], v[188:191], v[212:215], v[80:83]
	v_mfma_f32_16x16x32_bf16 v[68:71], v[176:179], v[220:223], v[68:71]
	v_mfma_f32_16x16x32_bf16 v[64:67], v[188:191], v[220:223], v[64:67]
	s_barrier
; #define PG8_STAGE(bufoff, gbase, voff) do { _Pragma("unroll") for (int _i = 0; _i < 2; ++_i) \
;         __builtin_amdgcn_global_load_lds((const unsigned*)((const char*)(gbase) + (voff)[_i]), (PG8_LAS unsigned*)(lds + (bufoff) + ldsw + _i * 8192), 16, 0, 0); } while (0)
; #define PG8_LDA(dst, b, h) do { _Pragma("unroll") for (int m = 0; m < 4; ++m) _Pragma("unroll") for (int k = 0; k < 2; ++k) dst[m][k] = *(const PG8_LAS bf16x8*)(lds + PG8_SA(b, h) + aoff + m * 2048 + k * 1024); } while (0)
; #define PG8_MMA(ai, bj, At, Bt) do { __builtin_amdgcn_s_setprio(1); _Pragma("unroll") for (int m = 0; m < 4; ++m) _Pragma("unroll") for (int n = 0; n < 2; ++n) _Pragma("unroll") for (int k = 0; k < 2; ++k) \
;         acc[ai][bj][m][n] = __builtin_amdgcn_mfma_f32_16x16x32_bf16(Bt[n][k], At[m][k], acc[ai][bj][m][n], 0, 0, 0); __builtin_amdgcn_s_setprio(0); } while (0)
; #define PG8_WAIT_V(n) asm volatile("s_waitcnt vmcnt(" #n ")" ::: "memory")
; #define PG8_WAIT_L(n) asm volatile("s_waitcnt lgkmcnt(" #n ")" ::: "memory")
; #define PG8_BAR __builtin_amdgcn_s_barrier()
; #define PG8_SCHED __builtin_amdgcn_sched_barrier(0)
; template <class Epi, class Sched, bool ALIGN_EPI = false, bool SP2 = false>
; __device__ __forceinline__ void gemm_phase(PG8_LAS unsigned char* lds, const Gemm g, const Sched& S, const Epi& E) {
;     ...
;             PG8_LDA(At, 1, 1); PG8_STAGE(PG8_SB(1, 0), b3, voffB); PG8_STAGE(PG8_SB(1, 1), b3 + hstep, voffB); PG8_STAGE(PG8_SA(1, 0), a3, voffA);
;             PG8_WAIT_V(8); PG8_WAIT_L(0); PG8_BAR; PG8_MMA(1, 0, At, B0); PG8_MMA(1, 1, At, B1); PG8_BAR; PG8_SCHED;
;     ...
;         if constexpr (ALIGN_EPI) { if (wr == 0) PG8_BAR; }
	s_setprio 0
	s_add_i32 s26, s47, s28
	v_lshl_add_u64 v[154:155], v[154:155], 0, s[8:9]
	s_mov_b32 m0, s26
	ds_read_b128 v[192:195], v162 offset:49152
	ds_read_b128 v[196:199], v162 offset:50176
	ds_read_b128 v[200:203], v162 offset:51200
	ds_read_b128 v[204:207], v162 offset:52224
	ds_read_b128 v[208:211], v162 offset:53248
	ds_read_b128 v[212:215], v162 offset:54272
	ds_read_b128 v[216:219], v162 offset:55296
	ds_read_b128 v[220:223], v162 offset:56320
	global_load_lds_dwordx4 v[154:155], off
	s_add_i32 m0, s26, 0x2000
	s_add_u32 s24, s24, 0x40080
	v_lshl_add_u64 v[154:155], v[184:185], 0, s[8:9]
	s_addc_u32 s25, s25, 0
	s_add_i32 s26, s48, s28
	global_load_lds_dwordx4 v[154:155], off
	v_lshl_add_u64 v[154:155], s[24:25], 0, v[130:131]
	s_mov_b32 m0, s26
	s_nop 0
	global_load_lds_dwordx4 v[154:155], off
	v_lshl_add_u64 v[154:155], s[24:25], 0, v[134:135]
	s_add_i32 m0, s26, 0x2000
	s_nop 0
	global_load_lds_dwordx4 v[154:155], off
	v_lshl_add_u64 v[154:155], v[224:225], 0, s[8:9]
	s_mov_b32 m0, s36
	s_nop 0
	global_load_lds_dwordx4 v[154:155], off
	v_lshl_add_u64 v[154:155], v[226:227], 0, s[8:9]
	s_mov_b32 m0, s37
	s_nop 0
	global_load_lds_dwordx4 v[154:155], off
	s_setprio 1
	s_waitcnt vmcnt(8)
	s_waitcnt lgkmcnt(0)
	s_barrier
	v_mfma_f32_16x16x32_bf16 v[60:63], v[146:149], v[192:195], v[60:63]
	v_mfma_f32_16x16x32_bf16 v[56:59], v[164:167], v[192:195], v[56:59]
	v_mfma_f32_16x16x32_bf16 v[44:47], v[146:149], v[200:203], v[44:47]
	v_mfma_f32_16x16x32_bf16 v[40:43], v[164:167], v[200:203], v[40:43]
	v_mfma_f32_16x16x32_bf16 v[28:31], v[146:149], v[208:211], v[28:31]
	v_mfma_f32_16x16x32_bf16 v[24:27], v[164:167], v[208:211], v[24:27]
	v_mfma_f32_16x16x32_bf16 v[12:15], v[146:149], v[216:219], v[12:15]
	v_mfma_f32_16x16x32_bf16 v[8:11], v[164:167], v[216:219], v[8:11]
	v_mfma_f32_16x16x32_bf16 v[60:63], v[150:153], v[196:199], v[60:63]
	v_mfma_f32_16x16x32_bf16 v[56:59], v[168:171], v[196:199], v[56:59]
	v_mfma_f32_16x16x32_bf16 v[44:47], v[150:153], v[204:207], v[44:47]
	v_mfma_f32_16x16x32_bf16 v[40:43], v[168:171], v[204:207], v[40:43]
	v_mfma_f32_16x16x32_bf16 v[28:31], v[150:153], v[212:215], v[28:31]
	v_mfma_f32_16x16x32_bf16 v[24:27], v[168:171], v[212:215], v[24:27]
	v_mfma_f32_16x16x32_bf16 v[12:15], v[150:153], v[220:223], v[12:15]
	v_mfma_f32_16x16x32_bf16 v[8:11], v[168:171], v[220:223], v[8:11]
	s_setprio 0
	s_setprio 1
	v_mfma_f32_16x16x32_bf16 v[52:55], v[172:175], v[192:195], v[52:55]
	v_mfma_f32_16x16x32_bf16 v[48:51], v[180:183], v[192:195], v[48:51]
	v_mfma_f32_16x16x32_bf16 v[36:39], v[172:175], v[200:203], v[36:39]
	v_mfma_f32_16x16x32_bf16 v[32:35], v[180:183], v[200:203], v[32:35]
	v_mfma_f32_16x16x32_bf16 v[20:23], v[172:175], v[208:211], v[20:23]
	v_mfma_f32_16x16x32_bf16 v[16:19], v[180:183], v[208:211], v[16:19]
	v_mfma_f32_16x16x32_bf16 v[4:7], v[172:175], v[216:219], v[4:7]
	v_mfma_f32_16x16x32_bf16 v[0:3], v[180:183], v[216:219], v[0:3]
	v_mfma_f32_16x16x32_bf16 v[52:55], v[176:179], v[196:199], v[52:55]
	v_mfma_f32_16x16x32_bf16 v[48:51], v[188:191], v[196:199], v[48:51]
	v_mfma_f32_16x16x32_bf16 v[36:39], v[176:179], v[204:207], v[36:39]
	v_mfma_f32_16x16x32_bf16 v[32:35], v[188:191], v[204:207], v[32:35]
	v_mfma_f32_16x16x32_bf16 v[20:23], v[176:179], v[212:215], v[20:23]
	v_mfma_f32_16x16x32_bf16 v[16:19], v[188:191], v[212:215], v[16:19]
	v_mfma_f32_16x16x32_bf16 v[4:7], v[176:179], v[220:223], v[4:7]
	v_mfma_f32_16x16x32_bf16 v[0:3], v[188:191], v[220:223], v[0:3]
	s_barrier
	s_setprio 0
	s_add_i32 s46, s46, 2
	s_add_u32 s22, s22, 0x100
	s_addc_u32 s23, s23, 0
	s_add_u32 s44, s44, 0x100
	s_addc_u32 s45, s45, 0
	s_cmp_gt_u32 s46, 13
	s_cbranch_scc0 .LBB0_572
	s_and_b64 vcc, exec, s[10:11]
	s_cbranch_vccz .LBB0_575
	s_barrier

;     __device__ __forceinline__ bool next(int i, Unit& u) const { if (!base.next(i >> 1, u)) return false; if (i & 1) { u.pm += 64; u.pn += 8; } return true; }
; #define PG8_STAGE(bufoff, gbase, voff) do { _Pragma("unroll") for (int _i = 0; _i < 2; ++_i) \
;         __builtin_amdgcn_global_load_lds((const unsigned*)((const char*)(gbase) + (voff)[_i]), (PG8_LAS unsigned*)(lds + (bufoff) + ldsw + _i * 8192), 16, 0, 0); } while (0)
; #define PG8_LDA(dst, b, h) do { _Pragma("unroll") for (int m = 0; m < 4; ++m) _Pragma("unroll") for (int k = 0; k < 2; ++k) dst[m][k] = *(const PG8_LAS bf16x8*)(lds + PG8_SA(b, h) + aoff + m * 2048 + k * 1024); } while (0)
; #define PG8_LDB(dst, b, h) do { _Pragma("unroll") for (int n = 0; n < 2; ++n) _Pragma("unroll") for (int k = 0; k < 2; ++k) dst[n][k] = *(const PG8_LAS bf16x8*)(lds + PG8_SB(b, h) + boff + n * 2048 + k * 1024); } while (0)
; #define PG8_WAIT_V(n) asm volatile("s_waitcnt vmcnt(" #n ")" ::: "memory")
; #define PG8_BAR __builtin_amdgcn_s_barrier()
; template <class Epi, class Sched, bool ALIGN_EPI = false, bool SP2 = false>
; __device__ __forceinline__ void gemm_phase(PG8_LAS unsigned char* lds, const Gemm g, const Sched& S, const Epi& E) {
;     ...
;         const bool has_next = S.next(ui + 1, nxt);
;         const char* nA = has_next ? (const char*)g.A + (size_t)nxt.pm * tstep : cA; const char* nB = has_next ? (const char*)g.Bt + (size_t)nxt.pn * tstep : cB;
;         for (int t = 0; t < nt; t += 2) {
;             const bool last = (t == nt - 2);
;             const char* a1 = cA + (size_t)(t + 1) * kstep;
;             const char* a2 = last ? nA : cA + (size_t)(t + 2) * kstep; const char* b2 = last ? nB : cB + (size_t)(t + 2) * kstep;
;             const char* a3 = a2 + kstep; const char* b3 = b2 + kstep;
;             if (last && has_next) S.a_ready(nxt);
;             if constexpr (SP2) {
;             PG8_LDB(B0, 0, 0); PG8_LDB(B1, 0, 1); PG8_SCHED; PG8_LDA(At, 0, 0); PG8_STAGE(PG8_SA(1, 1), a1 + hstep, voffA);
;             PG8_WAIT_V(8); PG8_WAIT_L(0); PG8_BAR; PG8_MMA(0, 0, At, B0); PG8_MMA(0, 1, At, B1); PG8_BAR; PG8_SCHED;
;             PG8_LDA(At, 0, 1); PG8_STAGE(PG8_SB(0, 0), b2, voffB); PG8_STAGE(PG8_SB(0, 1), b2 + hstep, voffB); PG8_STAGE(PG8_SA(0, 0), a2, voffA);
;             PG8_WAIT_V(8); PG8_WAIT_L(0); PG8_BAR; PG8_MMA(1, 0, At, B0); PG8_MMA(1, 1, At, B1); PG8_BAR; PG8_SCHED;
.LBB0_893:
	s_ashr_i32 s25, s24, 31
	s_lshl_b64 s[28:29], s[24:25], 20
	v_readlane_b32 s30, v236, 50
	v_readlane_b32 s31, v236, 51
	s_add_u32 s28, s30, s28
	s_addc_u32 s29, s31, s29
	s_and_b64 s[30:31], s[6:7], exec
	s_cselect_b32 s25, s29, s39
	s_cselect_b32 s35, s28, s38
	s_ashr_i32 s27, s26, 31
	s_lshl_b64 s[30:31], s[26:27], 20
	v_readlane_b32 s42, v236, 43
	v_readlane_b32 s43, v236, 44
	s_add_u32 s30, s42, s30
	s_addc_u32 s31, s43, s31
	s_and_b64 s[42:43], s[6:7], exec
	s_cselect_b32 s27, s31, s41
	s_cselect_b32 s55, s30, s40
	s_add_u32 s38, s38, 0x80080
	s_addc_u32 s39, s39, 0
	s_add_u32 s56, s40, 0x100
	s_addc_u32 s57, s41, 0
	s_mov_b32 s58, -2
	s_waitcnt lgkmcnt(0)
	ds_read_b128 v[72:75], v169
	ds_read_b128 v[84:87], v169 offset:1024
	ds_read_b128 v[92:95], v169 offset:2048
	ds_read_b128 v[96:99], v169 offset:3072
	ds_read_b128 v[156:159], v170
	ds_read_b128 v[160:163], v170 offset:1024
	ds_read_b128 v[174:177], v170 offset:2048
	ds_read_b128 v[178:181], v170 offset:3072
	s_add_u32 s40, s38, 0xfff80080
	s_addc_u32 s41, s39, -1
	s_cmp_eq_u32 s58, 28
	s_cselect_b32 s43, s25, s41
	s_cselect_b32 s42, s35, s40
	s_cselect_b32 s41, s27, s57
	s_cselect_b32 s40, s55, s56
	v_lshl_add_u64 v[164:165], s[38:39], 0, v[148:149]
	s_add_i32 m0, s37, 0xc000
	ds_read_b128 v[182:185], v171
	ds_read_b128 v[188:191], v171 offset:1024
	ds_read_b128 v[192:195], v171 offset:2048
	ds_read_b128 v[196:199], v171 offset:3072
	ds_read_b128 v[200:203], v171 offset:4096
	ds_read_b128 v[204:207], v171 offset:5120
	ds_read_b128 v[208:211], v171 offset:6144
	ds_read_b128 v[212:215], v171 offset:7168
	global_load_lds_dwordx4 v[164:165], off
	v_lshl_add_u64 v[164:165], s[38:39], 0, v[150:151]
	s_add_i32 m0, s37, 0xe000
	s_nop 0
	global_load_lds_dwordx4 v[164:165], off
	s_setprio 1
	s_waitcnt vmcnt(8)
	s_waitcnt lgkmcnt(0)
	s_barrier
	v_mfma_f32_16x16x32_bf16 v[140:143], v[72:75], v[182:185], 0
	v_mfma_f32_16x16x32_bf16 v[136:139], v[92:95], v[182:185], 0
	v_mfma_f32_16x16x32_bf16 v[124:127], v[72:75], v[192:195], 0
	v_mfma_f32_16x16x32_bf16 v[120:123], v[92:95], v[192:195], 0
	v_mfma_f32_16x16x32_bf16 v[108:111], v[72:75], v[200:203], 0
	v_mfma_f32_16x16x32_bf16 v[104:107], v[92:95], v[200:203], 0
	v_mfma_f32_16x16x32_bf16 v[80:83], v[72:75], v[208:211], 0
	v_mfma_f32_16x16x32_bf16 v[76:79], v[92:95], v[208:211], 0
	v_mfma_f32_16x16x32_bf16 v[140:143], v[84:87], v[188:191], v[140:143]
	v_mfma_f32_16x16x32_bf16 v[136:139], v[96:99], v[188:191], v[136:139]
	v_mfma_f32_16x16x32_bf16 v[124:127], v[84:87], v[196:199], v[124:127]
	v_mfma_f32_16x16x32_bf16 v[120:123], v[96:99], v[196:199], v[120:123]
	v_mfma_f32_16x16x32_bf16 v[108:111], v[84:87], v[204:207], v[108:111]
	v_mfma_f32_16x16x32_bf16 v[104:107], v[96:99], v[204:207], v[104:107]
	v_mfma_f32_16x16x32_bf16 v[80:83], v[84:87], v[212:215], v[80:83]
	v_mfma_f32_16x16x32_bf16 v[76:79], v[96:99], v[212:215], v[76:79]
	s_setprio 0
	s_setprio 1
	v_mfma_f32_16x16x32_bf16 v[132:135], v[156:159], v[182:185], 0
	v_mfma_f32_16x16x32_bf16 v[128:131], v[174:177], v[182:185], 0
	v_mfma_f32_16x16x32_bf16 v[116:119], v[156:159], v[192:195], 0
	v_mfma_f32_16x16x32_bf16 v[112:115], v[174:177], v[192:195], 0
	v_mfma_f32_16x16x32_bf16 v[100:103], v[156:159], v[200:203], 0
	v_mfma_f32_16x16x32_bf16 v[88:91], v[174:177], v[200:203], 0
	v_mfma_f32_16x16x32_bf16 v[68:71], v[156:159], v[208:211], 0
	v_mfma_f32_16x16x32_bf16 v[64:67], v[174:177], v[208:211], 0
	v_mfma_f32_16x16x32_bf16 v[132:135], v[160:163], v[188:191], v[132:135]
	v_mfma_f32_16x16x32_bf16 v[128:131], v[178:181], v[188:191], v[128:131]
	v_mfma_f32_16x16x32_bf16 v[116:119], v[160:163], v[196:199], v[116:119]
	v_mfma_f32_16x16x32_bf16 v[112:115], v[178:181], v[196:199], v[112:115]
	v_mfma_f32_16x16x32_bf16 v[100:103], v[160:163], v[204:207], v[100:103]
	v_mfma_f32_16x16x32_bf16 v[88:91], v[178:181], v[204:207], v[88:91]
	v_mfma_f32_16x16x32_bf16 v[68:71], v[160:163], v[212:215], v[68:71]
	v_mfma_f32_16x16x32_bf16 v[64:67], v[178:181], v[212:215], v[64:67]
	s_barrier
	s_setprio 0
	s_add_i32 s59, s53, s33
	v_lshl_add_u64 v[164:165], s[40:41], 0, v[144:145]
	s_mov_b32 m0, s59
	ds_read_b128 v[182:185], v171 offset:16384
	ds_read_b128 v[188:191], v171 offset:17408
	ds_read_b128 v[192:195], v171 offset:18432
	ds_read_b128 v[196:199], v171 offset:19456
	ds_read_b128 v[200:203], v171 offset:20480
	ds_read_b128 v[204:207], v171 offset:21504
	ds_read_b128 v[208:211], v171 offset:22528
	ds_read_b128 v[212:215], v171 offset:23552
	global_load_lds_dwordx4 v[164:165], off
	s_add_i32 m0, s59, 0x2000
	s_add_u32 s60, s40, 0x80000
	v_lshl_add_u64 v[216:217], s[40:41], 0, v[146:147]
	s_addc_u32 s61, s41, 0
	s_add_i32 s59, s54, s33
	global_load_lds_dwordx4 v[216:217], off
	v_lshl_add_u64 v[218:219], s[60:61], 0, v[144:145]
	s_mov_b32 m0, s59
	v_lshl_add_u64 v[220:221], s[42:43], 0, v[146:147]
	global_load_lds_dwordx4 v[218:219], off
	v_lshl_add_u64 v[218:219], s[60:61], 0, v[146:147]
	s_add_i32 m0, s59, 0x2000
	s_nop 0
	global_load_lds_dwordx4 v[218:219], off
	v_lshl_add_u64 v[218:219], s[42:43], 0, v[144:145]
	s_mov_b32 m0, s37
	s_nop 0
	global_load_lds_dwordx4 v[218:219], off
	s_mov_b32 m0, s44
	s_nop 0
	global_load_lds_dwordx4 v[220:221], off
	s_setprio 1
	s_waitcnt vmcnt(8)
	s_waitcnt lgkmcnt(0)
	s_barrier
; #define PG8_STAGE(bufoff, gbase, voff) do { _Pragma("unroll") for (int _i = 0; _i < 2; ++_i) \
;         __builtin_amdgcn_global_load_lds((const unsigned*)((const char*)(gbase) + (voff)[_i]), (PG8_LAS unsigned*)(lds + (bufoff) + ldsw + _i * 8192), 16, 0, 0); } while (0)
; #define PG8_LDA(dst, b, h) do { _Pragma("unroll") for (int m = 0; m < 4; ++m) _Pragma("unroll") for (int k = 0; k < 2; ++k) dst[m][k] = *(const PG8_LAS bf16x8*)(lds + PG8_SA(b, h) + aoff + m * 2048 + k * 1024); } while (0)
; #define PG8_LDB(dst, b, h) do { _Pragma("unroll") for (int n = 0; n < 2; ++n) _Pragma("unroll") for (int k = 0; k < 2; ++k) dst[n][k] = *(const PG8_LAS bf16x8*)(lds + PG8_SB(b, h) + boff + n * 2048 + k * 1024); } while (0)
; #define PG8_MMA(ai, bj, At, Bt) do { __builtin_amdgcn_s_setprio(1); _Pragma("unroll") for (int m = 0; m < 4; ++m) _Pragma("unroll") for (int n = 0; n < 2; ++n) _Pragma("unroll") for (int k = 0; k < 2; ++k) \
;         acc[ai][bj][m][n] = __builtin_amdgcn_mfma_f32_16x16x32_bf16(Bt[n][k], At[m][k], acc[ai][bj][m][n], 0, 0, 0); __builtin_amdgcn_s_setprio(0); } while (0)
; #define PG8_WAIT_V(n) asm volatile("s_waitcnt vmcnt(" #n ")" ::: "memory")
; #define PG8_WAIT_L(n) asm volatile("s_waitcnt lgkmcnt(" #n ")" ::: "memory")
; #define PG8_BAR __builtin_amdgcn_s_barrier()
; #define PG8_SCHED __builtin_amdgcn_sched_barrier(0)
; template <class Epi, class Sched, bool ALIGN_EPI = false, bool SP2 = false>
; __device__ __forceinline__ void gemm_phase(PG8_LAS unsigned char* lds, const Gemm g, const Sched& S, const Epi& E) {
;     ...
;             PG8_WAIT_V(8); PG8_WAIT_L(0); PG8_BAR; PG8_MMA(1, 0, At, B0); PG8_MMA(1, 1, At, B1); PG8_BAR; PG8_SCHED;
;             PG8_LDB(B0, 1, 0); PG8_LDB(B1, 1, 1); PG8_SCHED; PG8_LDA(At, 1, 0); PG8_STAGE(PG8_SA(0, 1), a2 + hstep, voffA);
;             PG8_WAIT_V(8); PG8_WAIT_L(0); PG8_BAR; PG8_MMA(0, 0, At, B0); PG8_MMA(0, 1, At, B1); PG8_BAR; PG8_SCHED;
	v_mfma_f32_16x16x32_bf16 v[60:63], v[72:75], v[182:185], 0
	v_mfma_f32_16x16x32_bf16 v[56:59], v[92:95], v[182:185], 0
	v_mfma_f32_16x16x32_bf16 v[44:47], v[72:75], v[192:195], 0
	v_mfma_f32_16x16x32_bf16 v[40:43], v[92:95], v[192:195], 0
	v_mfma_f32_16x16x32_bf16 v[28:31], v[72:75], v[200:203], 0
	v_mfma_f32_16x16x32_bf16 v[24:27], v[92:95], v[200:203], 0
	v_mfma_f32_16x16x32_bf16 v[12:15], v[72:75], v[208:211], 0
	v_mfma_f32_16x16x32_bf16 v[8:11], v[92:95], v[208:211], 0
	v_mfma_f32_16x16x32_bf16 v[60:63], v[84:87], v[188:191], v[60:63]
	v_mfma_f32_16x16x32_bf16 v[56:59], v[96:99], v[188:191], v[56:59]
	v_mfma_f32_16x16x32_bf16 v[44:47], v[84:87], v[196:199], v[44:47]
	v_mfma_f32_16x16x32_bf16 v[40:43], v[96:99], v[196:199], v[40:43]
	v_mfma_f32_16x16x32_bf16 v[28:31], v[84:87], v[204:207], v[28:31]
	v_mfma_f32_16x16x32_bf16 v[24:27], v[96:99], v[204:207], v[24:27]
	v_mfma_f32_16x16x32_bf16 v[12:15], v[84:87], v[212:215], v[12:15]
	v_mfma_f32_16x16x32_bf16 v[8:11], v[96:99], v[212:215], v[8:11]
	s_setprio 0
	s_setprio 1
	v_mfma_f32_16x16x32_bf16 v[52:55], v[156:159], v[182:185], 0
	v_mfma_f32_16x16x32_bf16 v[48:51], v[174:177], v[182:185], 0
	v_mfma_f32_16x16x32_bf16 v[36:39], v[156:159], v[192:195], 0
	v_mfma_f32_16x16x32_bf16 v[32:35], v[174:177], v[192:195], 0
	v_mfma_f32_16x16x32_bf16 v[20:23], v[156:159], v[200:203], 0
	v_mfma_f32_16x16x32_bf16 v[16:19], v[174:177], v[200:203], 0
	v_mfma_f32_16x16x32_bf16 v[4:7], v[156:159], v[208:211], 0
	v_mfma_f32_16x16x32_bf16 v[0:3], v[174:177], v[208:211], 0
	v_mfma_f32_16x16x32_bf16 v[52:55], v[160:163], v[188:191], v[52:55]
	v_mfma_f32_16x16x32_bf16 v[48:51], v[178:181], v[188:191], v[48:51]
	v_mfma_f32_16x16x32_bf16 v[36:39], v[160:163], v[196:199], v[36:39]
	v_mfma_f32_16x16x32_bf16 v[32:35], v[178:181], v[196:199], v[32:35]
	v_mfma_f32_16x16x32_bf16 v[20:23], v[160:163], v[204:207], v[20:23]
	v_mfma_f32_16x16x32_bf16 v[16:19], v[178:181], v[204:207], v[16:19]
	v_mfma_f32_16x16x32_bf16 v[4:7], v[160:163], v[212:215], v[4:7]
	v_mfma_f32_16x16x32_bf16 v[0:3], v[178:181], v[212:215], v[0:3]
	s_barrier
	s_setprio 0
	s_add_i32 s59, 0, 0x18000
	s_add_i32 s60, 0, 0x1c000
	v_add_u32_e32 v96, s59, v167
	v_add_u32_e32 v173, s60, v167
	ds_read_b128 v[72:75], v96
	ds_read_b128 v[84:87], v96 offset:1024
	ds_read_b128 v[92:95], v96 offset:2048
	ds_read_b128 v[96:99], v96 offset:3072
	ds_read_b128 v[156:159], v173
	ds_read_b128 v[160:163], v173 offset:1024
	ds_read_b128 v[174:177], v173 offset:2048
	ds_read_b128 v[178:181], v173 offset:3072
	s_add_u32 s42, s42, 0x80000
	s_addc_u32 s43, s43, 0
	s_mov_b32 m0, s45
	v_lshl_add_u64 v[222:223], s[42:43], 0, v[144:145]
	ds_read_b128 v[182:185], v171 offset:32768
	ds_read_b128 v[188:191], v171 offset:33792
	ds_read_b128 v[192:195], v171 offset:34816
	ds_read_b128 v[196:199], v171 offset:35840
	ds_read_b128 v[200:203], v171 offset:36864
	ds_read_b128 v[204:207], v171 offset:37888
	ds_read_b128 v[208:211], v171 offset:38912
	ds_read_b128 v[212:215], v171 offset:39936
	global_load_lds_dwordx4 v[222:223], off
	v_lshl_add_u64 v[222:223], s[42:43], 0, v[146:147]
	s_mov_b32 m0, s46
	s_nop 0
	global_load_lds_dwordx4 v[222:223], off
	s_setprio 1
	s_waitcnt vmcnt(8)
	s_waitcnt lgkmcnt(0)
	s_barrier
	v_mfma_f32_16x16x32_bf16 v[140:143], v[72:75], v[182:185], v[140:143]
	v_mfma_f32_16x16x32_bf16 v[136:139], v[92:95], v[182:185], v[136:139]
	v_mfma_f32_16x16x32_bf16 v[124:127], v[72:75], v[192:195], v[124:127]
	v_mfma_f32_16x16x32_bf16 v[120:123], v[92:95], v[192:195], v[120:123]
	v_mfma_f32_16x16x32_bf16 v[108:111], v[72:75], v[200:203], v[108:111]
	v_mfma_f32_16x16x32_bf16 v[104:107], v[92:95], v[200:203], v[104:107]
	v_mfma_f32_16x16x32_bf16 v[80:83], v[72:75], v[208:211], v[80:83]
	v_mfma_f32_16x16x32_bf16 v[76:79], v[92:95], v[208:211], v[76:79]
	v_mfma_f32_16x16x32_bf16 v[140:143], v[84:87], v[188:191], v[140:143]
	v_mfma_f32_16x16x32_bf16 v[136:139], v[96:99], v[188:191], v[136:139]
	v_mfma_f32_16x16x32_bf16 v[124:127], v[84:87], v[196:199], v[124:127]
	v_mfma_f32_16x16x32_bf16 v[120:123], v[96:99], v[196:199], v[120:123]
	v_mfma_f32_16x16x32_bf16 v[108:111], v[84:87], v[204:207], v[108:111]
	v_mfma_f32_16x16x32_bf16 v[104:107], v[96:99], v[204:207], v[104:107]
	v_mfma_f32_16x16x32_bf16 v[80:83], v[84:87], v[212:215], v[80:83]
	v_mfma_f32_16x16x32_bf16 v[76:79], v[96:99], v[212:215], v[76:79]
	s_setprio 0
	s_setprio 1
	v_mfma_f32_16x16x32_bf16 v[132:135], v[156:159], v[182:185], v[132:135]
	v_mfma_f32_16x16x32_bf16 v[128:131], v[174:177], v[182:185], v[128:131]
	v_mfma_f32_16x16x32_bf16 v[116:119], v[156:159], v[192:195], v[116:119]
	v_mfma_f32_16x16x32_bf16 v[112:115], v[174:177], v[192:195], v[112:115]
	v_mfma_f32_16x16x32_bf16 v[100:103], v[156:159], v[200:203], v[100:103]
	v_mfma_f32_16x16x32_bf16 v[88:91], v[174:177], v[200:203], v[88:91]
	v_mfma_f32_16x16x32_bf16 v[68:71], v[156:159], v[208:211], v[68:71]
	v_mfma_f32_16x16x32_bf16 v[64:67], v[174:177], v[208:211], v[64:67]
	v_mfma_f32_16x16x32_bf16 v[132:135], v[160:163], v[188:191], v[132:135]
	v_mfma_f32_16x16x32_bf16 v[128:131], v[178:181], v[188:191], v[128:131]
	v_mfma_f32_16x16x32_bf16 v[116:119], v[160:163], v[196:199], v[116:119]
	v_mfma_f32_16x16x32_bf16 v[112:115], v[178:181], v[196:199], v[112:115]
	v_mfma_f32_16x16x32_bf16 v[100:103], v[160:163], v[204:207], v[100:103]
	v_mfma_f32_16x16x32_bf16 v[88:91], v[178:181], v[204:207], v[88:91]
	v_mfma_f32_16x16x32_bf16 v[68:71], v[160:163], v[212:215], v[68:71]
	v_mfma_f32_16x16x32_bf16 v[64:67], v[178:181], v[212:215], v[64:67]
	s_barrier
; #define PG8_STAGE(bufoff, gbase, voff) do { _Pragma("unroll") for (int _i = 0; _i < 2; ++_i) \
;         __builtin_amdgcn_global_load_lds((const unsigned*)((const char*)(gbase) + (voff)[_i]), (PG8_LAS unsigned*)(lds + (bufoff) + ldsw + _i * 8192), 16, 0, 0); } while (0)
; #define PG8_LDA(dst, b, h) do { _Pragma("unroll") for (int m = 0; m < 4; ++m) _Pragma("unroll") for (int k = 0; k < 2; ++k) dst[m][k] = *(const PG8_LAS bf16x8*)(lds + PG8_SA(b, h) + aoff + m * 2048 + k * 1024); } while (0)
; #define PG8_LDB(dst, b, h) do { _Pragma("unroll") for (int n = 0; n < 2; ++n) _Pragma("unroll") for (int k = 0; k < 2; ++k) dst[n][k] = *(const PG8_LAS bf16x8*)(lds + PG8_SB(b, h) + boff + n * 2048 + k * 1024); } while (0)
; #define PG8_MMA(ai, bj, At, Bt) do { __builtin_amdgcn_s_setprio(1); _Pragma("unroll") for (int m = 0; m < 4; ++m) _Pragma("unroll") for (int n = 0; n < 2; ++n) _Pragma("unroll") for (int k = 0; k < 2; ++k) \
;         acc[ai][bj][m][n] = __builtin_amdgcn_mfma_f32_16x16x32_bf16(Bt[n][k], At[m][k], acc[ai][bj][m][n], 0, 0, 0); __builtin_amdgcn_s_setprio(0); } while (0)
; #define PG8_WAIT_V(n) asm volatile("s_waitcnt vmcnt(" #n ")" ::: "memory")
; #define PG8_WAIT_L(n) asm volatile("s_waitcnt lgkmcnt(" #n ")" ::: "memory")
; #define PG8_BAR __builtin_amdgcn_s_barrier()
; #define PG8_SCHED __builtin_amdgcn_sched_barrier(0)
; template <class Epi, class Sched, bool ALIGN_EPI = false, bool SP2 = false>
; __device__ __forceinline__ void gemm_phase(PG8_LAS unsigned char* lds, const Gemm g, const Sched& S, const Epi& E) {
;     ...
;         for (int t = 0; t < nt; t += 2) {
;             const bool last = (t == nt - 2);
;             const char* a1 = cA + (size_t)(t + 1) * kstep;
;             const char* a2 = last ? nA : cA + (size_t)(t + 2) * kstep; const char* b2 = last ? nB : cB + (size_t)(t + 2) * kstep;
;             const char* a3 = a2 + kstep; const char* b3 = b2 + kstep;
;             if (last && has_next) S.a_ready(nxt);
;             if constexpr (SP2) {
;             PG8_LDB(B0, 0, 0); PG8_LDB(B1, 0, 1); PG8_SCHED; PG8_LDA(At, 0, 0); PG8_STAGE(PG8_SA(1, 1), a1 + hstep, voffA);
;     ...
;             PG8_LDA(At, 1, 1); PG8_STAGE(PG8_SB(1, 0), b3, voffB); PG8_STAGE(PG8_SB(1, 1), b3 + hstep, voffB); PG8_STAGE(PG8_SA(1, 0), a3, voffA);
;             PG8_WAIT_V(8); PG8_WAIT_L(0); PG8_BAR; PG8_MMA(1, 0, At, B0); PG8_MMA(1, 1, At, B1); PG8_BAR; PG8_SCHED;
	s_setprio 0
	s_add_i32 s42, s59, s33
	v_lshl_add_u64 v[164:165], v[164:165], 0, s[12:13]
	s_mov_b32 m0, s42
	ds_read_b128 v[182:185], v171 offset:49152
	ds_read_b128 v[188:191], v171 offset:50176
	ds_read_b128 v[192:195], v171 offset:51200
	ds_read_b128 v[196:199], v171 offset:52224
	ds_read_b128 v[200:203], v171 offset:53248
	ds_read_b128 v[204:207], v171 offset:54272
	ds_read_b128 v[208:211], v171 offset:55296
	ds_read_b128 v[212:215], v171 offset:56320
	global_load_lds_dwordx4 v[164:165], off
	s_add_i32 m0, s42, 0x2000
	s_add_u32 s40, s40, 0x80080
	v_lshl_add_u64 v[164:165], v[216:217], 0, s[12:13]
	s_addc_u32 s41, s41, 0
	s_add_i32 s42, s60, s33
	global_load_lds_dwordx4 v[164:165], off
	v_lshl_add_u64 v[164:165], s[40:41], 0, v[144:145]
	s_mov_b32 m0, s42
	s_nop 0
	global_load_lds_dwordx4 v[164:165], off
	v_lshl_add_u64 v[164:165], s[40:41], 0, v[146:147]
	s_add_i32 m0, s42, 0x2000
	s_nop 0
	global_load_lds_dwordx4 v[164:165], off
	v_lshl_add_u64 v[164:165], v[218:219], 0, s[12:13]
	s_mov_b32 m0, s50
	s_nop 0
	global_load_lds_dwordx4 v[164:165], off
	v_lshl_add_u64 v[164:165], v[220:221], 0, s[12:13]
	s_mov_b32 m0, s51
	s_nop 0
	global_load_lds_dwordx4 v[164:165], off
	s_setprio 1
	s_waitcnt vmcnt(8)
	s_waitcnt lgkmcnt(0)
	s_barrier
	v_mfma_f32_16x16x32_bf16 v[60:63], v[72:75], v[182:185], v[60:63]
	v_mfma_f32_16x16x32_bf16 v[56:59], v[92:95], v[182:185], v[56:59]
	v_mfma_f32_16x16x32_bf16 v[44:47], v[72:75], v[192:195], v[44:47]
	v_mfma_f32_16x16x32_bf16 v[40:43], v[92:95], v[192:195], v[40:43]
	v_mfma_f32_16x16x32_bf16 v[28:31], v[72:75], v[200:203], v[28:31]
	v_mfma_f32_16x16x32_bf16 v[24:27], v[92:95], v[200:203], v[24:27]
	v_mfma_f32_16x16x32_bf16 v[12:15], v[72:75], v[208:211], v[12:15]
	v_mfma_f32_16x16x32_bf16 v[8:11], v[92:95], v[208:211], v[8:11]
	v_mfma_f32_16x16x32_bf16 v[60:63], v[84:87], v[188:191], v[60:63]
	v_mfma_f32_16x16x32_bf16 v[56:59], v[96:99], v[188:191], v[56:59]
	v_mfma_f32_16x16x32_bf16 v[44:47], v[84:87], v[196:199], v[44:47]
	v_mfma_f32_16x16x32_bf16 v[40:43], v[96:99], v[196:199], v[40:43]
	v_mfma_f32_16x16x32_bf16 v[28:31], v[84:87], v[204:207], v[28:31]
	v_mfma_f32_16x16x32_bf16 v[24:27], v[96:99], v[204:207], v[24:27]
	v_mfma_f32_16x16x32_bf16 v[12:15], v[84:87], v[212:215], v[12:15]
	v_mfma_f32_16x16x32_bf16 v[8:11], v[96:99], v[212:215], v[8:11]
	s_setprio 0
	s_setprio 1
	v_mfma_f32_16x16x32_bf16 v[52:55], v[156:159], v[182:185], v[52:55]
	v_mfma_f32_16x16x32_bf16 v[48:51], v[174:177], v[182:185], v[48:51]
	v_mfma_f32_16x16x32_bf16 v[36:39], v[156:159], v[192:195], v[36:39]
	v_mfma_f32_16x16x32_bf16 v[32:35], v[174:177], v[192:195], v[32:35]
	v_mfma_f32_16x16x32_bf16 v[20:23], v[156:159], v[200:203], v[20:23]
	v_mfma_f32_16x16x32_bf16 v[16:19], v[174:177], v[200:203], v[16:19]
	v_mfma_f32_16x16x32_bf16 v[4:7], v[156:159], v[208:211], v[4:7]
	v_mfma_f32_16x16x32_bf16 v[0:3], v[174:177], v[208:211], v[0:3]
	v_mfma_f32_16x16x32_bf16 v[52:55], v[160:163], v[188:191], v[52:55]
	v_mfma_f32_16x16x32_bf16 v[48:51], v[178:181], v[188:191], v[48:51]
	v_mfma_f32_16x16x32_bf16 v[36:39], v[160:163], v[196:199], v[36:39]
	v_mfma_f32_16x16x32_bf16 v[32:35], v[178:181], v[196:199], v[32:35]
	v_mfma_f32_16x16x32_bf16 v[20:23], v[160:163], v[204:207], v[20:23]
	v_mfma_f32_16x16x32_bf16 v[16:19], v[178:181], v[204:207], v[16:19]
	v_mfma_f32_16x16x32_bf16 v[4:7], v[160:163], v[212:215], v[4:7]
	v_mfma_f32_16x16x32_bf16 v[0:3], v[178:181], v[212:215], v[0:3]
	s_barrier
	s_setprio 0
	s_add_i32 s58, s58, 2
	s_add_u32 s38, s38, 0x100
	s_addc_u32 s39, s39, 0
	s_add_u32 s56, s56, 0x100
	s_addc_u32 s57, s57, 0
	s_cmp_gt_u32 s58, 29
.LBB0_894:
	ds_read_b128 v[72:75], v169
	ds_read_b128 v[84:87], v169 offset:1024
	ds_read_b128 v[92:95], v169 offset:2048
	ds_read_b128 v[96:99], v169 offset:3072
	ds_read_b128 v[156:159], v170
	ds_read_b128 v[160:163], v170 offset:1024
	ds_read_b128 v[174:177], v170 offset:2048
	ds_read_b128 v[178:181], v170 offset:3072
	s_add_u32 s40, s38, 0xfff80080
	s_addc_u32 s41, s39, -1
	s_cmp_eq_u32 s58, 28
	s_cselect_b32 s43, s25, s41
	s_cselect_b32 s42, s35, s40
	s_cselect_b32 s41, s27, s57
	s_cselect_b32 s40, s55, s56
	v_lshl_add_u64 v[164:165], s[38:39], 0, v[148:149]
	s_add_i32 m0, s37, 0xc000
	ds_read_b128 v[182:185], v171
	ds_read_b128 v[188:191], v171 offset:1024
	ds_read_b128 v[192:195], v171 offset:2048
	ds_read_b128 v[196:199], v171 offset:3072
	ds_read_b128 v[200:203], v171 offset:4096
	ds_read_b128 v[204:207], v171 offset:5120
	ds_read_b128 v[208:211], v171 offset:6144
	ds_read_b128 v[212:215], v171 offset:7168
	global_load_lds_dwordx4 v[164:165], off
	v_lshl_add_u64 v[164:165], s[38:39], 0, v[150:151]
	s_add_i32 m0, s37, 0xe000
	s_nop 0
	global_load_lds_dwordx4 v[164:165], off
	s_setprio 1
	s_waitcnt vmcnt(8)
	s_waitcnt lgkmcnt(0)
	s_barrier
; #define PG8_STAGE(bufoff, gbase, voff) do { _Pragma("unroll") for (int _i = 0; _i < 2; ++_i) \
;         __builtin_amdgcn_global_load_lds((const unsigned*)((const char*)(gbase) + (voff)[_i]), (PG8_LAS unsigned*)(lds + (bufoff) + ldsw + _i * 8192), 16, 0, 0); } while (0)
; #define PG8_LDA(dst, b, h) do { _Pragma("unroll") for (int m = 0; m < 4; ++m) _Pragma("unroll") for (int k = 0; k < 2; ++k) dst[m][k] = *(const PG8_LAS bf16x8*)(lds + PG8_SA(b, h) + aoff + m * 2048 + k * 1024); } while (0)
; #define PG8_LDB(dst, b, h) do { _Pragma("unroll") for (int n = 0; n < 2; ++n) _Pragma("unroll") for (int k = 0; k < 2; ++k) dst[n][k] = *(const PG8_LAS bf16x8*)(lds + PG8_SB(b, h) + boff + n * 2048 + k * 1024); } while (0)
; #define PG8_MMA(ai, bj, At, Bt) do { __builtin_amdgcn_s_setprio(1); _Pragma("unroll") for (int m = 0; m < 4; ++m) _Pragma("unroll") for (int n = 0; n < 2; ++n) _Pragma("unroll") for (int k = 0; k < 2; ++k) \
;         acc[ai][bj][m][n] = __builtin_amdgcn_mfma_f32_16x16x32_bf16(Bt[n][k], At[m][k], acc[ai][bj][m][n], 0, 0, 0); __builtin_amdgcn_s_setprio(0); } while (0)
; #define PG8_WAIT_V(n) asm volatile("s_waitcnt vmcnt(" #n ")" ::: "memory")
; #define PG8_WAIT_L(n) asm volatile("s_waitcnt lgkmcnt(" #n ")" ::: "memory")
; #define PG8_BAR __builtin_amdgcn_s_barrier()
; #define PG8_SCHED __builtin_amdgcn_sched_barrier(0)
; template <class Epi, class Sched, bool ALIGN_EPI = false, bool SP2 = false>
; __device__ __forceinline__ void gemm_phase(PG8_LAS unsigned char* lds, const Gemm g, const Sched& S, const Epi& E) {
;     ...
;             PG8_LDB(B0, 0, 0); PG8_LDB(B1, 0, 1); PG8_SCHED; PG8_LDA(At, 0, 0); PG8_STAGE(PG8_SA(1, 1), a1 + hstep, voffA);
;             PG8_WAIT_V(8); PG8_WAIT_L(0); PG8_BAR; PG8_MMA(0, 0, At, B0); PG8_MMA(0, 1, At, B1); PG8_BAR; PG8_SCHED;
;             PG8_LDA(At, 0, 1); PG8_STAGE(PG8_SB(0, 0), b2, voffB); PG8_STAGE(PG8_SB(0, 1), b2 + hstep, voffB); PG8_STAGE(PG8_SA(0, 0), a2, voffA);
;             PG8_WAIT_V(8); PG8_WAIT_L(0); PG8_BAR; PG8_MMA(1, 0, At, B0); PG8_MMA(1, 1, At, B1); PG8_BAR; PG8_SCHED;
	v_mfma_f32_16x16x32_bf16 v[140:143], v[72:75], v[182:185], v[140:143]
	v_mfma_f32_16x16x32_bf16 v[136:139], v[92:95], v[182:185], v[136:139]
	v_mfma_f32_16x16x32_bf16 v[124:127], v[72:75], v[192:195], v[124:127]
	v_mfma_f32_16x16x32_bf16 v[120:123], v[92:95], v[192:195], v[120:123]
	v_mfma_f32_16x16x32_bf16 v[108:111], v[72:75], v[200:203], v[108:111]
	v_mfma_f32_16x16x32_bf16 v[104:107], v[92:95], v[200:203], v[104:107]
	v_mfma_f32_16x16x32_bf16 v[80:83], v[72:75], v[208:211], v[80:83]
	v_mfma_f32_16x16x32_bf16 v[76:79], v[92:95], v[208:211], v[76:79]
	v_mfma_f32_16x16x32_bf16 v[140:143], v[84:87], v[188:191], v[140:143]
	v_mfma_f32_16x16x32_bf16 v[136:139], v[96:99], v[188:191], v[136:139]
	v_mfma_f32_16x16x32_bf16 v[124:127], v[84:87], v[196:199], v[124:127]
	v_mfma_f32_16x16x32_bf16 v[120:123], v[96:99], v[196:199], v[120:123]
	v_mfma_f32_16x16x32_bf16 v[108:111], v[84:87], v[204:207], v[108:111]
	v_mfma_f32_16x16x32_bf16 v[104:107], v[96:99], v[204:207], v[104:107]
	v_mfma_f32_16x16x32_bf16 v[80:83], v[84:87], v[212:215], v[80:83]
	v_mfma_f32_16x16x32_bf16 v[76:79], v[96:99], v[212:215], v[76:79]
	s_setprio 0
	s_setprio 1
	v_mfma_f32_16x16x32_bf16 v[132:135], v[156:159], v[182:185], v[132:135]
	v_mfma_f32_16x16x32_bf16 v[128:131], v[174:177], v[182:185], v[128:131]
	v_mfma_f32_16x16x32_bf16 v[116:119], v[156:159], v[192:195], v[116:119]
	v_mfma_f32_16x16x32_bf16 v[112:115], v[174:177], v[192:195], v[112:115]
	v_mfma_f32_16x16x32_bf16 v[100:103], v[156:159], v[200:203], v[100:103]
	v_mfma_f32_16x16x32_bf16 v[88:91], v[174:177], v[200:203], v[88:91]
	v_mfma_f32_16x16x32_bf16 v[68:71], v[156:159], v[208:211], v[68:71]
	v_mfma_f32_16x16x32_bf16 v[64:67], v[174:177], v[208:211], v[64:67]
	v_mfma_f32_16x16x32_bf16 v[132:135], v[160:163], v[188:191], v[132:135]
	v_mfma_f32_16x16x32_bf16 v[128:131], v[178:181], v[188:191], v[128:131]
	v_mfma_f32_16x16x32_bf16 v[116:119], v[160:163], v[196:199], v[116:119]
	v_mfma_f32_16x16x32_bf16 v[112:115], v[178:181], v[196:199], v[112:115]
	v_mfma_f32_16x16x32_bf16 v[100:103], v[160:163], v[204:207], v[100:103]
	v_mfma_f32_16x16x32_bf16 v[88:91], v[178:181], v[204:207], v[88:91]
	v_mfma_f32_16x16x32_bf16 v[68:71], v[160:163], v[212:215], v[68:71]
	v_mfma_f32_16x16x32_bf16 v[64:67], v[178:181], v[212:215], v[64:67]
	s_barrier
	s_setprio 0
	s_add_i32 s59, s53, s33
	v_lshl_add_u64 v[164:165], s[40:41], 0, v[144:145]
	s_mov_b32 m0, s59
	ds_read_b128 v[182:185], v171 offset:16384
	ds_read_b128 v[188:191], v171 offset:17408
	ds_read_b128 v[192:195], v171 offset:18432
	ds_read_b128 v[196:199], v171 offset:19456
	ds_read_b128 v[200:203], v171 offset:20480
	ds_read_b128 v[204:207], v171 offset:21504
	ds_read_b128 v[208:211], v171 offset:22528
	ds_read_b128 v[212:215], v171 offset:23552
	global_load_lds_dwordx4 v[164:165], off
	s_add_i32 m0, s59, 0x2000
	s_add_u32 s60, s40, 0x80000
	v_lshl_add_u64 v[216:217], s[40:41], 0, v[146:147]
	s_addc_u32 s61, s41, 0
	s_add_i32 s59, s54, s33
	global_load_lds_dwordx4 v[216:217], off
	v_lshl_add_u64 v[218:219], s[60:61], 0, v[144:145]
	s_mov_b32 m0, s59
	v_lshl_add_u64 v[220:221], s[42:43], 0, v[146:147]
	global_load_lds_dwordx4 v[218:219], off
	v_lshl_add_u64 v[218:219], s[60:61], 0, v[146:147]
	s_add_i32 m0, s59, 0x2000
	s_nop 0
	global_load_lds_dwordx4 v[218:219], off
	v_lshl_add_u64 v[218:219], s[42:43], 0, v[144:145]
	s_mov_b32 m0, s37
	s_nop 0
	global_load_lds_dwordx4 v[218:219], off
	s_mov_b32 m0, s44
	s_nop 0
	global_load_lds_dwordx4 v[220:221], off
	s_setprio 1
	s_waitcnt vmcnt(8)
	s_waitcnt lgkmcnt(0)
	s_barrier
	v_mfma_f32_16x16x32_bf16 v[60:63], v[72:75], v[182:185], v[60:63]
	v_mfma_f32_16x16x32_bf16 v[56:59], v[92:95], v[182:185], v[56:59]
	v_mfma_f32_16x16x32_bf16 v[44:47], v[72:75], v[192:195], v[44:47]
	v_mfma_f32_16x16x32_bf16 v[40:43], v[92:95], v[192:195], v[40:43]
	v_mfma_f32_16x16x32_bf16 v[28:31], v[72:75], v[200:203], v[28:31]
	v_mfma_f32_16x16x32_bf16 v[24:27], v[92:95], v[200:203], v[24:27]
	v_mfma_f32_16x16x32_bf16 v[12:15], v[72:75], v[208:211], v[12:15]
	v_mfma_f32_16x16x32_bf16 v[8:11], v[92:95], v[208:211], v[8:11]
	v_mfma_f32_16x16x32_bf16 v[60:63], v[84:87], v[188:191], v[60:63]
	v_mfma_f32_16x16x32_bf16 v[56:59], v[96:99], v[188:191], v[56:59]
	v_mfma_f32_16x16x32_bf16 v[44:47], v[84:87], v[196:199], v[44:47]
	v_mfma_f32_16x16x32_bf16 v[40:43], v[96:99], v[196:199], v[40:43]
	v_mfma_f32_16x16x32_bf16 v[28:31], v[84:87], v[204:207], v[28:31]
	v_mfma_f32_16x16x32_bf16 v[24:27], v[96:99], v[204:207], v[24:27]
	v_mfma_f32_16x16x32_bf16 v[12:15], v[84:87], v[212:215], v[12:15]
	v_mfma_f32_16x16x32_bf16 v[8:11], v[96:99], v[212:215], v[8:11]
	s_setprio 0
	s_setprio 1
	v_mfma_f32_16x16x32_bf16 v[52:55], v[156:159], v[182:185], v[52:55]
	v_mfma_f32_16x16x32_bf16 v[48:51], v[174:177], v[182:185], v[48:51]
	v_mfma_f32_16x16x32_bf16 v[36:39], v[156:159], v[192:195], v[36:39]
	v_mfma_f32_16x16x32_bf16 v[32:35], v[174:177], v[192:195], v[32:35]
	v_mfma_f32_16x16x32_bf16 v[20:23], v[156:159], v[200:203], v[20:23]
	v_mfma_f32_16x16x32_bf16 v[16:19], v[174:177], v[200:203], v[16:19]
	v_mfma_f32_16x16x32_bf16 v[4:7], v[156:159], v[208:211], v[4:7]
	v_mfma_f32_16x16x32_bf16 v[0:3], v[174:177], v[208:211], v[0:3]
	v_mfma_f32_16x16x32_bf16 v[52:55], v[160:163], v[188:191], v[52:55]
	v_mfma_f32_16x16x32_bf16 v[48:51], v[178:181], v[188:191], v[48:51]
	v_mfma_f32_16x16x32_bf16 v[36:39], v[160:163], v[196:199], v[36:39]
	v_mfma_f32_16x16x32_bf16 v[32:35], v[178:181], v[196:199], v[32:35]
	v_mfma_f32_16x16x32_bf16 v[20:23], v[160:163], v[204:207], v[20:23]
	v_mfma_f32_16x16x32_bf16 v[16:19], v[178:181], v[204:207], v[16:19]
	v_mfma_f32_16x16x32_bf16 v[4:7], v[160:163], v[212:215], v[4:7]
	v_mfma_f32_16x16x32_bf16 v[0:3], v[178:181], v[212:215], v[0:3]
	s_barrier
; #define PG8_STAGE(bufoff, gbase, voff) do { _Pragma("unroll") for (int _i = 0; _i < 2; ++_i) \
;         __builtin_amdgcn_global_load_lds((const unsigned*)((const char*)(gbase) + (voff)[_i]), (PG8_LAS unsigned*)(lds + (bufoff) + ldsw + _i * 8192), 16, 0, 0); } while (0)
; #define PG8_LDA(dst, b, h) do { _Pragma("unroll") for (int m = 0; m < 4; ++m) _Pragma("unroll") for (int k = 0; k < 2; ++k) dst[m][k] = *(const PG8_LAS bf16x8*)(lds + PG8_SA(b, h) + aoff + m * 2048 + k * 1024); } while (0)
; #define PG8_LDB(dst, b, h) do { _Pragma("unroll") for (int n = 0; n < 2; ++n) _Pragma("unroll") for (int k = 0; k < 2; ++k) dst[n][k] = *(const PG8_LAS bf16x8*)(lds + PG8_SB(b, h) + boff + n * 2048 + k * 1024); } while (0)
; #define PG8_MMA(ai, bj, At, Bt) do { __builtin_amdgcn_s_setprio(1); _Pragma("unroll") for (int m = 0; m < 4; ++m) _Pragma("unroll") for (int n = 0; n < 2; ++n) _Pragma("unroll") for (int k = 0; k < 2; ++k) \
;         acc[ai][bj][m][n] = __builtin_amdgcn_mfma_f32_16x16x32_bf16(Bt[n][k], At[m][k], acc[ai][bj][m][n], 0, 0, 0); __builtin_amdgcn_s_setprio(0); } while (0)
; #define PG8_WAIT_V(n) asm volatile("s_waitcnt vmcnt(" #n ")" ::: "memory")
; #define PG8_WAIT_L(n) asm volatile("s_waitcnt lgkmcnt(" #n ")" ::: "memory")
; #define PG8_BAR __builtin_amdgcn_s_barrier()
; #define PG8_SCHED __builtin_amdgcn_sched_barrier(0)
; template <class Epi, class Sched, bool ALIGN_EPI = false, bool SP2 = false>
; __device__ __forceinline__ void gemm_phase(PG8_LAS unsigned char* lds, const Gemm g, const Sched& S, const Epi& E) {
;     ...
;             PG8_LDB(B0, 1, 0); PG8_LDB(B1, 1, 1); PG8_SCHED; PG8_LDA(At, 1, 0); PG8_STAGE(PG8_SA(0, 1), a2 + hstep, voffA);
;             PG8_WAIT_V(8); PG8_WAIT_L(0); PG8_BAR; PG8_MMA(0, 0, At, B0); PG8_MMA(0, 1, At, B1); PG8_BAR; PG8_SCHED;
	s_setprio 0
	s_add_i32 s59, 0, 0x18000
	s_add_i32 s60, 0, 0x1c000
	v_add_u32_e32 v96, s59, v167
	v_add_u32_e32 v173, s60, v167
	ds_read_b128 v[72:75], v96
	ds_read_b128 v[84:87], v96 offset:1024
	ds_read_b128 v[92:95], v96 offset:2048
	ds_read_b128 v[96:99], v96 offset:3072
	ds_read_b128 v[156:159], v173
	ds_read_b128 v[160:163], v173 offset:1024
	ds_read_b128 v[174:177], v173 offset:2048
	ds_read_b128 v[178:181], v173 offset:3072
	s_add_u32 s42, s42, 0x80000
	s_addc_u32 s43, s43, 0
	s_mov_b32 m0, s45
	v_lshl_add_u64 v[222:223], s[42:43], 0, v[144:145]
	ds_read_b128 v[182:185], v171 offset:32768
	ds_read_b128 v[188:191], v171 offset:33792
	ds_read_b128 v[192:195], v171 offset:34816
	ds_read_b128 v[196:199], v171 offset:35840
	ds_read_b128 v[200:203], v171 offset:36864
	ds_read_b128 v[204:207], v171 offset:37888
	ds_read_b128 v[208:211], v171 offset:38912
	ds_read_b128 v[212:215], v171 offset:39936
	global_load_lds_dwordx4 v[222:223], off
	v_lshl_add_u64 v[222:223], s[42:43], 0, v[146:147]
	s_mov_b32 m0, s46
	s_nop 0
	global_load_lds_dwordx4 v[222:223], off
	s_setprio 1
	s_waitcnt vmcnt(8)
	s_waitcnt lgkmcnt(0)
	s_barrier
	v_mfma_f32_16x16x32_bf16 v[140:143], v[72:75], v[182:185], v[140:143]
	v_mfma_f32_16x16x32_bf16 v[136:139], v[92:95], v[182:185], v[136:139]
	v_mfma_f32_16x16x32_bf16 v[124:127], v[72:75], v[192:195], v[124:127]
	v_mfma_f32_16x16x32_bf16 v[120:123], v[92:95], v[192:195], v[120:123]
	v_mfma_f32_16x16x32_bf16 v[108:111], v[72:75], v[200:203], v[108:111]
	v_mfma_f32_16x16x32_bf16 v[104:107], v[92:95], v[200:203], v[104:107]
	v_mfma_f32_16x16x32_bf16 v[80:83], v[72:75], v[208:211], v[80:83]
	v_mfma_f32_16x16x32_bf16 v[76:79], v[92:95], v[208:211], v[76:79]
	v_mfma_f32_16x16x32_bf16 v[140:143], v[84:87], v[188:191], v[140:143]
	v_mfma_f32_16x16x32_bf16 v[136:139], v[96:99], v[188:191], v[136:139]
	v_mfma_f32_16x16x32_bf16 v[124:127], v[84:87], v[196:199], v[124:127]
	v_mfma_f32_16x16x32_bf16 v[120:123], v[96:99], v[196:199], v[120:123]
	v_mfma_f32_16x16x32_bf16 v[108:111], v[84:87], v[204:207], v[108:111]
	v_mfma_f32_16x16x32_bf16 v[104:107], v[96:99], v[204:207], v[104:107]
	v_mfma_f32_16x16x32_bf16 v[80:83], v[84:87], v[212:215], v[80:83]
	v_mfma_f32_16x16x32_bf16 v[76:79], v[96:99], v[212:215], v[76:79]
	s_setprio 0
	s_setprio 1
	v_mfma_f32_16x16x32_bf16 v[132:135], v[156:159], v[182:185], v[132:135]
	v_mfma_f32_16x16x32_bf16 v[128:131], v[174:177], v[182:185], v[128:131]
	v_mfma_f32_16x16x32_bf16 v[116:119], v[156:159], v[192:195], v[116:119]
	v_mfma_f32_16x16x32_bf16 v[112:115], v[174:177], v[192:195], v[112:115]
	v_mfma_f32_16x16x32_bf16 v[100:103], v[156:159], v[200:203], v[100:103]
	v_mfma_f32_16x16x32_bf16 v[88:91], v[174:177], v[200:203], v[88:91]
	v_mfma_f32_16x16x32_bf16 v[68:71], v[156:159], v[208:211], v[68:71]
	v_mfma_f32_16x16x32_bf16 v[64:67], v[174:177], v[208:211], v[64:67]
	v_mfma_f32_16x16x32_bf16 v[132:135], v[160:163], v[188:191], v[132:135]
	v_mfma_f32_16x16x32_bf16 v[128:131], v[178:181], v[188:191], v[128:131]
	v_mfma_f32_16x16x32_bf16 v[116:119], v[160:163], v[196:199], v[116:119]
	v_mfma_f32_16x16x32_bf16 v[112:115], v[178:181], v[196:199], v[112:115]
	v_mfma_f32_16x16x32_bf16 v[100:103], v[160:163], v[204:207], v[100:103]
	v_mfma_f32_16x16x32_bf16 v[88:91], v[178:181], v[204:207], v[88:91]
	v_mfma_f32_16x16x32_bf16 v[68:71], v[160:163], v[212:215], v[68:71]
	v_mfma_f32_16x16x32_bf16 v[64:67], v[178:181], v[212:215], v[64:67]
	s_barrier
; #define PG8_STAGE(bufoff, gbase, voff) do { _Pragma("unroll") for (int _i = 0; _i < 2; ++_i) \
;         __builtin_amdgcn_global_load_lds((const unsigned*)((const char*)(gbase) + (voff)[_i]), (PG8_LAS unsigned*)(lds + (bufoff) + ldsw + _i * 8192), 16, 0, 0); } while (0)
; #define PG8_LDA(dst, b, h) do { _Pragma("unroll") for (int m = 0; m < 4; ++m) _Pragma("unroll") for (int k = 0; k < 2; ++k) dst[m][k] = *(const PG8_LAS bf16x8*)(lds + PG8_SA(b, h) + aoff + m * 2048 + k * 1024); } while (0)
; #define PG8_MMA(ai, bj, At, Bt) do { __builtin_amdgcn_s_setprio(1); _Pragma("unroll") for (int m = 0; m < 4; ++m) _Pragma("unroll") for (int n = 0; n < 2; ++n) _Pragma("unroll") for (int k = 0; k < 2; ++k) \
;         acc[ai][bj][m][n] = __builtin_amdgcn_mfma_f32_16x16x32_bf16(Bt[n][k], At[m][k], acc[ai][bj][m][n], 0, 0, 0); __builtin_amdgcn_s_setprio(0); } while (0)
; #define PG8_WAIT_V(n) asm volatile("s_waitcnt vmcnt(" #n ")" ::: "memory")
; #define PG8_WAIT_L(n) asm volatile("s_waitcnt lgkmcnt(" #n ")" ::: "memory")
; #define PG8_BAR __builtin_amdgcn_s_barrier()
; #define PG8_SCHED __builtin_amdgcn_sched_barrier(0)
; template <class Epi, class Sched, bool ALIGN_EPI = false, bool SP2 = false>
; __device__ __forceinline__ void gemm_phase(PG8_LAS unsigned char* lds, const Gemm g, const Sched& S, const Epi& E) {
;     ...
;             PG8_LDA(At, 1, 1); PG8_STAGE(PG8_SB(1, 0), b3, voffB); PG8_STAGE(PG8_SB(1, 1), b3 + hstep, voffB); PG8_STAGE(PG8_SA(1, 0), a3, voffA);
;             PG8_WAIT_V(8); PG8_WAIT_L(0); PG8_BAR; PG8_MMA(1, 0, At, B0); PG8_MMA(1, 1, At, B1); PG8_BAR; PG8_SCHED;
;     ...
;         if constexpr (ALIGN_EPI) { if (wr == 0) PG8_BAR; }
	s_setprio 0
	s_add_i32 s42, s59, s33
	v_lshl_add_u64 v[164:165], v[164:165], 0, s[12:13]
	s_mov_b32 m0, s42
	ds_read_b128 v[182:185], v171 offset:49152
	ds_read_b128 v[188:191], v171 offset:50176
	ds_read_b128 v[192:195], v171 offset:51200
	ds_read_b128 v[196:199], v171 offset:52224
	ds_read_b128 v[200:203], v171 offset:53248
	ds_read_b128 v[204:207], v171 offset:54272
	ds_read_b128 v[208:211], v171 offset:55296
	ds_read_b128 v[212:215], v171 offset:56320
	global_load_lds_dwordx4 v[164:165], off
	s_add_i32 m0, s42, 0x2000
	s_add_u32 s40, s40, 0x80080
	v_lshl_add_u64 v[164:165], v[216:217], 0, s[12:13]
	s_addc_u32 s41, s41, 0
	s_add_i32 s42, s60, s33
	global_load_lds_dwordx4 v[164:165], off
	v_lshl_add_u64 v[164:165], s[40:41], 0, v[144:145]
	s_mov_b32 m0, s42
	s_nop 0
	global_load_lds_dwordx4 v[164:165], off
	v_lshl_add_u64 v[164:165], s[40:41], 0, v[146:147]
	s_add_i32 m0, s42, 0x2000
	s_nop 0
	global_load_lds_dwordx4 v[164:165], off
	v_lshl_add_u64 v[164:165], v[218:219], 0, s[12:13]
	s_mov_b32 m0, s50
	s_nop 0
	global_load_lds_dwordx4 v[164:165], off
	v_lshl_add_u64 v[164:165], v[220:221], 0, s[12:13]
	s_mov_b32 m0, s51
	s_nop 0
	global_load_lds_dwordx4 v[164:165], off
	s_setprio 1
	s_waitcnt vmcnt(8)
	s_waitcnt lgkmcnt(0)
	s_barrier
	v_mfma_f32_16x16x32_bf16 v[60:63], v[72:75], v[182:185], v[60:63]
	v_mfma_f32_16x16x32_bf16 v[56:59], v[92:95], v[182:185], v[56:59]
	v_mfma_f32_16x16x32_bf16 v[44:47], v[72:75], v[192:195], v[44:47]
	v_mfma_f32_16x16x32_bf16 v[40:43], v[92:95], v[192:195], v[40:43]
	v_mfma_f32_16x16x32_bf16 v[28:31], v[72:75], v[200:203], v[28:31]
	v_mfma_f32_16x16x32_bf16 v[24:27], v[92:95], v[200:203], v[24:27]
	v_mfma_f32_16x16x32_bf16 v[12:15], v[72:75], v[208:211], v[12:15]
	v_mfma_f32_16x16x32_bf16 v[8:11], v[92:95], v[208:211], v[8:11]
	v_mfma_f32_16x16x32_bf16 v[60:63], v[84:87], v[188:191], v[60:63]
	v_mfma_f32_16x16x32_bf16 v[56:59], v[96:99], v[188:191], v[56:59]
	v_mfma_f32_16x16x32_bf16 v[44:47], v[84:87], v[196:199], v[44:47]
	v_mfma_f32_16x16x32_bf16 v[40:43], v[96:99], v[196:199], v[40:43]
	v_mfma_f32_16x16x32_bf16 v[28:31], v[84:87], v[204:207], v[28:31]
	v_mfma_f32_16x16x32_bf16 v[24:27], v[96:99], v[204:207], v[24:27]
	v_mfma_f32_16x16x32_bf16 v[12:15], v[84:87], v[212:215], v[12:15]
	v_mfma_f32_16x16x32_bf16 v[8:11], v[96:99], v[212:215], v[8:11]
	s_setprio 0
	s_setprio 1
	v_mfma_f32_16x16x32_bf16 v[52:55], v[156:159], v[182:185], v[52:55]
	v_mfma_f32_16x16x32_bf16 v[48:51], v[174:177], v[182:185], v[48:51]
	v_mfma_f32_16x16x32_bf16 v[36:39], v[156:159], v[192:195], v[36:39]
	v_mfma_f32_16x16x32_bf16 v[32:35], v[174:177], v[192:195], v[32:35]
	v_mfma_f32_16x16x32_bf16 v[20:23], v[156:159], v[200:203], v[20:23]
	v_mfma_f32_16x16x32_bf16 v[16:19], v[174:177], v[200:203], v[16:19]
	v_mfma_f32_16x16x32_bf16 v[4:7], v[156:159], v[208:211], v[4:7]
	v_mfma_f32_16x16x32_bf16 v[0:3], v[174:177], v[208:211], v[0:3]
	v_mfma_f32_16x16x32_bf16 v[52:55], v[160:163], v[188:191], v[52:55]
	v_mfma_f32_16x16x32_bf16 v[48:51], v[178:181], v[188:191], v[48:51]
	v_mfma_f32_16x16x32_bf16 v[36:39], v[160:163], v[196:199], v[36:39]
	v_mfma_f32_16x16x32_bf16 v[32:35], v[178:181], v[196:199], v[32:35]
	v_mfma_f32_16x16x32_bf16 v[20:23], v[160:163], v[204:207], v[20:23]
	v_mfma_f32_16x16x32_bf16 v[16:19], v[178:181], v[204:207], v[16:19]
	v_mfma_f32_16x16x32_bf16 v[4:7], v[160:163], v[212:215], v[4:7]
	v_mfma_f32_16x16x32_bf16 v[0:3], v[178:181], v[212:215], v[0:3]
	s_barrier
	s_setprio 0
	s_add_i32 s58, s58, 2
	s_add_u32 s38, s38, 0x100
	s_addc_u32 s39, s39, 0
	s_add_u32 s56, s56, 0x100
	s_addc_u32 s57, s57, 0
	s_cmp_gt_u32 s58, 29
	s_cbranch_scc0 .LBB0_894
	s_and_b64 vcc, exec, s[14:15]
	s_cbranch_vccz .LBB0_897
	s_barrier

;     __device__ __forceinline__ bool next(int i, Unit& u) const { if (!base.next(i >> 1, u)) return false; if (i & 1) { u.pm += 64; u.pn += 8; } return true; }
; #define PG8_STAGE(bufoff, gbase, voff) do { _Pragma("unroll") for (int _i = 0; _i < 2; ++_i) \
;         __builtin_amdgcn_global_load_lds((const unsigned*)((const char*)(gbase) + (voff)[_i]), (PG8_LAS unsigned*)(lds + (bufoff) + ldsw + _i * 8192), 16, 0, 0); } while (0)
; #define PG8_LDA(dst, b, h) do { _Pragma("unroll") for (int m = 0; m < 4; ++m) _Pragma("unroll") for (int k = 0; k < 2; ++k) dst[m][k] = *(const PG8_LAS bf16x8*)(lds + PG8_SA(b, h) + aoff + m * 2048 + k * 1024); } while (0)
; #define PG8_LDB(dst, b, h) do { _Pragma("unroll") for (int n = 0; n < 2; ++n) _Pragma("unroll") for (int k = 0; k < 2; ++k) dst[n][k] = *(const PG8_LAS bf16x8*)(lds + PG8_SB(b, h) + boff + n * 2048 + k * 1024); } while (0)
; #define PG8_WAIT_V(n) asm volatile("s_waitcnt vmcnt(" #n ")" ::: "memory")
; #define PG8_BAR __builtin_amdgcn_s_barrier()
; template <class Epi, class Sched, bool ALIGN_EPI = false, bool SP2 = false>
; __device__ __forceinline__ void gemm_phase(PG8_LAS unsigned char* lds, const Gemm g, const Sched& S, const Epi& E) {
;     ...
;         const bool has_next = S.next(ui + 1, nxt);
;         const char* nA = has_next ? (const char*)g.A + (size_t)nxt.pm * tstep : cA; const char* nB = has_next ? (const char*)g.Bt + (size_t)nxt.pn * tstep : cB;
;         for (int t = 0; t < nt; t += 2) {
;             const bool last = (t == nt - 2);
;             const char* a1 = cA + (size_t)(t + 1) * kstep;
;             const char* a2 = last ? nA : cA + (size_t)(t + 2) * kstep; const char* b2 = last ? nB : cB + (size_t)(t + 2) * kstep;
;             const char* a3 = a2 + kstep; const char* b3 = b2 + kstep;
;             if (last && has_next) S.a_ready(nxt);
;             if constexpr (SP2) {
;             PG8_LDB(B0, 0, 0); PG8_LDB(B1, 0, 1); PG8_SCHED; PG8_LDA(At, 0, 0); PG8_STAGE(PG8_SA(1, 1), a1 + hstep, voffA);
;             PG8_WAIT_V(8); PG8_WAIT_L(0); PG8_BAR; PG8_MMA(0, 0, At, B0); PG8_MMA(0, 1, At, B1); PG8_BAR; PG8_SCHED;
;             PG8_LDA(At, 0, 1); PG8_STAGE(PG8_SB(0, 0), b2, voffB); PG8_STAGE(PG8_SB(0, 1), b2 + hstep, voffB); PG8_STAGE(PG8_SA(0, 0), a2, voffA);
;             PG8_WAIT_V(8); PG8_WAIT_L(0); PG8_BAR; PG8_MMA(1, 0, At, B0); PG8_MMA(1, 1, At, B1); PG8_BAR; PG8_SCHED;
.LBB0_993:
	s_ashr_i32 s15, s14, 31
	s_lshl_b64 s[18:19], s[14:15], 20
	s_add_u32 s18, s8, s18
	s_addc_u32 s19, s9, s19
	s_and_b64 s[20:21], s[4:5], exec
	s_cselect_b32 s15, s19, s25
	s_cselect_b32 s43, s18, s24
	s_ashr_i32 s17, s16, 31
	s_lshl_b64 s[20:21], s[16:17], 20
	v_readlane_b32 s28, v236, 52
	v_readlane_b32 s29, v236, 53
	s_add_u32 s20, s28, s20
	s_addc_u32 s21, s29, s21
	s_and_b64 s[28:29], s[4:5], exec
	s_cselect_b32 s17, s21, s27
	s_cselect_b32 s44, s20, s26
	s_add_u32 s24, s24, 0x80080
	s_addc_u32 s25, s25, 0
	s_add_u32 s45, s26, 0x100
	s_addc_u32 s46, s27, 0
	s_mov_b32 s47, -2
	ds_read_b128 v[128:131], v173
	ds_read_b128 v[132:135], v173 offset:1024
	ds_read_b128 v[136:139], v173 offset:2048
	ds_read_b128 v[140:143], v173 offset:3072
	ds_read_b128 v[176:179], v174
	ds_read_b128 v[180:183], v174 offset:1024
	ds_read_b128 v[188:191], v174 offset:2048
	ds_read_b128 v[192:195], v174 offset:3072
	s_add_u32 s26, s24, 0xfff80080
	s_addc_u32 s27, s25, -1
	s_cmp_eq_u32 s47, 28
	s_cselect_b32 s29, s15, s27
	s_cselect_b32 s28, s43, s26
	s_cselect_b32 s27, s17, s46
	s_cselect_b32 s26, s44, s45
	v_lshl_add_u64 v[160:161], s[24:25], 0, v[152:153]
	s_add_i32 m0, s23, 0xc000
	ds_read_b128 v[196:199], v175
	ds_read_b128 v[200:203], v175 offset:1024
	ds_read_b128 v[204:207], v175 offset:2048
	ds_read_b128 v[208:211], v175 offset:3072
	ds_read_b128 v[212:215], v175 offset:4096
	ds_read_b128 v[216:219], v175 offset:5120
	ds_read_b128 v[220:223], v175 offset:6144
	ds_read_b128 v[224:227], v175 offset:7168
	global_load_lds_dwordx4 v[160:161], off
	v_lshl_add_u64 v[160:161], s[24:25], 0, v[154:155]
	s_add_i32 m0, s23, 0xe000
	s_nop 0
	global_load_lds_dwordx4 v[160:161], off
	s_setprio 1
	s_waitcnt vmcnt(8)
	s_waitcnt lgkmcnt(0)
	s_barrier
	v_mfma_f32_16x16x32_bf16 v[124:127], v[128:131], v[196:199], 0
	v_mfma_f32_16x16x32_bf16 v[120:123], v[136:139], v[196:199], 0
	v_mfma_f32_16x16x32_bf16 v[108:111], v[128:131], v[204:207], 0
	v_mfma_f32_16x16x32_bf16 v[104:107], v[136:139], v[204:207], 0
	v_mfma_f32_16x16x32_bf16 v[92:95], v[128:131], v[212:215], 0
	v_mfma_f32_16x16x32_bf16 v[88:91], v[136:139], v[212:215], 0
	v_mfma_f32_16x16x32_bf16 v[76:79], v[128:131], v[220:223], 0
	v_mfma_f32_16x16x32_bf16 v[72:75], v[136:139], v[220:223], 0
	v_mfma_f32_16x16x32_bf16 v[124:127], v[132:135], v[200:203], v[124:127]
	v_mfma_f32_16x16x32_bf16 v[120:123], v[140:143], v[200:203], v[120:123]
	v_mfma_f32_16x16x32_bf16 v[108:111], v[132:135], v[208:211], v[108:111]
	v_mfma_f32_16x16x32_bf16 v[104:107], v[140:143], v[208:211], v[104:107]
	v_mfma_f32_16x16x32_bf16 v[92:95], v[132:135], v[216:219], v[92:95]
	v_mfma_f32_16x16x32_bf16 v[88:91], v[140:143], v[216:219], v[88:91]
	v_mfma_f32_16x16x32_bf16 v[76:79], v[132:135], v[224:227], v[76:79]
	v_mfma_f32_16x16x32_bf16 v[72:75], v[140:143], v[224:227], v[72:75]
	s_setprio 0
	s_setprio 1
	v_mfma_f32_16x16x32_bf16 v[116:119], v[176:179], v[196:199], 0
	v_mfma_f32_16x16x32_bf16 v[112:115], v[188:191], v[196:199], 0
	v_mfma_f32_16x16x32_bf16 v[100:103], v[176:179], v[204:207], 0
	v_mfma_f32_16x16x32_bf16 v[96:99], v[188:191], v[204:207], 0
	v_mfma_f32_16x16x32_bf16 v[84:87], v[176:179], v[212:215], 0
	v_mfma_f32_16x16x32_bf16 v[80:83], v[188:191], v[212:215], 0
	v_mfma_f32_16x16x32_bf16 v[68:71], v[176:179], v[220:223], 0
	v_mfma_f32_16x16x32_bf16 v[64:67], v[188:191], v[220:223], 0
	v_mfma_f32_16x16x32_bf16 v[116:119], v[180:183], v[200:203], v[116:119]
	v_mfma_f32_16x16x32_bf16 v[112:115], v[192:195], v[200:203], v[112:115]
	v_mfma_f32_16x16x32_bf16 v[100:103], v[180:183], v[208:211], v[100:103]
	v_mfma_f32_16x16x32_bf16 v[96:99], v[192:195], v[208:211], v[96:99]
	v_mfma_f32_16x16x32_bf16 v[84:87], v[180:183], v[216:219], v[84:87]
	v_mfma_f32_16x16x32_bf16 v[80:83], v[192:195], v[216:219], v[80:83]
	v_mfma_f32_16x16x32_bf16 v[68:71], v[180:183], v[224:227], v[68:71]
	v_mfma_f32_16x16x32_bf16 v[64:67], v[192:195], v[224:227], v[64:67]
	s_barrier
	s_setprio 0
	s_add_i32 s48, s40, s31
	v_lshl_add_u64 v[160:161], s[26:27], 0, v[146:147]
	s_mov_b32 m0, s48
	ds_read_b128 v[196:199], v175 offset:16384
	ds_read_b128 v[200:203], v175 offset:17408
	ds_read_b128 v[204:207], v175 offset:18432
	ds_read_b128 v[208:211], v175 offset:19456
	ds_read_b128 v[212:215], v175 offset:20480
	ds_read_b128 v[216:219], v175 offset:21504
	ds_read_b128 v[220:223], v175 offset:22528
	ds_read_b128 v[224:227], v175 offset:23552
	global_load_lds_dwordx4 v[160:161], off
	s_add_i32 m0, s48, 0x2000
	s_add_u32 s48, s26, 0x80000
	v_lshl_add_u64 v[184:185], s[26:27], 0, v[150:151]
	s_addc_u32 s49, s27, 0
	s_add_i32 s50, s41, s31
	global_load_lds_dwordx4 v[184:185], off
	v_lshl_add_u64 v[228:229], s[48:49], 0, v[146:147]
	s_mov_b32 m0, s50
	v_lshl_add_u64 v[230:231], s[28:29], 0, v[148:149]
	global_load_lds_dwordx4 v[228:229], off
	v_lshl_add_u64 v[228:229], s[48:49], 0, v[150:151]
	s_add_i32 m0, s50, 0x2000
	s_nop 0
	global_load_lds_dwordx4 v[228:229], off
	v_lshl_add_u64 v[228:229], s[28:29], 0, v[144:145]
	s_mov_b32 m0, s23
	s_nop 0
	global_load_lds_dwordx4 v[228:229], off
	s_mov_b32 m0, s33
	s_nop 0
	global_load_lds_dwordx4 v[230:231], off
	s_setprio 1
	s_waitcnt vmcnt(8)
	s_waitcnt lgkmcnt(0)
	s_barrier
; #define PG8_STAGE(bufoff, gbase, voff) do { _Pragma("unroll") for (int _i = 0; _i < 2; ++_i) \
;         __builtin_amdgcn_global_load_lds((const unsigned*)((const char*)(gbase) + (voff)[_i]), (PG8_LAS unsigned*)(lds + (bufoff) + ldsw + _i * 8192), 16, 0, 0); } while (0)
; #define PG8_LDA(dst, b, h) do { _Pragma("unroll") for (int m = 0; m < 4; ++m) _Pragma("unroll") for (int k = 0; k < 2; ++k) dst[m][k] = *(const PG8_LAS bf16x8*)(lds + PG8_SA(b, h) + aoff + m * 2048 + k * 1024); } while (0)
; #define PG8_LDB(dst, b, h) do { _Pragma("unroll") for (int n = 0; n < 2; ++n) _Pragma("unroll") for (int k = 0; k < 2; ++k) dst[n][k] = *(const PG8_LAS bf16x8*)(lds + PG8_SB(b, h) + boff + n * 2048 + k * 1024); } while (0)
; #define PG8_MMA(ai, bj, At, Bt) do { __builtin_amdgcn_s_setprio(1); _Pragma("unroll") for (int m = 0; m < 4; ++m) _Pragma("unroll") for (int n = 0; n < 2; ++n) _Pragma("unroll") for (int k = 0; k < 2; ++k) \
;         acc[ai][bj][m][n] = __builtin_amdgcn_mfma_f32_16x16x32_bf16(Bt[n][k], At[m][k], acc[ai][bj][m][n], 0, 0, 0); __builtin_amdgcn_s_setprio(0); } while (0)
; #define PG8_WAIT_V(n) asm volatile("s_waitcnt vmcnt(" #n ")" ::: "memory")
; #define PG8_WAIT_L(n) asm volatile("s_waitcnt lgkmcnt(" #n ")" ::: "memory")
; #define PG8_BAR __builtin_amdgcn_s_barrier()
; #define PG8_SCHED __builtin_amdgcn_sched_barrier(0)
; template <class Epi, class Sched, bool ALIGN_EPI = false, bool SP2 = false>
; __device__ __forceinline__ void gemm_phase(PG8_LAS unsigned char* lds, const Gemm g, const Sched& S, const Epi& E) {
;     ...
;             PG8_WAIT_V(8); PG8_WAIT_L(0); PG8_BAR; PG8_MMA(1, 0, At, B0); PG8_MMA(1, 1, At, B1); PG8_BAR; PG8_SCHED;
;             PG8_LDB(B0, 1, 0); PG8_LDB(B1, 1, 1); PG8_SCHED; PG8_LDA(At, 1, 0); PG8_STAGE(PG8_SA(0, 1), a2 + hstep, voffA);
;             PG8_WAIT_V(8); PG8_WAIT_L(0); PG8_BAR; PG8_MMA(0, 0, At, B0); PG8_MMA(0, 1, At, B1); PG8_BAR; PG8_SCHED;
	v_mfma_f32_16x16x32_bf16 v[60:63], v[128:131], v[196:199], 0
	v_mfma_f32_16x16x32_bf16 v[56:59], v[136:139], v[196:199], 0
	v_mfma_f32_16x16x32_bf16 v[44:47], v[128:131], v[204:207], 0
	v_mfma_f32_16x16x32_bf16 v[40:43], v[136:139], v[204:207], 0
	v_mfma_f32_16x16x32_bf16 v[28:31], v[128:131], v[212:215], 0
	v_mfma_f32_16x16x32_bf16 v[24:27], v[136:139], v[212:215], 0
	v_mfma_f32_16x16x32_bf16 v[12:15], v[128:131], v[220:223], 0
	v_mfma_f32_16x16x32_bf16 v[8:11], v[136:139], v[220:223], 0
	v_mfma_f32_16x16x32_bf16 v[60:63], v[132:135], v[200:203], v[60:63]
	v_mfma_f32_16x16x32_bf16 v[56:59], v[140:143], v[200:203], v[56:59]
	v_mfma_f32_16x16x32_bf16 v[44:47], v[132:135], v[208:211], v[44:47]
	v_mfma_f32_16x16x32_bf16 v[40:43], v[140:143], v[208:211], v[40:43]
	v_mfma_f32_16x16x32_bf16 v[28:31], v[132:135], v[216:219], v[28:31]
	v_mfma_f32_16x16x32_bf16 v[24:27], v[140:143], v[216:219], v[24:27]
	v_mfma_f32_16x16x32_bf16 v[12:15], v[132:135], v[224:227], v[12:15]
	v_mfma_f32_16x16x32_bf16 v[8:11], v[140:143], v[224:227], v[8:11]
	s_setprio 0
	s_setprio 1
	v_mfma_f32_16x16x32_bf16 v[52:55], v[176:179], v[196:199], 0
	v_mfma_f32_16x16x32_bf16 v[48:51], v[188:191], v[196:199], 0
	v_mfma_f32_16x16x32_bf16 v[36:39], v[176:179], v[204:207], 0
	v_mfma_f32_16x16x32_bf16 v[32:35], v[188:191], v[204:207], 0
	v_mfma_f32_16x16x32_bf16 v[20:23], v[176:179], v[212:215], 0
	v_mfma_f32_16x16x32_bf16 v[16:19], v[188:191], v[212:215], 0
	v_mfma_f32_16x16x32_bf16 v[4:7], v[176:179], v[220:223], 0
	v_mfma_f32_16x16x32_bf16 v[0:3], v[188:191], v[220:223], 0
	v_mfma_f32_16x16x32_bf16 v[52:55], v[180:183], v[200:203], v[52:55]
	v_mfma_f32_16x16x32_bf16 v[48:51], v[192:195], v[200:203], v[48:51]
	v_mfma_f32_16x16x32_bf16 v[36:39], v[180:183], v[208:211], v[36:39]
	v_mfma_f32_16x16x32_bf16 v[32:35], v[192:195], v[208:211], v[32:35]
	v_mfma_f32_16x16x32_bf16 v[20:23], v[180:183], v[216:219], v[20:23]
	v_mfma_f32_16x16x32_bf16 v[16:19], v[192:195], v[216:219], v[16:19]
	v_mfma_f32_16x16x32_bf16 v[4:7], v[180:183], v[224:227], v[4:7]
	v_mfma_f32_16x16x32_bf16 v[0:3], v[192:195], v[224:227], v[0:3]
	s_barrier
	s_setprio 0
	s_add_i32 s48, 0, 0x18000
	s_add_i32 s49, 0, 0x1c000
	v_add_u32_e32 v140, s48, v163
	v_add_u32_e32 v187, s49, v163
	ds_read_b128 v[128:131], v140
	ds_read_b128 v[132:135], v140 offset:1024
	ds_read_b128 v[136:139], v140 offset:2048
	ds_read_b128 v[140:143], v140 offset:3072
	ds_read_b128 v[176:179], v187
	ds_read_b128 v[180:183], v187 offset:1024
	ds_read_b128 v[188:191], v187 offset:2048
	ds_read_b128 v[192:195], v187 offset:3072
	s_add_u32 s28, s28, 0x80000
	s_addc_u32 s29, s29, 0
	s_mov_b32 m0, s34
	v_lshl_add_u64 v[232:233], s[28:29], 0, v[144:145]
	ds_read_b128 v[196:199], v175 offset:32768
	ds_read_b128 v[200:203], v175 offset:33792
	ds_read_b128 v[204:207], v175 offset:34816
	ds_read_b128 v[208:211], v175 offset:35840
	ds_read_b128 v[212:215], v175 offset:36864
	ds_read_b128 v[216:219], v175 offset:37888
	ds_read_b128 v[220:223], v175 offset:38912
	ds_read_b128 v[224:227], v175 offset:39936
	global_load_lds_dwordx4 v[232:233], off
	v_lshl_add_u64 v[232:233], s[28:29], 0, v[148:149]
	s_mov_b32 m0, s35
	s_nop 0
	global_load_lds_dwordx4 v[232:233], off
	s_setprio 1
	s_waitcnt vmcnt(8)
	s_waitcnt lgkmcnt(0)
	s_barrier
	v_mfma_f32_16x16x32_bf16 v[124:127], v[128:131], v[196:199], v[124:127]
	v_mfma_f32_16x16x32_bf16 v[120:123], v[136:139], v[196:199], v[120:123]
	v_mfma_f32_16x16x32_bf16 v[108:111], v[128:131], v[204:207], v[108:111]
	v_mfma_f32_16x16x32_bf16 v[104:107], v[136:139], v[204:207], v[104:107]
	v_mfma_f32_16x16x32_bf16 v[92:95], v[128:131], v[212:215], v[92:95]
	v_mfma_f32_16x16x32_bf16 v[88:91], v[136:139], v[212:215], v[88:91]
	v_mfma_f32_16x16x32_bf16 v[76:79], v[128:131], v[220:223], v[76:79]
	v_mfma_f32_16x16x32_bf16 v[72:75], v[136:139], v[220:223], v[72:75]
	v_mfma_f32_16x16x32_bf16 v[124:127], v[132:135], v[200:203], v[124:127]
	v_mfma_f32_16x16x32_bf16 v[120:123], v[140:143], v[200:203], v[120:123]
	v_mfma_f32_16x16x32_bf16 v[108:111], v[132:135], v[208:211], v[108:111]
	v_mfma_f32_16x16x32_bf16 v[104:107], v[140:143], v[208:211], v[104:107]
	v_mfma_f32_16x16x32_bf16 v[92:95], v[132:135], v[216:219], v[92:95]
	v_mfma_f32_16x16x32_bf16 v[88:91], v[140:143], v[216:219], v[88:91]
	v_mfma_f32_16x16x32_bf16 v[76:79], v[132:135], v[224:227], v[76:79]
	v_mfma_f32_16x16x32_bf16 v[72:75], v[140:143], v[224:227], v[72:75]
	s_setprio 0
	s_setprio 1
	v_mfma_f32_16x16x32_bf16 v[116:119], v[176:179], v[196:199], v[116:119]
	v_mfma_f32_16x16x32_bf16 v[112:115], v[188:191], v[196:199], v[112:115]
	v_mfma_f32_16x16x32_bf16 v[100:103], v[176:179], v[204:207], v[100:103]
	v_mfma_f32_16x16x32_bf16 v[96:99], v[188:191], v[204:207], v[96:99]
	v_mfma_f32_16x16x32_bf16 v[84:87], v[176:179], v[212:215], v[84:87]
	v_mfma_f32_16x16x32_bf16 v[80:83], v[188:191], v[212:215], v[80:83]
	v_mfma_f32_16x16x32_bf16 v[68:71], v[176:179], v[220:223], v[68:71]
	v_mfma_f32_16x16x32_bf16 v[64:67], v[188:191], v[220:223], v[64:67]
	v_mfma_f32_16x16x32_bf16 v[116:119], v[180:183], v[200:203], v[116:119]
	v_mfma_f32_16x16x32_bf16 v[112:115], v[192:195], v[200:203], v[112:115]
	v_mfma_f32_16x16x32_bf16 v[100:103], v[180:183], v[208:211], v[100:103]
	v_mfma_f32_16x16x32_bf16 v[96:99], v[192:195], v[208:211], v[96:99]
	v_mfma_f32_16x16x32_bf16 v[84:87], v[180:183], v[216:219], v[84:87]
	v_mfma_f32_16x16x32_bf16 v[80:83], v[192:195], v[216:219], v[80:83]
	v_mfma_f32_16x16x32_bf16 v[68:71], v[180:183], v[224:227], v[68:71]
	v_mfma_f32_16x16x32_bf16 v[64:67], v[192:195], v[224:227], v[64:67]
	s_barrier
; #define PG8_STAGE(bufoff, gbase, voff) do { _Pragma("unroll") for (int _i = 0; _i < 2; ++_i) \
;         __builtin_amdgcn_global_load_lds((const unsigned*)((const char*)(gbase) + (voff)[_i]), (PG8_LAS unsigned*)(lds + (bufoff) + ldsw + _i * 8192), 16, 0, 0); } while (0)
; #define PG8_LDA(dst, b, h) do { _Pragma("unroll") for (int m = 0; m < 4; ++m) _Pragma("unroll") for (int k = 0; k < 2; ++k) dst[m][k] = *(const PG8_LAS bf16x8*)(lds + PG8_SA(b, h) + aoff + m * 2048 + k * 1024); } while (0)
; #define PG8_LDB(dst, b, h) do { _Pragma("unroll") for (int n = 0; n < 2; ++n) _Pragma("unroll") for (int k = 0; k < 2; ++k) dst[n][k] = *(const PG8_LAS bf16x8*)(lds + PG8_SB(b, h) + boff + n * 2048 + k * 1024); } while (0)
; #define PG8_MMA(ai, bj, At, Bt) do { __builtin_amdgcn_s_setprio(1); _Pragma("unroll") for (int m = 0; m < 4; ++m) _Pragma("unroll") for (int n = 0; n < 2; ++n) _Pragma("unroll") for (int k = 0; k < 2; ++k) \
;         acc[ai][bj][m][n] = __builtin_amdgcn_mfma_f32_16x16x32_bf16(Bt[n][k], At[m][k], acc[ai][bj][m][n], 0, 0, 0); __builtin_amdgcn_s_setprio(0); } while (0)
; #define PG8_WAIT_V(n) asm volatile("s_waitcnt vmcnt(" #n ")" ::: "memory")
; template <class Epi, class Sched, bool ALIGN_EPI = false, bool SP2 = false>
; __device__ __forceinline__ void gemm_phase(PG8_LAS unsigned char* lds, const Gemm g, const Sched& S, const Epi& E) {
;     ...
;             PG8_LDB(B0, 0, 0); PG8_LDB(B1, 0, 1); PG8_SCHED; PG8_LDA(At, 0, 0); PG8_STAGE(PG8_SA(1, 1), a1 + hstep, voffA);
;             PG8_WAIT_V(8); PG8_WAIT_L(0); PG8_BAR; PG8_MMA(0, 0, At, B0); PG8_MMA(0, 1, At, B1); PG8_BAR; PG8_SCHED;
;             PG8_LDA(At, 0, 1); PG8_STAGE(PG8_SB(0, 0), b2, voffB); PG8_STAGE(PG8_SB(0, 1), b2 + hstep, voffB); PG8_STAGE(PG8_SA(0, 0), a2, voffA);
;             PG8_WAIT_V(8); PG8_WAIT_L(0); PG8_BAR; PG8_MMA(1, 0, At, B0); PG8_MMA(1, 1, At, B1); PG8_BAR; PG8_SCHED;
;             PG8_LDB(B0, 1, 0); PG8_LDB(B1, 1, 1); PG8_SCHED; PG8_LDA(At, 1, 0); PG8_STAGE(PG8_SA(0, 1), a2 + hstep, voffA);
;             PG8_WAIT_V(8); PG8_WAIT_L(0); PG8_BAR; PG8_MMA(0, 0, At, B0); PG8_MMA(0, 1, At, B1); PG8_BAR; PG8_SCHED;
;             PG8_LDA(At, 1, 1); PG8_STAGE(PG8_SB(1, 0), b3, voffB); PG8_STAGE(PG8_SB(1, 1), b3 + hstep, voffB); PG8_STAGE(PG8_SA(1, 0), a3, voffA);
;             PG8_WAIT_V(8); PG8_WAIT_L(0); PG8_BAR; PG8_MMA(1, 0, At, B0); PG8_MMA(1, 1, At, B1); PG8_BAR; PG8_SCHED;
	s_setprio 0
	s_add_i32 s28, s48, s31
	v_lshl_add_u64 v[160:161], v[160:161], 0, s[10:11]
	s_mov_b32 m0, s28
	ds_read_b128 v[196:199], v175 offset:49152
	ds_read_b128 v[200:203], v175 offset:50176
	ds_read_b128 v[204:207], v175 offset:51200
	ds_read_b128 v[208:211], v175 offset:52224
	ds_read_b128 v[212:215], v175 offset:53248
	ds_read_b128 v[216:219], v175 offset:54272
	ds_read_b128 v[220:223], v175 offset:55296
	ds_read_b128 v[224:227], v175 offset:56320
	global_load_lds_dwordx4 v[160:161], off
	s_add_i32 m0, s28, 0x2000
	s_add_u32 s26, s26, 0x80080
	v_lshl_add_u64 v[160:161], v[184:185], 0, s[10:11]
	s_addc_u32 s27, s27, 0
	s_add_i32 s28, s49, s31
	global_load_lds_dwordx4 v[160:161], off
	v_lshl_add_u64 v[160:161], s[26:27], 0, v[146:147]
	s_mov_b32 m0, s28
	s_nop 0
	global_load_lds_dwordx4 v[160:161], off
	v_lshl_add_u64 v[160:161], s[26:27], 0, v[150:151]
	s_add_i32 m0, s28, 0x2000
	s_nop 0
	global_load_lds_dwordx4 v[160:161], off
	v_lshl_add_u64 v[160:161], v[228:229], 0, s[10:11]
	s_mov_b32 m0, s38
	s_nop 0
	global_load_lds_dwordx4 v[160:161], off
	v_lshl_add_u64 v[160:161], v[230:231], 0, s[10:11]
	s_mov_b32 m0, s39
	s_nop 0
	global_load_lds_dwordx4 v[160:161], off
	s_setprio 1
	s_waitcnt vmcnt(8)
	s_waitcnt lgkmcnt(0)
	s_barrier
	v_mfma_f32_16x16x32_bf16 v[60:63], v[128:131], v[196:199], v[60:63]
	v_mfma_f32_16x16x32_bf16 v[56:59], v[136:139], v[196:199], v[56:59]
	v_mfma_f32_16x16x32_bf16 v[44:47], v[128:131], v[204:207], v[44:47]
	v_mfma_f32_16x16x32_bf16 v[40:43], v[136:139], v[204:207], v[40:43]
	v_mfma_f32_16x16x32_bf16 v[28:31], v[128:131], v[212:215], v[28:31]
	v_mfma_f32_16x16x32_bf16 v[24:27], v[136:139], v[212:215], v[24:27]
	v_mfma_f32_16x16x32_bf16 v[12:15], v[128:131], v[220:223], v[12:15]
	v_mfma_f32_16x16x32_bf16 v[8:11], v[136:139], v[220:223], v[8:11]
	v_mfma_f32_16x16x32_bf16 v[60:63], v[132:135], v[200:203], v[60:63]
	v_mfma_f32_16x16x32_bf16 v[56:59], v[140:143], v[200:203], v[56:59]
	v_mfma_f32_16x16x32_bf16 v[44:47], v[132:135], v[208:211], v[44:47]
	v_mfma_f32_16x16x32_bf16 v[40:43], v[140:143], v[208:211], v[40:43]
	v_mfma_f32_16x16x32_bf16 v[28:31], v[132:135], v[216:219], v[28:31]
	v_mfma_f32_16x16x32_bf16 v[24:27], v[140:143], v[216:219], v[24:27]
	v_mfma_f32_16x16x32_bf16 v[12:15], v[132:135], v[224:227], v[12:15]
	v_mfma_f32_16x16x32_bf16 v[8:11], v[140:143], v[224:227], v[8:11]
	s_setprio 0
	s_setprio 1
	v_mfma_f32_16x16x32_bf16 v[52:55], v[176:179], v[196:199], v[52:55]
	v_mfma_f32_16x16x32_bf16 v[48:51], v[188:191], v[196:199], v[48:51]
	v_mfma_f32_16x16x32_bf16 v[36:39], v[176:179], v[204:207], v[36:39]
	v_mfma_f32_16x16x32_bf16 v[32:35], v[188:191], v[204:207], v[32:35]
	v_mfma_f32_16x16x32_bf16 v[20:23], v[176:179], v[212:215], v[20:23]
	v_mfma_f32_16x16x32_bf16 v[16:19], v[188:191], v[212:215], v[16:19]
	v_mfma_f32_16x16x32_bf16 v[4:7], v[176:179], v[220:223], v[4:7]
	v_mfma_f32_16x16x32_bf16 v[0:3], v[188:191], v[220:223], v[0:3]
	v_mfma_f32_16x16x32_bf16 v[52:55], v[180:183], v[200:203], v[52:55]
	v_mfma_f32_16x16x32_bf16 v[48:51], v[192:195], v[200:203], v[48:51]
	v_mfma_f32_16x16x32_bf16 v[36:39], v[180:183], v[208:211], v[36:39]
	v_mfma_f32_16x16x32_bf16 v[32:35], v[192:195], v[208:211], v[32:35]
	v_mfma_f32_16x16x32_bf16 v[20:23], v[180:183], v[216:219], v[20:23]
	v_mfma_f32_16x16x32_bf16 v[16:19], v[192:195], v[216:219], v[16:19]
	v_mfma_f32_16x16x32_bf16 v[4:7], v[180:183], v[224:227], v[4:7]
	v_mfma_f32_16x16x32_bf16 v[0:3], v[192:195], v[224:227], v[0:3]
	s_barrier
	s_setprio 0
	s_add_i32 s47, s47, 2
	s_add_u32 s24, s24, 0x100
	s_addc_u32 s25, s25, 0
	s_add_u32 s45, s45, 0x100
	s_addc_u32 s46, s46, 0
	s_cmp_gt_u32 s47, 29
.LBB0_994:
	ds_read_b128 v[128:131], v173
	ds_read_b128 v[132:135], v173 offset:1024
	ds_read_b128 v[136:139], v173 offset:2048
	ds_read_b128 v[140:143], v173 offset:3072
	ds_read_b128 v[176:179], v174
	ds_read_b128 v[180:183], v174 offset:1024
	ds_read_b128 v[188:191], v174 offset:2048
	ds_read_b128 v[192:195], v174 offset:3072
	s_add_u32 s26, s24, 0xfff80080
	s_addc_u32 s27, s25, -1
	s_cmp_eq_u32 s47, 28
	s_cselect_b32 s29, s15, s27
	s_cselect_b32 s28, s43, s26
	s_cselect_b32 s27, s17, s46
	s_cselect_b32 s26, s44, s45
	v_lshl_add_u64 v[160:161], s[24:25], 0, v[152:153]
	s_add_i32 m0, s23, 0xc000
	ds_read_b128 v[196:199], v175
	ds_read_b128 v[200:203], v175 offset:1024
	ds_read_b128 v[204:207], v175 offset:2048
	ds_read_b128 v[208:211], v175 offset:3072
	ds_read_b128 v[212:215], v175 offset:4096
	ds_read_b128 v[216:219], v175 offset:5120
	ds_read_b128 v[220:223], v175 offset:6144
	ds_read_b128 v[224:227], v175 offset:7168
	global_load_lds_dwordx4 v[160:161], off
	v_lshl_add_u64 v[160:161], s[24:25], 0, v[154:155]
	s_add_i32 m0, s23, 0xe000
	s_nop 0
	global_load_lds_dwordx4 v[160:161], off
	s_setprio 1
	s_waitcnt vmcnt(8)
	s_waitcnt lgkmcnt(0)
	s_barrier
; #define PG8_STAGE(bufoff, gbase, voff) do { _Pragma("unroll") for (int _i = 0; _i < 2; ++_i) \
;         __builtin_amdgcn_global_load_lds((const unsigned*)((const char*)(gbase) + (voff)[_i]), (PG8_LAS unsigned*)(lds + (bufoff) + ldsw + _i * 8192), 16, 0, 0); } while (0)
; #define PG8_LDA(dst, b, h) do { _Pragma("unroll") for (int m = 0; m < 4; ++m) _Pragma("unroll") for (int k = 0; k < 2; ++k) dst[m][k] = *(const PG8_LAS bf16x8*)(lds + PG8_SA(b, h) + aoff + m * 2048 + k * 1024); } while (0)
; #define PG8_LDB(dst, b, h) do { _Pragma("unroll") for (int n = 0; n < 2; ++n) _Pragma("unroll") for (int k = 0; k < 2; ++k) dst[n][k] = *(const PG8_LAS bf16x8*)(lds + PG8_SB(b, h) + boff + n * 2048 + k * 1024); } while (0)
; #define PG8_MMA(ai, bj, At, Bt) do { __builtin_amdgcn_s_setprio(1); _Pragma("unroll") for (int m = 0; m < 4; ++m) _Pragma("unroll") for (int n = 0; n < 2; ++n) _Pragma("unroll") for (int k = 0; k < 2; ++k) \
;         acc[ai][bj][m][n] = __builtin_amdgcn_mfma_f32_16x16x32_bf16(Bt[n][k], At[m][k], acc[ai][bj][m][n], 0, 0, 0); __builtin_amdgcn_s_setprio(0); } while (0)
; #define PG8_WAIT_V(n) asm volatile("s_waitcnt vmcnt(" #n ")" ::: "memory")
; template <class Epi, class Sched, bool ALIGN_EPI = false, bool SP2 = false>
; __device__ __forceinline__ void gemm_phase(PG8_LAS unsigned char* lds, const Gemm g, const Sched& S, const Epi& E) {
;     ...
;             PG8_LDB(B0, 0, 0); PG8_LDB(B1, 0, 1); PG8_SCHED; PG8_LDA(At, 0, 0); PG8_STAGE(PG8_SA(1, 1), a1 + hstep, voffA);
;             PG8_WAIT_V(8); PG8_WAIT_L(0); PG8_BAR; PG8_MMA(0, 0, At, B0); PG8_MMA(0, 1, At, B1); PG8_BAR; PG8_SCHED;
;             PG8_LDA(At, 0, 1); PG8_STAGE(PG8_SB(0, 0), b2, voffB); PG8_STAGE(PG8_SB(0, 1), b2 + hstep, voffB); PG8_STAGE(PG8_SA(0, 0), a2, voffA);
;             PG8_WAIT_V(8); PG8_WAIT_L(0); PG8_BAR; PG8_MMA(1, 0, At, B0); PG8_MMA(1, 1, At, B1); PG8_BAR; PG8_SCHED;
;             PG8_LDB(B0, 1, 0); PG8_LDB(B1, 1, 1); PG8_SCHED; PG8_LDA(At, 1, 0); PG8_STAGE(PG8_SA(0, 1), a2 + hstep, voffA);
;             PG8_WAIT_V(8); PG8_WAIT_L(0); PG8_BAR; PG8_MMA(0, 0, At, B0); PG8_MMA(0, 1, At, B1); PG8_BAR; PG8_SCHED;
;             PG8_LDA(At, 1, 1); PG8_STAGE(PG8_SB(1, 0), b3, voffB); PG8_STAGE(PG8_SB(1, 1), b3 + hstep, voffB); PG8_STAGE(PG8_SA(1, 0), a3, voffA);
;             PG8_WAIT_V(8); PG8_WAIT_L(0); PG8_BAR; PG8_MMA(1, 0, At, B0); PG8_MMA(1, 1, At, B1); PG8_BAR; PG8_SCHED;
	v_mfma_f32_16x16x32_bf16 v[124:127], v[128:131], v[196:199], v[124:127]
	v_mfma_f32_16x16x32_bf16 v[120:123], v[136:139], v[196:199], v[120:123]
	v_mfma_f32_16x16x32_bf16 v[108:111], v[128:131], v[204:207], v[108:111]
	v_mfma_f32_16x16x32_bf16 v[104:107], v[136:139], v[204:207], v[104:107]
	v_mfma_f32_16x16x32_bf16 v[92:95], v[128:131], v[212:215], v[92:95]
	v_mfma_f32_16x16x32_bf16 v[88:91], v[136:139], v[212:215], v[88:91]
	v_mfma_f32_16x16x32_bf16 v[76:79], v[128:131], v[220:223], v[76:79]
	v_mfma_f32_16x16x32_bf16 v[72:75], v[136:139], v[220:223], v[72:75]
	v_mfma_f32_16x16x32_bf16 v[124:127], v[132:135], v[200:203], v[124:127]
	v_mfma_f32_16x16x32_bf16 v[120:123], v[140:143], v[200:203], v[120:123]
	v_mfma_f32_16x16x32_bf16 v[108:111], v[132:135], v[208:211], v[108:111]
	v_mfma_f32_16x16x32_bf16 v[104:107], v[140:143], v[208:211], v[104:107]
	v_mfma_f32_16x16x32_bf16 v[92:95], v[132:135], v[216:219], v[92:95]
	v_mfma_f32_16x16x32_bf16 v[88:91], v[140:143], v[216:219], v[88:91]
	v_mfma_f32_16x16x32_bf16 v[76:79], v[132:135], v[224:227], v[76:79]
	v_mfma_f32_16x16x32_bf16 v[72:75], v[140:143], v[224:227], v[72:75]
	s_setprio 0
	s_setprio 1
	v_mfma_f32_16x16x32_bf16 v[116:119], v[176:179], v[196:199], v[116:119]
	v_mfma_f32_16x16x32_bf16 v[112:115], v[188:191], v[196:199], v[112:115]
	v_mfma_f32_16x16x32_bf16 v[100:103], v[176:179], v[204:207], v[100:103]
	v_mfma_f32_16x16x32_bf16 v[96:99], v[188:191], v[204:207], v[96:99]
	v_mfma_f32_16x16x32_bf16 v[84:87], v[176:179], v[212:215], v[84:87]
	v_mfma_f32_16x16x32_bf16 v[80:83], v[188:191], v[212:215], v[80:83]
	v_mfma_f32_16x16x32_bf16 v[68:71], v[176:179], v[220:223], v[68:71]
	v_mfma_f32_16x16x32_bf16 v[64:67], v[188:191], v[220:223], v[64:67]
	v_mfma_f32_16x16x32_bf16 v[116:119], v[180:183], v[200:203], v[116:119]
	v_mfma_f32_16x16x32_bf16 v[112:115], v[192:195], v[200:203], v[112:115]
	v_mfma_f32_16x16x32_bf16 v[100:103], v[180:183], v[208:211], v[100:103]
	v_mfma_f32_16x16x32_bf16 v[96:99], v[192:195], v[208:211], v[96:99]
	v_mfma_f32_16x16x32_bf16 v[84:87], v[180:183], v[216:219], v[84:87]
	v_mfma_f32_16x16x32_bf16 v[80:83], v[192:195], v[216:219], v[80:83]
	v_mfma_f32_16x16x32_bf16 v[68:71], v[180:183], v[224:227], v[68:71]
	v_mfma_f32_16x16x32_bf16 v[64:67], v[192:195], v[224:227], v[64:67]
	s_barrier
	s_setprio 0
	s_add_i32 s48, s40, s31
	v_lshl_add_u64 v[160:161], s[26:27], 0, v[146:147]
	s_mov_b32 m0, s48
	ds_read_b128 v[196:199], v175 offset:16384
	ds_read_b128 v[200:203], v175 offset:17408
	ds_read_b128 v[204:207], v175 offset:18432
	ds_read_b128 v[208:211], v175 offset:19456
	ds_read_b128 v[212:215], v175 offset:20480
	ds_read_b128 v[216:219], v175 offset:21504
	ds_read_b128 v[220:223], v175 offset:22528
	ds_read_b128 v[224:227], v175 offset:23552
	global_load_lds_dwordx4 v[160:161], off
	s_add_i32 m0, s48, 0x2000
	s_add_u32 s48, s26, 0x80000
	v_lshl_add_u64 v[184:185], s[26:27], 0, v[150:151]
	s_addc_u32 s49, s27, 0
	s_add_i32 s50, s41, s31
	global_load_lds_dwordx4 v[184:185], off
	v_lshl_add_u64 v[228:229], s[48:49], 0, v[146:147]
	s_mov_b32 m0, s50
	v_lshl_add_u64 v[230:231], s[28:29], 0, v[148:149]
	global_load_lds_dwordx4 v[228:229], off
	v_lshl_add_u64 v[228:229], s[48:49], 0, v[150:151]
	s_add_i32 m0, s50, 0x2000
	s_nop 0
	global_load_lds_dwordx4 v[228:229], off
	v_lshl_add_u64 v[228:229], s[28:29], 0, v[144:145]
	s_mov_b32 m0, s23
	s_nop 0
	global_load_lds_dwordx4 v[228:229], off
	s_mov_b32 m0, s33
	s_nop 0
	global_load_lds_dwordx4 v[230:231], off
	s_setprio 1
	s_waitcnt vmcnt(8)
	s_waitcnt lgkmcnt(0)
	s_barrier
	v_mfma_f32_16x16x32_bf16 v[60:63], v[128:131], v[196:199], v[60:63]
	v_mfma_f32_16x16x32_bf16 v[56:59], v[136:139], v[196:199], v[56:59]
	v_mfma_f32_16x16x32_bf16 v[44:47], v[128:131], v[204:207], v[44:47]
	v_mfma_f32_16x16x32_bf16 v[40:43], v[136:139], v[204:207], v[40:43]
	v_mfma_f32_16x16x32_bf16 v[28:31], v[128:131], v[212:215], v[28:31]
	v_mfma_f32_16x16x32_bf16 v[24:27], v[136:139], v[212:215], v[24:27]
	v_mfma_f32_16x16x32_bf16 v[12:15], v[128:131], v[220:223], v[12:15]
	v_mfma_f32_16x16x32_bf16 v[8:11], v[136:139], v[220:223], v[8:11]
	v_mfma_f32_16x16x32_bf16 v[60:63], v[132:135], v[200:203], v[60:63]
	v_mfma_f32_16x16x32_bf16 v[56:59], v[140:143], v[200:203], v[56:59]
	v_mfma_f32_16x16x32_bf16 v[44:47], v[132:135], v[208:211], v[44:47]
	v_mfma_f32_16x16x32_bf16 v[40:43], v[140:143], v[208:211], v[40:43]
	v_mfma_f32_16x16x32_bf16 v[28:31], v[132:135], v[216:219], v[28:31]
	v_mfma_f32_16x16x32_bf16 v[24:27], v[140:143], v[216:219], v[24:27]
	v_mfma_f32_16x16x32_bf16 v[12:15], v[132:135], v[224:227], v[12:15]
	v_mfma_f32_16x16x32_bf16 v[8:11], v[140:143], v[224:227], v[8:11]
	s_setprio 0
	s_setprio 1
	v_mfma_f32_16x16x32_bf16 v[52:55], v[176:179], v[196:199], v[52:55]
	v_mfma_f32_16x16x32_bf16 v[48:51], v[188:191], v[196:199], v[48:51]
	v_mfma_f32_16x16x32_bf16 v[36:39], v[176:179], v[204:207], v[36:39]
	v_mfma_f32_16x16x32_bf16 v[32:35], v[188:191], v[204:207], v[32:35]
	v_mfma_f32_16x16x32_bf16 v[20:23], v[176:179], v[212:215], v[20:23]
	v_mfma_f32_16x16x32_bf16 v[16:19], v[188:191], v[212:215], v[16:19]
	v_mfma_f32_16x16x32_bf16 v[4:7], v[176:179], v[220:223], v[4:7]
	v_mfma_f32_16x16x32_bf16 v[0:3], v[188:191], v[220:223], v[0:3]
	v_mfma_f32_16x16x32_bf16 v[52:55], v[180:183], v[200:203], v[52:55]
	v_mfma_f32_16x16x32_bf16 v[48:51], v[192:195], v[200:203], v[48:51]
	v_mfma_f32_16x16x32_bf16 v[36:39], v[180:183], v[208:211], v[36:39]
	v_mfma_f32_16x16x32_bf16 v[32:35], v[192:195], v[208:211], v[32:35]
	v_mfma_f32_16x16x32_bf16 v[20:23], v[180:183], v[216:219], v[20:23]
	v_mfma_f32_16x16x32_bf16 v[16:19], v[192:195], v[216:219], v[16:19]
	v_mfma_f32_16x16x32_bf16 v[4:7], v[180:183], v[224:227], v[4:7]
	v_mfma_f32_16x16x32_bf16 v[0:3], v[192:195], v[224:227], v[0:3]
	s_barrier
; #define PG8_STAGE(bufoff, gbase, voff) do { _Pragma("unroll") for (int _i = 0; _i < 2; ++_i) \
;         __builtin_amdgcn_global_load_lds((const unsigned*)((const char*)(gbase) + (voff)[_i]), (PG8_LAS unsigned*)(lds + (bufoff) + ldsw + _i * 8192), 16, 0, 0); } while (0)
; #define PG8_LDA(dst, b, h) do { _Pragma("unroll") for (int m = 0; m < 4; ++m) _Pragma("unroll") for (int k = 0; k < 2; ++k) dst[m][k] = *(const PG8_LAS bf16x8*)(lds + PG8_SA(b, h) + aoff + m * 2048 + k * 1024); } while (0)
; #define PG8_LDB(dst, b, h) do { _Pragma("unroll") for (int n = 0; n < 2; ++n) _Pragma("unroll") for (int k = 0; k < 2; ++k) dst[n][k] = *(const PG8_LAS bf16x8*)(lds + PG8_SB(b, h) + boff + n * 2048 + k * 1024); } while (0)
; #define PG8_MMA(ai, bj, At, Bt) do { __builtin_amdgcn_s_setprio(1); _Pragma("unroll") for (int m = 0; m < 4; ++m) _Pragma("unroll") for (int n = 0; n < 2; ++n) _Pragma("unroll") for (int k = 0; k < 2; ++k) \
;         acc[ai][bj][m][n] = __builtin_amdgcn_mfma_f32_16x16x32_bf16(Bt[n][k], At[m][k], acc[ai][bj][m][n], 0, 0, 0); __builtin_amdgcn_s_setprio(0); } while (0)
; #define PG8_WAIT_V(n) asm volatile("s_waitcnt vmcnt(" #n ")" ::: "memory")
; template <class Epi, class Sched, bool ALIGN_EPI = false, bool SP2 = false>
; __device__ __forceinline__ void gemm_phase(PG8_LAS unsigned char* lds, const Gemm g, const Sched& S, const Epi& E) {
;     ...
;             PG8_LDB(B0, 0, 0); PG8_LDB(B1, 0, 1); PG8_SCHED; PG8_LDA(At, 0, 0); PG8_STAGE(PG8_SA(1, 1), a1 + hstep, voffA);
;             PG8_WAIT_V(8); PG8_WAIT_L(0); PG8_BAR; PG8_MMA(0, 0, At, B0); PG8_MMA(0, 1, At, B1); PG8_BAR; PG8_SCHED;
;             PG8_LDA(At, 0, 1); PG8_STAGE(PG8_SB(0, 0), b2, voffB); PG8_STAGE(PG8_SB(0, 1), b2 + hstep, voffB); PG8_STAGE(PG8_SA(0, 0), a2, voffA);
;             PG8_WAIT_V(8); PG8_WAIT_L(0); PG8_BAR; PG8_MMA(1, 0, At, B0); PG8_MMA(1, 1, At, B1); PG8_BAR; PG8_SCHED;
;             PG8_LDB(B0, 1, 0); PG8_LDB(B1, 1, 1); PG8_SCHED; PG8_LDA(At, 1, 0); PG8_STAGE(PG8_SA(0, 1), a2 + hstep, voffA);
;             PG8_WAIT_V(8); PG8_WAIT_L(0); PG8_BAR; PG8_MMA(0, 0, At, B0); PG8_MMA(0, 1, At, B1); PG8_BAR; PG8_SCHED;
;             PG8_LDA(At, 1, 1); PG8_STAGE(PG8_SB(1, 0), b3, voffB); PG8_STAGE(PG8_SB(1, 1), b3 + hstep, voffB); PG8_STAGE(PG8_SA(1, 0), a3, voffA);
;             PG8_WAIT_V(8); PG8_WAIT_L(0); PG8_BAR; PG8_MMA(1, 0, At, B0); PG8_MMA(1, 1, At, B1); PG8_BAR; PG8_SCHED;
	s_setprio 0
	s_add_i32 s48, 0, 0x18000
	s_add_i32 s49, 0, 0x1c000
	v_add_u32_e32 v140, s48, v163
	v_add_u32_e32 v187, s49, v163
	ds_read_b128 v[128:131], v140
	ds_read_b128 v[132:135], v140 offset:1024
	ds_read_b128 v[136:139], v140 offset:2048
	ds_read_b128 v[140:143], v140 offset:3072
	ds_read_b128 v[176:179], v187
	ds_read_b128 v[180:183], v187 offset:1024
	ds_read_b128 v[188:191], v187 offset:2048
	ds_read_b128 v[192:195], v187 offset:3072
	s_add_u32 s28, s28, 0x80000
	s_addc_u32 s29, s29, 0
	s_mov_b32 m0, s34
	v_lshl_add_u64 v[232:233], s[28:29], 0, v[144:145]
	ds_read_b128 v[196:199], v175 offset:32768
	ds_read_b128 v[200:203], v175 offset:33792
	ds_read_b128 v[204:207], v175 offset:34816
	ds_read_b128 v[208:211], v175 offset:35840
	ds_read_b128 v[212:215], v175 offset:36864
	ds_read_b128 v[216:219], v175 offset:37888
	ds_read_b128 v[220:223], v175 offset:38912
	ds_read_b128 v[224:227], v175 offset:39936
	global_load_lds_dwordx4 v[232:233], off
	v_lshl_add_u64 v[232:233], s[28:29], 0, v[148:149]
	s_mov_b32 m0, s35
	s_nop 0
	global_load_lds_dwordx4 v[232:233], off
	s_setprio 1
	s_waitcnt vmcnt(8)
	s_waitcnt lgkmcnt(0)
	s_barrier
	v_mfma_f32_16x16x32_bf16 v[124:127], v[128:131], v[196:199], v[124:127]
	v_mfma_f32_16x16x32_bf16 v[120:123], v[136:139], v[196:199], v[120:123]
	v_mfma_f32_16x16x32_bf16 v[108:111], v[128:131], v[204:207], v[108:111]
	v_mfma_f32_16x16x32_bf16 v[104:107], v[136:139], v[204:207], v[104:107]
	v_mfma_f32_16x16x32_bf16 v[92:95], v[128:131], v[212:215], v[92:95]
	v_mfma_f32_16x16x32_bf16 v[88:91], v[136:139], v[212:215], v[88:91]
	v_mfma_f32_16x16x32_bf16 v[76:79], v[128:131], v[220:223], v[76:79]
	v_mfma_f32_16x16x32_bf16 v[72:75], v[136:139], v[220:223], v[72:75]
	v_mfma_f32_16x16x32_bf16 v[124:127], v[132:135], v[200:203], v[124:127]
	v_mfma_f32_16x16x32_bf16 v[120:123], v[140:143], v[200:203], v[120:123]
	v_mfma_f32_16x16x32_bf16 v[108:111], v[132:135], v[208:211], v[108:111]
	v_mfma_f32_16x16x32_bf16 v[104:107], v[140:143], v[208:211], v[104:107]
	v_mfma_f32_16x16x32_bf16 v[92:95], v[132:135], v[216:219], v[92:95]
	v_mfma_f32_16x16x32_bf16 v[88:91], v[140:143], v[216:219], v[88:91]
	v_mfma_f32_16x16x32_bf16 v[76:79], v[132:135], v[224:227], v[76:79]
	v_mfma_f32_16x16x32_bf16 v[72:75], v[140:143], v[224:227], v[72:75]
	s_setprio 0
	s_setprio 1
	v_mfma_f32_16x16x32_bf16 v[116:119], v[176:179], v[196:199], v[116:119]
	v_mfma_f32_16x16x32_bf16 v[112:115], v[188:191], v[196:199], v[112:115]
	v_mfma_f32_16x16x32_bf16 v[100:103], v[176:179], v[204:207], v[100:103]
	v_mfma_f32_16x16x32_bf16 v[96:99], v[188:191], v[204:207], v[96:99]
	v_mfma_f32_16x16x32_bf16 v[84:87], v[176:179], v[212:215], v[84:87]
	v_mfma_f32_16x16x32_bf16 v[80:83], v[188:191], v[212:215], v[80:83]
	v_mfma_f32_16x16x32_bf16 v[68:71], v[176:179], v[220:223], v[68:71]
	v_mfma_f32_16x16x32_bf16 v[64:67], v[188:191], v[220:223], v[64:67]
	v_mfma_f32_16x16x32_bf16 v[116:119], v[180:183], v[200:203], v[116:119]
	v_mfma_f32_16x16x32_bf16 v[112:115], v[192:195], v[200:203], v[112:115]
	v_mfma_f32_16x16x32_bf16 v[100:103], v[180:183], v[208:211], v[100:103]
	v_mfma_f32_16x16x32_bf16 v[96:99], v[192:195], v[208:211], v[96:99]
	v_mfma_f32_16x16x32_bf16 v[84:87], v[180:183], v[216:219], v[84:87]
	v_mfma_f32_16x16x32_bf16 v[80:83], v[192:195], v[216:219], v[80:83]
	v_mfma_f32_16x16x32_bf16 v[68:71], v[180:183], v[224:227], v[68:71]
	v_mfma_f32_16x16x32_bf16 v[64:67], v[192:195], v[224:227], v[64:67]
	s_barrier
; #define PG8_STAGE(bufoff, gbase, voff) do { _Pragma("unroll") for (int _i = 0; _i < 2; ++_i) \
;         __builtin_amdgcn_global_load_lds((const unsigned*)((const char*)(gbase) + (voff)[_i]), (PG8_LAS unsigned*)(lds + (bufoff) + ldsw + _i * 8192), 16, 0, 0); } while (0)
; #define PG8_LDA(dst, b, h) do { _Pragma("unroll") for (int m = 0; m < 4; ++m) _Pragma("unroll") for (int k = 0; k < 2; ++k) dst[m][k] = *(const PG8_LAS bf16x8*)(lds + PG8_SA(b, h) + aoff + m * 2048 + k * 1024); } while (0)
; #define PG8_LDB(dst, b, h) do { _Pragma("unroll") for (int n = 0; n < 2; ++n) _Pragma("unroll") for (int k = 0; k < 2; ++k) dst[n][k] = *(const PG8_LAS bf16x8*)(lds + PG8_SB(b, h) + boff + n * 2048 + k * 1024); } while (0)
; #define PG8_MMA(ai, bj, At, Bt) do { __builtin_amdgcn_s_setprio(1); _Pragma("unroll") for (int m = 0; m < 4; ++m) _Pragma("unroll") for (int n = 0; n < 2; ++n) _Pragma("unroll") for (int k = 0; k < 2; ++k) \
;         acc[ai][bj][m][n] = __builtin_amdgcn_mfma_f32_16x16x32_bf16(Bt[n][k], At[m][k], acc[ai][bj][m][n], 0, 0, 0); __builtin_amdgcn_s_setprio(0); } while (0)
; template <class Epi, class Sched, bool ALIGN_EPI = false, bool SP2 = false>
; __device__ __forceinline__ void gemm_phase(PG8_LAS unsigned char* lds, const Gemm g, const Sched& S, const Epi& E) {
;     ...
;             PG8_LDB(B0, 0, 0); PG8_LDB(B1, 0, 1); PG8_SCHED; PG8_LDA(At, 0, 0); PG8_STAGE(PG8_SA(1, 1), a1 + hstep, voffA);
;             PG8_WAIT_V(8); PG8_WAIT_L(0); PG8_BAR; PG8_MMA(0, 0, At, B0); PG8_MMA(0, 1, At, B1); PG8_BAR; PG8_SCHED;
;             PG8_LDA(At, 0, 1); PG8_STAGE(PG8_SB(0, 0), b2, voffB); PG8_STAGE(PG8_SB(0, 1), b2 + hstep, voffB); PG8_STAGE(PG8_SA(0, 0), a2, voffA);
;             PG8_WAIT_V(8); PG8_WAIT_L(0); PG8_BAR; PG8_MMA(1, 0, At, B0); PG8_MMA(1, 1, At, B1); PG8_BAR; PG8_SCHED;
;             PG8_LDB(B0, 1, 0); PG8_LDB(B1, 1, 1); PG8_SCHED; PG8_LDA(At, 1, 0); PG8_STAGE(PG8_SA(0, 1), a2 + hstep, voffA);
;             PG8_WAIT_V(8); PG8_WAIT_L(0); PG8_BAR; PG8_MMA(0, 0, At, B0); PG8_MMA(0, 1, At, B1); PG8_BAR; PG8_SCHED;
;             PG8_LDA(At, 1, 1); PG8_STAGE(PG8_SB(1, 0), b3, voffB); PG8_STAGE(PG8_SB(1, 1), b3 + hstep, voffB); PG8_STAGE(PG8_SA(1, 0), a3, voffA);
;             PG8_WAIT_V(8); PG8_WAIT_L(0); PG8_BAR; PG8_MMA(1, 0, At, B0); PG8_MMA(1, 1, At, B1); PG8_BAR; PG8_SCHED;
;     ...
;         if constexpr (ALIGN_EPI) { if (wr == 0) PG8_BAR; }
	s_setprio 0
	s_add_i32 s28, s48, s31
	v_lshl_add_u64 v[160:161], v[160:161], 0, s[10:11]
	s_mov_b32 m0, s28
	ds_read_b128 v[196:199], v175 offset:49152
	ds_read_b128 v[200:203], v175 offset:50176
	ds_read_b128 v[204:207], v175 offset:51200
	ds_read_b128 v[208:211], v175 offset:52224
	ds_read_b128 v[212:215], v175 offset:53248
	ds_read_b128 v[216:219], v175 offset:54272
	ds_read_b128 v[220:223], v175 offset:55296
	ds_read_b128 v[224:227], v175 offset:56320
	global_load_lds_dwordx4 v[160:161], off
	s_add_i32 m0, s28, 0x2000
	s_add_u32 s26, s26, 0x80080
	v_lshl_add_u64 v[160:161], v[184:185], 0, s[10:11]
	s_addc_u32 s27, s27, 0
	s_add_i32 s28, s49, s31
	global_load_lds_dwordx4 v[160:161], off
	v_lshl_add_u64 v[160:161], s[26:27], 0, v[146:147]
	s_mov_b32 m0, s28
	s_nop 0
	global_load_lds_dwordx4 v[160:161], off
	v_lshl_add_u64 v[160:161], s[26:27], 0, v[150:151]
	s_add_i32 m0, s28, 0x2000
	s_nop 0
	global_load_lds_dwordx4 v[160:161], off
	v_lshl_add_u64 v[160:161], v[228:229], 0, s[10:11]
	s_mov_b32 m0, s38
	s_nop 0
	global_load_lds_dwordx4 v[160:161], off
	v_lshl_add_u64 v[160:161], v[230:231], 0, s[10:11]
	s_mov_b32 m0, s39
	s_nop 0
	global_load_lds_dwordx4 v[160:161], off
	s_setprio 1
	s_waitcnt vmcnt(8)
	s_waitcnt lgkmcnt(0)
	s_barrier
	v_mfma_f32_16x16x32_bf16 v[60:63], v[128:131], v[196:199], v[60:63]
	v_mfma_f32_16x16x32_bf16 v[56:59], v[136:139], v[196:199], v[56:59]
	v_mfma_f32_16x16x32_bf16 v[44:47], v[128:131], v[204:207], v[44:47]
	v_mfma_f32_16x16x32_bf16 v[40:43], v[136:139], v[204:207], v[40:43]
	v_mfma_f32_16x16x32_bf16 v[28:31], v[128:131], v[212:215], v[28:31]
	v_mfma_f32_16x16x32_bf16 v[24:27], v[136:139], v[212:215], v[24:27]
	v_mfma_f32_16x16x32_bf16 v[12:15], v[128:131], v[220:223], v[12:15]
	v_mfma_f32_16x16x32_bf16 v[8:11], v[136:139], v[220:223], v[8:11]
	v_mfma_f32_16x16x32_bf16 v[60:63], v[132:135], v[200:203], v[60:63]
	v_mfma_f32_16x16x32_bf16 v[56:59], v[140:143], v[200:203], v[56:59]
	v_mfma_f32_16x16x32_bf16 v[44:47], v[132:135], v[208:211], v[44:47]
	v_mfma_f32_16x16x32_bf16 v[40:43], v[140:143], v[208:211], v[40:43]
	v_mfma_f32_16x16x32_bf16 v[28:31], v[132:135], v[216:219], v[28:31]
	v_mfma_f32_16x16x32_bf16 v[24:27], v[140:143], v[216:219], v[24:27]
	v_mfma_f32_16x16x32_bf16 v[12:15], v[132:135], v[224:227], v[12:15]
	v_mfma_f32_16x16x32_bf16 v[8:11], v[140:143], v[224:227], v[8:11]
	s_setprio 0
	s_setprio 1
	v_mfma_f32_16x16x32_bf16 v[52:55], v[176:179], v[196:199], v[52:55]
	v_mfma_f32_16x16x32_bf16 v[48:51], v[188:191], v[196:199], v[48:51]
	v_mfma_f32_16x16x32_bf16 v[36:39], v[176:179], v[204:207], v[36:39]
	v_mfma_f32_16x16x32_bf16 v[32:35], v[188:191], v[204:207], v[32:35]
	v_mfma_f32_16x16x32_bf16 v[20:23], v[176:179], v[212:215], v[20:23]
	v_mfma_f32_16x16x32_bf16 v[16:19], v[188:191], v[212:215], v[16:19]
	v_mfma_f32_16x16x32_bf16 v[4:7], v[176:179], v[220:223], v[4:7]
	v_mfma_f32_16x16x32_bf16 v[0:3], v[188:191], v[220:223], v[0:3]
	v_mfma_f32_16x16x32_bf16 v[52:55], v[180:183], v[200:203], v[52:55]
	v_mfma_f32_16x16x32_bf16 v[48:51], v[192:195], v[200:203], v[48:51]
	v_mfma_f32_16x16x32_bf16 v[36:39], v[180:183], v[208:211], v[36:39]
	v_mfma_f32_16x16x32_bf16 v[32:35], v[192:195], v[208:211], v[32:35]
	v_mfma_f32_16x16x32_bf16 v[20:23], v[180:183], v[216:219], v[20:23]
	v_mfma_f32_16x16x32_bf16 v[16:19], v[192:195], v[216:219], v[16:19]
	v_mfma_f32_16x16x32_bf16 v[4:7], v[180:183], v[224:227], v[4:7]
	v_mfma_f32_16x16x32_bf16 v[0:3], v[192:195], v[224:227], v[0:3]
	s_barrier
	s_setprio 0
	s_add_i32 s47, s47, 2
	s_add_u32 s24, s24, 0x100
	s_addc_u32 s25, s25, 0
	s_add_u32 s45, s45, 0x100
	s_addc_u32 s46, s46, 0
	s_cmp_gt_u32 s47, 29
	s_cbranch_scc0 .LBB0_994
	s_and_b64 vcc, exec, s[12:13]
	s_cbranch_vccz .LBB0_997
	s_barrier

;     __device__ __forceinline__ bool next(int i, Unit& u) const { if (!base.next(i >> 1, u)) return false; if (i & 1) { u.pm += 64; u.pn += 8; } return true; }
; #define PG8_STAGE(bufoff, gbase, voff) do { _Pragma("unroll") for (int _i = 0; _i < 2; ++_i) \
;         __builtin_amdgcn_global_load_lds((const unsigned*)((const char*)(gbase) + (voff)[_i]), (PG8_LAS unsigned*)(lds + (bufoff) + ldsw + _i * 8192), 16, 0, 0); } while (0)
; #define PG8_WAIT_V(n) asm volatile("s_waitcnt vmcnt(" #n ")" ::: "memory")
; template <class Epi, class Sched, bool ALIGN_EPI = false, bool SP2 = false>
; __device__ __forceinline__ void gemm_phase(PG8_LAS unsigned char* lds, const Gemm g, const Sched& S, const Epi& E) {
;     ...
;         const bool has_next = S.next(ui + 1, nxt);
;         const char* nA = has_next ? (const char*)g.A + (size_t)nxt.pm * tstep : cA; const char* nB = has_next ? (const char*)g.Bt + (size_t)nxt.pn * tstep : cB;
;         for (int t = 0; t < nt; t += 2) {
;             const bool last = (t == nt - 2);
;             const char* a1 = cA + (size_t)(t + 1) * kstep;
;             const char* a2 = last ? nA : cA + (size_t)(t + 2) * kstep; const char* b2 = last ? nB : cB + (size_t)(t + 2) * kstep;
;             const char* a3 = a2 + kstep; const char* b3 = b2 + kstep;
;             if (last && has_next) S.a_ready(nxt);
;             if constexpr (SP2) {
;             PG8_LDB(B0, 0, 0); PG8_LDB(B1, 0, 1); PG8_SCHED; PG8_LDA(At, 0, 0); PG8_STAGE(PG8_SA(1, 1), a1 + hstep, voffA);
;             PG8_WAIT_V(8); PG8_WAIT_L(0); PG8_BAR; PG8_MMA(0, 0, At, B0); PG8_MMA(0, 1, At, B1); PG8_BAR; PG8_SCHED;
;             PG8_LDA(At, 0, 1); PG8_STAGE(PG8_SB(0, 0), b2, voffB); PG8_STAGE(PG8_SB(0, 1), b2 + hstep, voffB); PG8_STAGE(PG8_SA(0, 0), a2, voffA);
;             PG8_WAIT_V(8); PG8_WAIT_L(0); PG8_BAR; PG8_MMA(1, 0, At, B0); PG8_MMA(1, 1, At, B1); PG8_BAR; PG8_SCHED;
;             PG8_LDB(B0, 1, 0); PG8_LDB(B1, 1, 1); PG8_SCHED; PG8_LDA(At, 1, 0); PG8_STAGE(PG8_SA(0, 1), a2 + hstep, voffA);
;             PG8_WAIT_V(8); PG8_WAIT_L(0); PG8_BAR; PG8_MMA(0, 0, At, B0); PG8_MMA(0, 1, At, B1); PG8_BAR; PG8_SCHED;
;             PG8_LDA(At, 1, 1); PG8_STAGE(PG8_SB(1, 0), b3, voffB); PG8_STAGE(PG8_SB(1, 1), b3 + hstep, voffB); PG8_STAGE(PG8_SA(1, 0), a3, voffA);
;             PG8_WAIT_V(8); PG8_WAIT_L(0); PG8_BAR; PG8_MMA(1, 0, At, B0); PG8_MMA(1, 1, At, B1); PG8_BAR; PG8_SCHED;
.LBB0_1070:
	s_ashr_i32 s19, s18, 31
	s_lshl_b64 s[20:21], s[18:19], 22
	s_add_u32 s20, s72, s20
	s_addc_u32 s21, s73, s21
	s_and_b64 s[22:23], s[0:1], exec
	s_cselect_b32 s19, s21, s27
	s_cselect_b32 s51, s20, s26
	s_ashr_i32 s17, s16, 31
	s_lshl_b64 s[22:23], s[16:17], 22
	v_readlane_b32 s30, v236, 54
	v_readlane_b32 s31, v236, 55
	s_add_u32 s22, s30, s22
	s_addc_u32 s23, s31, s23
	s_and_b64 s[30:31], s[0:1], exec
	s_cselect_b32 s17, s23, s29
	s_cselect_b32 s52, s22, s28
	s_add_u32 s26, s26, 0x200080
	s_addc_u32 s27, s27, 0
	s_add_u32 s53, s28, 0x100
	s_addc_u32 s54, s29, 0
	s_mov_b32 s55, -2
	ds_read_b128 v[64:67], v165
	ds_read_b128 v[108:111], v165 offset:1024
	ds_read_b128 v[116:119], v165 offset:2048
	ds_read_b128 v[128:131], v165 offset:3072
	ds_read_b128 v[156:159], v166
	ds_read_b128 v[168:171], v166 offset:1024
	ds_read_b128 v[172:175], v166 offset:2048
	ds_read_b128 v[176:179], v166 offset:3072
	s_add_u32 s28, s26, 0xffe00080
	s_addc_u32 s29, s27, -1
	s_cmpk_eq_i32 s55, 0x7c
	s_cselect_b32 s31, s19, s29
	s_cselect_b32 s30, s51, s28
	s_cselect_b32 s29, s17, s54
	s_cselect_b32 s28, s52, s53
	v_lshl_add_u64 v[160:161], s[26:27], 0, v[148:149]
	s_add_i32 m0, s35, 0xc000
	ds_read_b128 v[180:183], v167
	ds_read_b128 v[184:187], v167 offset:1024
	ds_read_b128 v[188:191], v167 offset:2048
	ds_read_b128 v[192:195], v167 offset:3072
	ds_read_b128 v[196:199], v167 offset:4096
	ds_read_b128 v[200:203], v167 offset:5120
	ds_read_b128 v[204:207], v167 offset:6144
	ds_read_b128 v[208:211], v167 offset:7168
	global_load_lds_dwordx4 v[160:161], off
	v_lshl_add_u64 v[160:161], s[26:27], 0, v[150:151]
	s_add_i32 m0, s35, 0xe000
	s_nop 0
	global_load_lds_dwordx4 v[160:161], off
	s_setprio 1
	s_waitcnt vmcnt(8)
	s_waitcnt lgkmcnt(0)
	s_barrier
	v_mfma_f32_16x16x32_bf16 v[140:143], v[64:67], v[180:183], 0
	v_mfma_f32_16x16x32_bf16 v[136:139], v[116:119], v[180:183], 0
	v_mfma_f32_16x16x32_bf16 v[120:123], v[64:67], v[188:191], 0
	v_mfma_f32_16x16x32_bf16 v[112:115], v[116:119], v[188:191], 0
	v_mfma_f32_16x16x32_bf16 v[96:99], v[64:67], v[196:199], 0
	v_mfma_f32_16x16x32_bf16 v[92:95], v[116:119], v[196:199], 0
	v_mfma_f32_16x16x32_bf16 v[80:83], v[64:67], v[204:207], 0
	v_mfma_f32_16x16x32_bf16 v[76:79], v[116:119], v[204:207], 0
	v_mfma_f32_16x16x32_bf16 v[140:143], v[108:111], v[184:187], v[140:143]
	v_mfma_f32_16x16x32_bf16 v[136:139], v[128:131], v[184:187], v[136:139]
	v_mfma_f32_16x16x32_bf16 v[120:123], v[108:111], v[192:195], v[120:123]
	v_mfma_f32_16x16x32_bf16 v[112:115], v[128:131], v[192:195], v[112:115]
	v_mfma_f32_16x16x32_bf16 v[96:99], v[108:111], v[200:203], v[96:99]
	v_mfma_f32_16x16x32_bf16 v[92:95], v[128:131], v[200:203], v[92:95]
	v_mfma_f32_16x16x32_bf16 v[80:83], v[108:111], v[208:211], v[80:83]
	v_mfma_f32_16x16x32_bf16 v[76:79], v[128:131], v[208:211], v[76:79]
	s_setprio 0
	s_setprio 1
	v_mfma_f32_16x16x32_bf16 v[132:135], v[156:159], v[180:183], 0
	v_mfma_f32_16x16x32_bf16 v[124:127], v[172:175], v[180:183], 0
	v_mfma_f32_16x16x32_bf16 v[104:107], v[156:159], v[188:191], 0
	v_mfma_f32_16x16x32_bf16 v[100:103], v[172:175], v[188:191], 0
	v_mfma_f32_16x16x32_bf16 v[88:91], v[156:159], v[196:199], 0
	v_mfma_f32_16x16x32_bf16 v[84:87], v[172:175], v[196:199], 0
	v_mfma_f32_16x16x32_bf16 v[72:75], v[156:159], v[204:207], 0
	v_mfma_f32_16x16x32_bf16 v[68:71], v[172:175], v[204:207], 0
	v_mfma_f32_16x16x32_bf16 v[132:135], v[168:171], v[184:187], v[132:135]
	v_mfma_f32_16x16x32_bf16 v[124:127], v[176:179], v[184:187], v[124:127]
	v_mfma_f32_16x16x32_bf16 v[104:107], v[168:171], v[192:195], v[104:107]
	v_mfma_f32_16x16x32_bf16 v[100:103], v[176:179], v[192:195], v[100:103]
	v_mfma_f32_16x16x32_bf16 v[88:91], v[168:171], v[200:203], v[88:91]
	v_mfma_f32_16x16x32_bf16 v[84:87], v[176:179], v[200:203], v[84:87]
	v_mfma_f32_16x16x32_bf16 v[72:75], v[168:171], v[208:211], v[72:75]
	v_mfma_f32_16x16x32_bf16 v[68:71], v[176:179], v[208:211], v[68:71]
	s_barrier
	s_setprio 0
	s_add_i32 s56, s45, s34
	v_lshl_add_u64 v[160:161], s[28:29], 0, v[144:145]
	s_mov_b32 m0, s56
	ds_read_b128 v[180:183], v167 offset:16384
	ds_read_b128 v[184:187], v167 offset:17408
	ds_read_b128 v[188:191], v167 offset:18432
	ds_read_b128 v[192:195], v167 offset:19456
	ds_read_b128 v[196:199], v167 offset:20480
	ds_read_b128 v[200:203], v167 offset:21504
	ds_read_b128 v[204:207], v167 offset:22528
	ds_read_b128 v[208:211], v167 offset:23552
	global_load_lds_dwordx4 v[160:161], off
	s_add_i32 m0, s56, 0x2000
	s_add_u32 s56, s28, 0x200000
	v_lshl_add_u64 v[212:213], s[28:29], 0, v[146:147]
	s_addc_u32 s57, s29, 0
	s_add_i32 s58, s46, s34
	global_load_lds_dwordx4 v[212:213], off
	v_lshl_add_u64 v[214:215], s[56:57], 0, v[144:145]
	s_mov_b32 m0, s58
	v_lshl_add_u64 v[216:217], s[30:31], 0, v[146:147]
	global_load_lds_dwordx4 v[214:215], off
	v_lshl_add_u64 v[214:215], s[56:57], 0, v[146:147]
	s_add_i32 m0, s58, 0x2000
	s_nop 0
	global_load_lds_dwordx4 v[214:215], off
	v_lshl_add_u64 v[214:215], s[30:31], 0, v[144:145]
	s_mov_b32 m0, s35
	s_nop 0
	global_load_lds_dwordx4 v[214:215], off
	s_mov_b32 m0, s36
	s_nop 0
	global_load_lds_dwordx4 v[216:217], off
	s_setprio 1
	s_waitcnt vmcnt(8)
	s_waitcnt lgkmcnt(0)
	s_barrier
; #define PG8_STAGE(bufoff, gbase, voff) do { _Pragma("unroll") for (int _i = 0; _i < 2; ++_i) \
;         __builtin_amdgcn_global_load_lds((const unsigned*)((const char*)(gbase) + (voff)[_i]), (PG8_LAS unsigned*)(lds + (bufoff) + ldsw + _i * 8192), 16, 0, 0); } while (0)
; #define PG8_LDA(dst, b, h) do { _Pragma("unroll") for (int m = 0; m < 4; ++m) _Pragma("unroll") for (int k = 0; k < 2; ++k) dst[m][k] = *(const PG8_LAS bf16x8*)(lds + PG8_SA(b, h) + aoff + m * 2048 + k * 1024); } while (0)
; #define PG8_LDB(dst, b, h) do { _Pragma("unroll") for (int n = 0; n < 2; ++n) _Pragma("unroll") for (int k = 0; k < 2; ++k) dst[n][k] = *(const PG8_LAS bf16x8*)(lds + PG8_SB(b, h) + boff + n * 2048 + k * 1024); } while (0)
; #define PG8_MMA(ai, bj, At, Bt) do { __builtin_amdgcn_s_setprio(1); _Pragma("unroll") for (int m = 0; m < 4; ++m) _Pragma("unroll") for (int n = 0; n < 2; ++n) _Pragma("unroll") for (int k = 0; k < 2; ++k) \
;         acc[ai][bj][m][n] = __builtin_amdgcn_mfma_f32_16x16x32_bf16(Bt[n][k], At[m][k], acc[ai][bj][m][n], 0, 0, 0); __builtin_amdgcn_s_setprio(0); } while (0)
; #define PG8_WAIT_V(n) asm volatile("s_waitcnt vmcnt(" #n ")" ::: "memory")
; template <class Epi, class Sched, bool ALIGN_EPI = false, bool SP2 = false>
; __device__ __forceinline__ void gemm_phase(PG8_LAS unsigned char* lds, const Gemm g, const Sched& S, const Epi& E) {
;     ...
;             PG8_LDB(B0, 0, 0); PG8_LDB(B1, 0, 1); PG8_SCHED; PG8_LDA(At, 0, 0); PG8_STAGE(PG8_SA(1, 1), a1 + hstep, voffA);
;             PG8_WAIT_V(8); PG8_WAIT_L(0); PG8_BAR; PG8_MMA(0, 0, At, B0); PG8_MMA(0, 1, At, B1); PG8_BAR; PG8_SCHED;
;             PG8_LDA(At, 0, 1); PG8_STAGE(PG8_SB(0, 0), b2, voffB); PG8_STAGE(PG8_SB(0, 1), b2 + hstep, voffB); PG8_STAGE(PG8_SA(0, 0), a2, voffA);
;             PG8_WAIT_V(8); PG8_WAIT_L(0); PG8_BAR; PG8_MMA(1, 0, At, B0); PG8_MMA(1, 1, At, B1); PG8_BAR; PG8_SCHED;
;             PG8_LDB(B0, 1, 0); PG8_LDB(B1, 1, 1); PG8_SCHED; PG8_LDA(At, 1, 0); PG8_STAGE(PG8_SA(0, 1), a2 + hstep, voffA);
;             PG8_WAIT_V(8); PG8_WAIT_L(0); PG8_BAR; PG8_MMA(0, 0, At, B0); PG8_MMA(0, 1, At, B1); PG8_BAR; PG8_SCHED;
;             PG8_LDA(At, 1, 1); PG8_STAGE(PG8_SB(1, 0), b3, voffB); PG8_STAGE(PG8_SB(1, 1), b3 + hstep, voffB); PG8_STAGE(PG8_SA(1, 0), a3, voffA);
;             PG8_WAIT_V(8); PG8_WAIT_L(0); PG8_BAR; PG8_MMA(1, 0, At, B0); PG8_MMA(1, 1, At, B1); PG8_BAR; PG8_SCHED;
	v_mfma_f32_16x16x32_bf16 v[60:63], v[64:67], v[180:183], 0
	v_mfma_f32_16x16x32_bf16 v[56:59], v[116:119], v[180:183], 0
	v_mfma_f32_16x16x32_bf16 v[44:47], v[64:67], v[188:191], 0
	v_mfma_f32_16x16x32_bf16 v[40:43], v[116:119], v[188:191], 0
	v_mfma_f32_16x16x32_bf16 v[28:31], v[64:67], v[196:199], 0
	v_mfma_f32_16x16x32_bf16 v[24:27], v[116:119], v[196:199], 0
	v_mfma_f32_16x16x32_bf16 v[12:15], v[64:67], v[204:207], 0
	v_mfma_f32_16x16x32_bf16 v[8:11], v[116:119], v[204:207], 0
	v_mfma_f32_16x16x32_bf16 v[60:63], v[108:111], v[184:187], v[60:63]
	v_mfma_f32_16x16x32_bf16 v[56:59], v[128:131], v[184:187], v[56:59]
	v_mfma_f32_16x16x32_bf16 v[44:47], v[108:111], v[192:195], v[44:47]
	v_mfma_f32_16x16x32_bf16 v[40:43], v[128:131], v[192:195], v[40:43]
	v_mfma_f32_16x16x32_bf16 v[28:31], v[108:111], v[200:203], v[28:31]
	v_mfma_f32_16x16x32_bf16 v[24:27], v[128:131], v[200:203], v[24:27]
	v_mfma_f32_16x16x32_bf16 v[12:15], v[108:111], v[208:211], v[12:15]
	v_mfma_f32_16x16x32_bf16 v[8:11], v[128:131], v[208:211], v[8:11]
	s_setprio 0
	s_setprio 1
	v_mfma_f32_16x16x32_bf16 v[52:55], v[156:159], v[180:183], 0
	v_mfma_f32_16x16x32_bf16 v[48:51], v[172:175], v[180:183], 0
	v_mfma_f32_16x16x32_bf16 v[36:39], v[156:159], v[188:191], 0
	v_mfma_f32_16x16x32_bf16 v[32:35], v[172:175], v[188:191], 0
	v_mfma_f32_16x16x32_bf16 v[20:23], v[156:159], v[196:199], 0
	v_mfma_f32_16x16x32_bf16 v[16:19], v[172:175], v[196:199], 0
	v_mfma_f32_16x16x32_bf16 v[4:7], v[156:159], v[204:207], 0
	v_mfma_f32_16x16x32_bf16 v[0:3], v[172:175], v[204:207], 0
	v_mfma_f32_16x16x32_bf16 v[52:55], v[168:171], v[184:187], v[52:55]
	v_mfma_f32_16x16x32_bf16 v[48:51], v[176:179], v[184:187], v[48:51]
	v_mfma_f32_16x16x32_bf16 v[36:39], v[168:171], v[192:195], v[36:39]
	v_mfma_f32_16x16x32_bf16 v[32:35], v[176:179], v[192:195], v[32:35]
	v_mfma_f32_16x16x32_bf16 v[20:23], v[168:171], v[200:203], v[20:23]
	v_mfma_f32_16x16x32_bf16 v[16:19], v[176:179], v[200:203], v[16:19]
	v_mfma_f32_16x16x32_bf16 v[4:7], v[168:171], v[208:211], v[4:7]
	v_mfma_f32_16x16x32_bf16 v[0:3], v[176:179], v[208:211], v[0:3]
	s_barrier
	s_setprio 0
	s_add_i32 s56, 0, 0x18000
	s_add_i32 s57, 0, 0x1c000
	v_add_u32_e32 v128, s56, v163
	v_add_u32_e32 v176, s57, v163
	ds_read_b128 v[64:67], v128
	ds_read_b128 v[108:111], v128 offset:1024
	ds_read_b128 v[116:119], v128 offset:2048
	ds_read_b128 v[128:131], v128 offset:3072
	ds_read_b128 v[156:159], v176
	ds_read_b128 v[168:171], v176 offset:1024
	ds_read_b128 v[172:175], v176 offset:2048
	ds_read_b128 v[176:179], v176 offset:3072
	s_add_u32 s30, s30, 0x200000
	s_addc_u32 s31, s31, 0
	s_mov_b32 m0, s37
	v_lshl_add_u64 v[218:219], s[30:31], 0, v[144:145]
	ds_read_b128 v[180:183], v167 offset:32768
	ds_read_b128 v[184:187], v167 offset:33792
	ds_read_b128 v[188:191], v167 offset:34816
	ds_read_b128 v[192:195], v167 offset:35840
	ds_read_b128 v[196:199], v167 offset:36864
	ds_read_b128 v[200:203], v167 offset:37888
	ds_read_b128 v[204:207], v167 offset:38912
	ds_read_b128 v[208:211], v167 offset:39936
	global_load_lds_dwordx4 v[218:219], off
	v_lshl_add_u64 v[218:219], s[30:31], 0, v[146:147]
	s_mov_b32 m0, s38
	s_nop 0
	global_load_lds_dwordx4 v[218:219], off
	s_setprio 1
	s_waitcnt vmcnt(8)
	s_waitcnt lgkmcnt(0)
	s_barrier
	v_mfma_f32_16x16x32_bf16 v[140:143], v[64:67], v[180:183], v[140:143]
	v_mfma_f32_16x16x32_bf16 v[136:139], v[116:119], v[180:183], v[136:139]
	v_mfma_f32_16x16x32_bf16 v[120:123], v[64:67], v[188:191], v[120:123]
	v_mfma_f32_16x16x32_bf16 v[112:115], v[116:119], v[188:191], v[112:115]
	v_mfma_f32_16x16x32_bf16 v[96:99], v[64:67], v[196:199], v[96:99]
	v_mfma_f32_16x16x32_bf16 v[92:95], v[116:119], v[196:199], v[92:95]
	v_mfma_f32_16x16x32_bf16 v[80:83], v[64:67], v[204:207], v[80:83]
	v_mfma_f32_16x16x32_bf16 v[76:79], v[116:119], v[204:207], v[76:79]
	v_mfma_f32_16x16x32_bf16 v[140:143], v[108:111], v[184:187], v[140:143]
	v_mfma_f32_16x16x32_bf16 v[136:139], v[128:131], v[184:187], v[136:139]
	v_mfma_f32_16x16x32_bf16 v[120:123], v[108:111], v[192:195], v[120:123]
	v_mfma_f32_16x16x32_bf16 v[112:115], v[128:131], v[192:195], v[112:115]
	v_mfma_f32_16x16x32_bf16 v[96:99], v[108:111], v[200:203], v[96:99]
	v_mfma_f32_16x16x32_bf16 v[92:95], v[128:131], v[200:203], v[92:95]
	v_mfma_f32_16x16x32_bf16 v[80:83], v[108:111], v[208:211], v[80:83]
	v_mfma_f32_16x16x32_bf16 v[76:79], v[128:131], v[208:211], v[76:79]
	s_setprio 0
	s_setprio 1
	v_mfma_f32_16x16x32_bf16 v[132:135], v[156:159], v[180:183], v[132:135]
	v_mfma_f32_16x16x32_bf16 v[124:127], v[172:175], v[180:183], v[124:127]
	v_mfma_f32_16x16x32_bf16 v[104:107], v[156:159], v[188:191], v[104:107]
	v_mfma_f32_16x16x32_bf16 v[100:103], v[172:175], v[188:191], v[100:103]
	v_mfma_f32_16x16x32_bf16 v[88:91], v[156:159], v[196:199], v[88:91]
	v_mfma_f32_16x16x32_bf16 v[84:87], v[172:175], v[196:199], v[84:87]
	v_mfma_f32_16x16x32_bf16 v[72:75], v[156:159], v[204:207], v[72:75]
	v_mfma_f32_16x16x32_bf16 v[68:71], v[172:175], v[204:207], v[68:71]
	v_mfma_f32_16x16x32_bf16 v[132:135], v[168:171], v[184:187], v[132:135]
	v_mfma_f32_16x16x32_bf16 v[124:127], v[176:179], v[184:187], v[124:127]
	v_mfma_f32_16x16x32_bf16 v[104:107], v[168:171], v[192:195], v[104:107]
	v_mfma_f32_16x16x32_bf16 v[100:103], v[176:179], v[192:195], v[100:103]
	v_mfma_f32_16x16x32_bf16 v[88:91], v[168:171], v[200:203], v[88:91]
	v_mfma_f32_16x16x32_bf16 v[84:87], v[176:179], v[200:203], v[84:87]
	v_mfma_f32_16x16x32_bf16 v[72:75], v[168:171], v[208:211], v[72:75]
	v_mfma_f32_16x16x32_bf16 v[68:71], v[176:179], v[208:211], v[68:71]
	s_barrier
; #define PG8_STAGE(bufoff, gbase, voff) do { _Pragma("unroll") for (int _i = 0; _i < 2; ++_i) \
;         __builtin_amdgcn_global_load_lds((const unsigned*)((const char*)(gbase) + (voff)[_i]), (PG8_LAS unsigned*)(lds + (bufoff) + ldsw + _i * 8192), 16, 0, 0); } while (0)
; #define PG8_LDA(dst, b, h) do { _Pragma("unroll") for (int m = 0; m < 4; ++m) _Pragma("unroll") for (int k = 0; k < 2; ++k) dst[m][k] = *(const PG8_LAS bf16x8*)(lds + PG8_SA(b, h) + aoff + m * 2048 + k * 1024); } while (0)
; #define PG8_LDB(dst, b, h) do { _Pragma("unroll") for (int n = 0; n < 2; ++n) _Pragma("unroll") for (int k = 0; k < 2; ++k) dst[n][k] = *(const PG8_LAS bf16x8*)(lds + PG8_SB(b, h) + boff + n * 2048 + k * 1024); } while (0)
; #define PG8_MMA(ai, bj, At, Bt) do { __builtin_amdgcn_s_setprio(1); _Pragma("unroll") for (int m = 0; m < 4; ++m) _Pragma("unroll") for (int n = 0; n < 2; ++n) _Pragma("unroll") for (int k = 0; k < 2; ++k) \
;         acc[ai][bj][m][n] = __builtin_amdgcn_mfma_f32_16x16x32_bf16(Bt[n][k], At[m][k], acc[ai][bj][m][n], 0, 0, 0); __builtin_amdgcn_s_setprio(0); } while (0)
; #define PG8_WAIT_V(n) asm volatile("s_waitcnt vmcnt(" #n ")" ::: "memory")
; template <class Epi, class Sched, bool ALIGN_EPI = false, bool SP2 = false>
; __device__ __forceinline__ void gemm_phase(PG8_LAS unsigned char* lds, const Gemm g, const Sched& S, const Epi& E) {
;     ...
;             PG8_LDB(B0, 0, 0); PG8_LDB(B1, 0, 1); PG8_SCHED; PG8_LDA(At, 0, 0); PG8_STAGE(PG8_SA(1, 1), a1 + hstep, voffA);
;             PG8_WAIT_V(8); PG8_WAIT_L(0); PG8_BAR; PG8_MMA(0, 0, At, B0); PG8_MMA(0, 1, At, B1); PG8_BAR; PG8_SCHED;
;             PG8_LDA(At, 0, 1); PG8_STAGE(PG8_SB(0, 0), b2, voffB); PG8_STAGE(PG8_SB(0, 1), b2 + hstep, voffB); PG8_STAGE(PG8_SA(0, 0), a2, voffA);
;             PG8_WAIT_V(8); PG8_WAIT_L(0); PG8_BAR; PG8_MMA(1, 0, At, B0); PG8_MMA(1, 1, At, B1); PG8_BAR; PG8_SCHED;
;             PG8_LDB(B0, 1, 0); PG8_LDB(B1, 1, 1); PG8_SCHED; PG8_LDA(At, 1, 0); PG8_STAGE(PG8_SA(0, 1), a2 + hstep, voffA);
;             PG8_WAIT_V(8); PG8_WAIT_L(0); PG8_BAR; PG8_MMA(0, 0, At, B0); PG8_MMA(0, 1, At, B1); PG8_BAR; PG8_SCHED;
;             PG8_LDA(At, 1, 1); PG8_STAGE(PG8_SB(1, 0), b3, voffB); PG8_STAGE(PG8_SB(1, 1), b3 + hstep, voffB); PG8_STAGE(PG8_SA(1, 0), a3, voffA);
;             PG8_WAIT_V(8); PG8_WAIT_L(0); PG8_BAR; PG8_MMA(1, 0, At, B0); PG8_MMA(1, 1, At, B1); PG8_BAR; PG8_SCHED;
	s_setprio 0
	s_add_i32 s30, s56, s34
	v_lshl_add_u64 v[160:161], v[160:161], 0, s[4:5]
	s_mov_b32 m0, s30
	ds_read_b128 v[180:183], v167 offset:49152
	ds_read_b128 v[184:187], v167 offset:50176
	ds_read_b128 v[188:191], v167 offset:51200
	ds_read_b128 v[192:195], v167 offset:52224
	ds_read_b128 v[196:199], v167 offset:53248
	ds_read_b128 v[200:203], v167 offset:54272
	ds_read_b128 v[204:207], v167 offset:55296
	ds_read_b128 v[208:211], v167 offset:56320
	global_load_lds_dwordx4 v[160:161], off
	s_add_i32 m0, s30, 0x2000
	s_add_u32 s28, s28, 0x200080
	v_lshl_add_u64 v[160:161], v[212:213], 0, s[4:5]
	s_addc_u32 s29, s29, 0
	s_add_i32 s30, s57, s34
	global_load_lds_dwordx4 v[160:161], off
	v_lshl_add_u64 v[160:161], s[28:29], 0, v[144:145]
	s_mov_b32 m0, s30
	s_nop 0
	global_load_lds_dwordx4 v[160:161], off
	v_lshl_add_u64 v[160:161], s[28:29], 0, v[146:147]
	s_add_i32 m0, s30, 0x2000
	s_nop 0
	global_load_lds_dwordx4 v[160:161], off
	v_lshl_add_u64 v[160:161], v[214:215], 0, s[4:5]
	s_mov_b32 m0, s42
	s_nop 0
	global_load_lds_dwordx4 v[160:161], off
	v_lshl_add_u64 v[160:161], v[216:217], 0, s[4:5]
	s_mov_b32 m0, s43
	s_nop 0
	global_load_lds_dwordx4 v[160:161], off
	s_setprio 1
	s_waitcnt vmcnt(8)
	s_waitcnt lgkmcnt(0)
	s_barrier
	v_mfma_f32_16x16x32_bf16 v[60:63], v[64:67], v[180:183], v[60:63]
	v_mfma_f32_16x16x32_bf16 v[56:59], v[116:119], v[180:183], v[56:59]
	v_mfma_f32_16x16x32_bf16 v[44:47], v[64:67], v[188:191], v[44:47]
	v_mfma_f32_16x16x32_bf16 v[40:43], v[116:119], v[188:191], v[40:43]
	v_mfma_f32_16x16x32_bf16 v[28:31], v[64:67], v[196:199], v[28:31]
	v_mfma_f32_16x16x32_bf16 v[24:27], v[116:119], v[196:199], v[24:27]
	v_mfma_f32_16x16x32_bf16 v[12:15], v[64:67], v[204:207], v[12:15]
	v_mfma_f32_16x16x32_bf16 v[8:11], v[116:119], v[204:207], v[8:11]
	v_mfma_f32_16x16x32_bf16 v[60:63], v[108:111], v[184:187], v[60:63]
	v_mfma_f32_16x16x32_bf16 v[56:59], v[128:131], v[184:187], v[56:59]
	v_mfma_f32_16x16x32_bf16 v[44:47], v[108:111], v[192:195], v[44:47]
	v_mfma_f32_16x16x32_bf16 v[40:43], v[128:131], v[192:195], v[40:43]
	v_mfma_f32_16x16x32_bf16 v[28:31], v[108:111], v[200:203], v[28:31]
	v_mfma_f32_16x16x32_bf16 v[24:27], v[128:131], v[200:203], v[24:27]
	v_mfma_f32_16x16x32_bf16 v[12:15], v[108:111], v[208:211], v[12:15]
	v_mfma_f32_16x16x32_bf16 v[8:11], v[128:131], v[208:211], v[8:11]
	s_setprio 0
	s_setprio 1
	v_mfma_f32_16x16x32_bf16 v[52:55], v[156:159], v[180:183], v[52:55]
	v_mfma_f32_16x16x32_bf16 v[48:51], v[172:175], v[180:183], v[48:51]
	v_mfma_f32_16x16x32_bf16 v[36:39], v[156:159], v[188:191], v[36:39]
	v_mfma_f32_16x16x32_bf16 v[32:35], v[172:175], v[188:191], v[32:35]
	v_mfma_f32_16x16x32_bf16 v[20:23], v[156:159], v[196:199], v[20:23]
	v_mfma_f32_16x16x32_bf16 v[16:19], v[172:175], v[196:199], v[16:19]
	v_mfma_f32_16x16x32_bf16 v[4:7], v[156:159], v[204:207], v[4:7]
	v_mfma_f32_16x16x32_bf16 v[0:3], v[172:175], v[204:207], v[0:3]
	v_mfma_f32_16x16x32_bf16 v[52:55], v[168:171], v[184:187], v[52:55]
	v_mfma_f32_16x16x32_bf16 v[48:51], v[176:179], v[184:187], v[48:51]
	v_mfma_f32_16x16x32_bf16 v[36:39], v[168:171], v[192:195], v[36:39]
	v_mfma_f32_16x16x32_bf16 v[32:35], v[176:179], v[192:195], v[32:35]
	v_mfma_f32_16x16x32_bf16 v[20:23], v[168:171], v[200:203], v[20:23]
	v_mfma_f32_16x16x32_bf16 v[16:19], v[176:179], v[200:203], v[16:19]
	v_mfma_f32_16x16x32_bf16 v[4:7], v[168:171], v[208:211], v[4:7]
	v_mfma_f32_16x16x32_bf16 v[0:3], v[176:179], v[208:211], v[0:3]
	s_barrier
	s_setprio 0
	s_add_i32 s55, s55, 2
	s_add_u32 s26, s26, 0x100
	s_addc_u32 s27, s27, 0
	s_add_u32 s53, s53, 0x100
	s_addc_u32 s54, s54, 0
	s_cmpk_gt_u32 s55, 0x7d
.LBB0_1071:
	ds_read_b128 v[64:67], v165
	ds_read_b128 v[108:111], v165 offset:1024
	ds_read_b128 v[116:119], v165 offset:2048
	ds_read_b128 v[128:131], v165 offset:3072
	ds_read_b128 v[156:159], v166
	ds_read_b128 v[168:171], v166 offset:1024
	ds_read_b128 v[172:175], v166 offset:2048
	ds_read_b128 v[176:179], v166 offset:3072
	s_add_u32 s28, s26, 0xffe00080
	s_addc_u32 s29, s27, -1
	s_cmpk_eq_i32 s55, 0x7c
	s_cselect_b32 s31, s19, s29
	s_cselect_b32 s30, s51, s28
	s_cselect_b32 s29, s17, s54
	s_cselect_b32 s28, s52, s53
	v_lshl_add_u64 v[160:161], s[26:27], 0, v[148:149]
	s_add_i32 m0, s35, 0xc000
	ds_read_b128 v[180:183], v167
	ds_read_b128 v[184:187], v167 offset:1024
	ds_read_b128 v[188:191], v167 offset:2048
	ds_read_b128 v[192:195], v167 offset:3072
	ds_read_b128 v[196:199], v167 offset:4096
	ds_read_b128 v[200:203], v167 offset:5120
	ds_read_b128 v[204:207], v167 offset:6144
	ds_read_b128 v[208:211], v167 offset:7168
	global_load_lds_dwordx4 v[160:161], off
	v_lshl_add_u64 v[160:161], s[26:27], 0, v[150:151]
	s_add_i32 m0, s35, 0xe000
	s_nop 0
	global_load_lds_dwordx4 v[160:161], off
	s_setprio 1
	s_waitcnt vmcnt(8)
	s_waitcnt lgkmcnt(0)
	s_barrier
; #define PG8_STAGE(bufoff, gbase, voff) do { _Pragma("unroll") for (int _i = 0; _i < 2; ++_i) \
;         __builtin_amdgcn_global_load_lds((const unsigned*)((const char*)(gbase) + (voff)[_i]), (PG8_LAS unsigned*)(lds + (bufoff) + ldsw + _i * 8192), 16, 0, 0); } while (0)
; #define PG8_LDA(dst, b, h) do { _Pragma("unroll") for (int m = 0; m < 4; ++m) _Pragma("unroll") for (int k = 0; k < 2; ++k) dst[m][k] = *(const PG8_LAS bf16x8*)(lds + PG8_SA(b, h) + aoff + m * 2048 + k * 1024); } while (0)
; #define PG8_LDB(dst, b, h) do { _Pragma("unroll") for (int n = 0; n < 2; ++n) _Pragma("unroll") for (int k = 0; k < 2; ++k) dst[n][k] = *(const PG8_LAS bf16x8*)(lds + PG8_SB(b, h) + boff + n * 2048 + k * 1024); } while (0)
; #define PG8_MMA(ai, bj, At, Bt) do { __builtin_amdgcn_s_setprio(1); _Pragma("unroll") for (int m = 0; m < 4; ++m) _Pragma("unroll") for (int n = 0; n < 2; ++n) _Pragma("unroll") for (int k = 0; k < 2; ++k) \
;         acc[ai][bj][m][n] = __builtin_amdgcn_mfma_f32_16x16x32_bf16(Bt[n][k], At[m][k], acc[ai][bj][m][n], 0, 0, 0); __builtin_amdgcn_s_setprio(0); } while (0)
; #define PG8_WAIT_V(n) asm volatile("s_waitcnt vmcnt(" #n ")" ::: "memory")
; template <class Epi, class Sched, bool ALIGN_EPI = false, bool SP2 = false>
; __device__ __forceinline__ void gemm_phase(PG8_LAS unsigned char* lds, const Gemm g, const Sched& S, const Epi& E) {
;     ...
;             PG8_LDB(B0, 0, 0); PG8_LDB(B1, 0, 1); PG8_SCHED; PG8_LDA(At, 0, 0); PG8_STAGE(PG8_SA(1, 1), a1 + hstep, voffA);
;             PG8_WAIT_V(8); PG8_WAIT_L(0); PG8_BAR; PG8_MMA(0, 0, At, B0); PG8_MMA(0, 1, At, B1); PG8_BAR; PG8_SCHED;
;             PG8_LDA(At, 0, 1); PG8_STAGE(PG8_SB(0, 0), b2, voffB); PG8_STAGE(PG8_SB(0, 1), b2 + hstep, voffB); PG8_STAGE(PG8_SA(0, 0), a2, voffA);
;             PG8_WAIT_V(8); PG8_WAIT_L(0); PG8_BAR; PG8_MMA(1, 0, At, B0); PG8_MMA(1, 1, At, B1); PG8_BAR; PG8_SCHED;
;             PG8_LDB(B0, 1, 0); PG8_LDB(B1, 1, 1); PG8_SCHED; PG8_LDA(At, 1, 0); PG8_STAGE(PG8_SA(0, 1), a2 + hstep, voffA);
;             PG8_WAIT_V(8); PG8_WAIT_L(0); PG8_BAR; PG8_MMA(0, 0, At, B0); PG8_MMA(0, 1, At, B1); PG8_BAR; PG8_SCHED;
;             PG8_LDA(At, 1, 1); PG8_STAGE(PG8_SB(1, 0), b3, voffB); PG8_STAGE(PG8_SB(1, 1), b3 + hstep, voffB); PG8_STAGE(PG8_SA(1, 0), a3, voffA);
;             PG8_WAIT_V(8); PG8_WAIT_L(0); PG8_BAR; PG8_MMA(1, 0, At, B0); PG8_MMA(1, 1, At, B1); PG8_BAR; PG8_SCHED;
	v_mfma_f32_16x16x32_bf16 v[140:143], v[64:67], v[180:183], v[140:143]
	v_mfma_f32_16x16x32_bf16 v[136:139], v[116:119], v[180:183], v[136:139]
	v_mfma_f32_16x16x32_bf16 v[120:123], v[64:67], v[188:191], v[120:123]
	v_mfma_f32_16x16x32_bf16 v[112:115], v[116:119], v[188:191], v[112:115]
	v_mfma_f32_16x16x32_bf16 v[96:99], v[64:67], v[196:199], v[96:99]
	v_mfma_f32_16x16x32_bf16 v[92:95], v[116:119], v[196:199], v[92:95]
	v_mfma_f32_16x16x32_bf16 v[80:83], v[64:67], v[204:207], v[80:83]
	v_mfma_f32_16x16x32_bf16 v[76:79], v[116:119], v[204:207], v[76:79]
	v_mfma_f32_16x16x32_bf16 v[140:143], v[108:111], v[184:187], v[140:143]
	v_mfma_f32_16x16x32_bf16 v[136:139], v[128:131], v[184:187], v[136:139]
	v_mfma_f32_16x16x32_bf16 v[120:123], v[108:111], v[192:195], v[120:123]
	v_mfma_f32_16x16x32_bf16 v[112:115], v[128:131], v[192:195], v[112:115]
	v_mfma_f32_16x16x32_bf16 v[96:99], v[108:111], v[200:203], v[96:99]
	v_mfma_f32_16x16x32_bf16 v[92:95], v[128:131], v[200:203], v[92:95]
	v_mfma_f32_16x16x32_bf16 v[80:83], v[108:111], v[208:211], v[80:83]
	v_mfma_f32_16x16x32_bf16 v[76:79], v[128:131], v[208:211], v[76:79]
	s_setprio 0
	s_setprio 1
	v_mfma_f32_16x16x32_bf16 v[132:135], v[156:159], v[180:183], v[132:135]
	v_mfma_f32_16x16x32_bf16 v[124:127], v[172:175], v[180:183], v[124:127]
	v_mfma_f32_16x16x32_bf16 v[104:107], v[156:159], v[188:191], v[104:107]
	v_mfma_f32_16x16x32_bf16 v[100:103], v[172:175], v[188:191], v[100:103]
	v_mfma_f32_16x16x32_bf16 v[88:91], v[156:159], v[196:199], v[88:91]
	v_mfma_f32_16x16x32_bf16 v[84:87], v[172:175], v[196:199], v[84:87]
	v_mfma_f32_16x16x32_bf16 v[72:75], v[156:159], v[204:207], v[72:75]
	v_mfma_f32_16x16x32_bf16 v[68:71], v[172:175], v[204:207], v[68:71]
	v_mfma_f32_16x16x32_bf16 v[132:135], v[168:171], v[184:187], v[132:135]
	v_mfma_f32_16x16x32_bf16 v[124:127], v[176:179], v[184:187], v[124:127]
	v_mfma_f32_16x16x32_bf16 v[104:107], v[168:171], v[192:195], v[104:107]
	v_mfma_f32_16x16x32_bf16 v[100:103], v[176:179], v[192:195], v[100:103]
	v_mfma_f32_16x16x32_bf16 v[88:91], v[168:171], v[200:203], v[88:91]
	v_mfma_f32_16x16x32_bf16 v[84:87], v[176:179], v[200:203], v[84:87]
	v_mfma_f32_16x16x32_bf16 v[72:75], v[168:171], v[208:211], v[72:75]
	v_mfma_f32_16x16x32_bf16 v[68:71], v[176:179], v[208:211], v[68:71]
	s_barrier
	s_setprio 0
	s_add_i32 s56, s45, s34
	v_lshl_add_u64 v[160:161], s[28:29], 0, v[144:145]
	s_mov_b32 m0, s56
	ds_read_b128 v[180:183], v167 offset:16384
	ds_read_b128 v[184:187], v167 offset:17408
	ds_read_b128 v[188:191], v167 offset:18432
	ds_read_b128 v[192:195], v167 offset:19456
	ds_read_b128 v[196:199], v167 offset:20480
	ds_read_b128 v[200:203], v167 offset:21504
	ds_read_b128 v[204:207], v167 offset:22528
	ds_read_b128 v[208:211], v167 offset:23552
	global_load_lds_dwordx4 v[160:161], off
	s_add_i32 m0, s56, 0x2000
	s_add_u32 s56, s28, 0x200000
	v_lshl_add_u64 v[212:213], s[28:29], 0, v[146:147]
	s_addc_u32 s57, s29, 0
	s_add_i32 s58, s46, s34
	global_load_lds_dwordx4 v[212:213], off
	v_lshl_add_u64 v[214:215], s[56:57], 0, v[144:145]
	s_mov_b32 m0, s58
	v_lshl_add_u64 v[216:217], s[30:31], 0, v[146:147]
	global_load_lds_dwordx4 v[214:215], off
	v_lshl_add_u64 v[214:215], s[56:57], 0, v[146:147]
	s_add_i32 m0, s58, 0x2000
	s_nop 0
	global_load_lds_dwordx4 v[214:215], off
	v_lshl_add_u64 v[214:215], s[30:31], 0, v[144:145]
	s_mov_b32 m0, s35
	s_nop 0
	global_load_lds_dwordx4 v[214:215], off
	s_mov_b32 m0, s36
	s_nop 0
	global_load_lds_dwordx4 v[216:217], off
	s_setprio 1
	s_waitcnt vmcnt(8)
	s_waitcnt lgkmcnt(0)
	s_barrier
	v_mfma_f32_16x16x32_bf16 v[60:63], v[64:67], v[180:183], v[60:63]
	v_mfma_f32_16x16x32_bf16 v[56:59], v[116:119], v[180:183], v[56:59]
	v_mfma_f32_16x16x32_bf16 v[44:47], v[64:67], v[188:191], v[44:47]
	v_mfma_f32_16x16x32_bf16 v[40:43], v[116:119], v[188:191], v[40:43]
	v_mfma_f32_16x16x32_bf16 v[28:31], v[64:67], v[196:199], v[28:31]
	v_mfma_f32_16x16x32_bf16 v[24:27], v[116:119], v[196:199], v[24:27]
	v_mfma_f32_16x16x32_bf16 v[12:15], v[64:67], v[204:207], v[12:15]
	v_mfma_f32_16x16x32_bf16 v[8:11], v[116:119], v[204:207], v[8:11]
	v_mfma_f32_16x16x32_bf16 v[60:63], v[108:111], v[184:187], v[60:63]
	v_mfma_f32_16x16x32_bf16 v[56:59], v[128:131], v[184:187], v[56:59]
	v_mfma_f32_16x16x32_bf16 v[44:47], v[108:111], v[192:195], v[44:47]
	v_mfma_f32_16x16x32_bf16 v[40:43], v[128:131], v[192:195], v[40:43]
	v_mfma_f32_16x16x32_bf16 v[28:31], v[108:111], v[200:203], v[28:31]
	v_mfma_f32_16x16x32_bf16 v[24:27], v[128:131], v[200:203], v[24:27]
	v_mfma_f32_16x16x32_bf16 v[12:15], v[108:111], v[208:211], v[12:15]
	v_mfma_f32_16x16x32_bf16 v[8:11], v[128:131], v[208:211], v[8:11]
	s_setprio 0
	s_setprio 1
	v_mfma_f32_16x16x32_bf16 v[52:55], v[156:159], v[180:183], v[52:55]
	v_mfma_f32_16x16x32_bf16 v[48:51], v[172:175], v[180:183], v[48:51]
	v_mfma_f32_16x16x32_bf16 v[36:39], v[156:159], v[188:191], v[36:39]
	v_mfma_f32_16x16x32_bf16 v[32:35], v[172:175], v[188:191], v[32:35]
	v_mfma_f32_16x16x32_bf16 v[20:23], v[156:159], v[196:199], v[20:23]
	v_mfma_f32_16x16x32_bf16 v[16:19], v[172:175], v[196:199], v[16:19]
	v_mfma_f32_16x16x32_bf16 v[4:7], v[156:159], v[204:207], v[4:7]
	v_mfma_f32_16x16x32_bf16 v[0:3], v[172:175], v[204:207], v[0:3]
	v_mfma_f32_16x16x32_bf16 v[52:55], v[168:171], v[184:187], v[52:55]
	v_mfma_f32_16x16x32_bf16 v[48:51], v[176:179], v[184:187], v[48:51]
	v_mfma_f32_16x16x32_bf16 v[36:39], v[168:171], v[192:195], v[36:39]
	v_mfma_f32_16x16x32_bf16 v[32:35], v[176:179], v[192:195], v[32:35]
	v_mfma_f32_16x16x32_bf16 v[20:23], v[168:171], v[200:203], v[20:23]
	v_mfma_f32_16x16x32_bf16 v[16:19], v[176:179], v[200:203], v[16:19]
	v_mfma_f32_16x16x32_bf16 v[4:7], v[168:171], v[208:211], v[4:7]
	v_mfma_f32_16x16x32_bf16 v[0:3], v[176:179], v[208:211], v[0:3]
	s_barrier
; #define PG8_STAGE(bufoff, gbase, voff) do { _Pragma("unroll") for (int _i = 0; _i < 2; ++_i) \
;         __builtin_amdgcn_global_load_lds((const unsigned*)((const char*)(gbase) + (voff)[_i]), (PG8_LAS unsigned*)(lds + (bufoff) + ldsw + _i * 8192), 16, 0, 0); } while (0)
; #define PG8_LDA(dst, b, h) do { _Pragma("unroll") for (int m = 0; m < 4; ++m) _Pragma("unroll") for (int k = 0; k < 2; ++k) dst[m][k] = *(const PG8_LAS bf16x8*)(lds + PG8_SA(b, h) + aoff + m * 2048 + k * 1024); } while (0)
; #define PG8_LDB(dst, b, h) do { _Pragma("unroll") for (int n = 0; n < 2; ++n) _Pragma("unroll") for (int k = 0; k < 2; ++k) dst[n][k] = *(const PG8_LAS bf16x8*)(lds + PG8_SB(b, h) + boff + n * 2048 + k * 1024); } while (0)
; #define PG8_MMA(ai, bj, At, Bt) do { __builtin_amdgcn_s_setprio(1); _Pragma("unroll") for (int m = 0; m < 4; ++m) _Pragma("unroll") for (int n = 0; n < 2; ++n) _Pragma("unroll") for (int k = 0; k < 2; ++k) \
;         acc[ai][bj][m][n] = __builtin_amdgcn_mfma_f32_16x16x32_bf16(Bt[n][k], At[m][k], acc[ai][bj][m][n], 0, 0, 0); __builtin_amdgcn_s_setprio(0); } while (0)
; #define PG8_WAIT_V(n) asm volatile("s_waitcnt vmcnt(" #n ")" ::: "memory")
; template <class Epi, class Sched, bool ALIGN_EPI = false, bool SP2 = false>
; __device__ __forceinline__ void gemm_phase(PG8_LAS unsigned char* lds, const Gemm g, const Sched& S, const Epi& E) {
;     ...
;             PG8_LDB(B0, 0, 0); PG8_LDB(B1, 0, 1); PG8_SCHED; PG8_LDA(At, 0, 0); PG8_STAGE(PG8_SA(1, 1), a1 + hstep, voffA);
;             PG8_WAIT_V(8); PG8_WAIT_L(0); PG8_BAR; PG8_MMA(0, 0, At, B0); PG8_MMA(0, 1, At, B1); PG8_BAR; PG8_SCHED;
;             PG8_LDA(At, 0, 1); PG8_STAGE(PG8_SB(0, 0), b2, voffB); PG8_STAGE(PG8_SB(0, 1), b2 + hstep, voffB); PG8_STAGE(PG8_SA(0, 0), a2, voffA);
;             PG8_WAIT_V(8); PG8_WAIT_L(0); PG8_BAR; PG8_MMA(1, 0, At, B0); PG8_MMA(1, 1, At, B1); PG8_BAR; PG8_SCHED;
;             PG8_LDB(B0, 1, 0); PG8_LDB(B1, 1, 1); PG8_SCHED; PG8_LDA(At, 1, 0); PG8_STAGE(PG8_SA(0, 1), a2 + hstep, voffA);
;             PG8_WAIT_V(8); PG8_WAIT_L(0); PG8_BAR; PG8_MMA(0, 0, At, B0); PG8_MMA(0, 1, At, B1); PG8_BAR; PG8_SCHED;
;             PG8_LDA(At, 1, 1); PG8_STAGE(PG8_SB(1, 0), b3, voffB); PG8_STAGE(PG8_SB(1, 1), b3 + hstep, voffB); PG8_STAGE(PG8_SA(1, 0), a3, voffA);
;             PG8_WAIT_V(8); PG8_WAIT_L(0); PG8_BAR; PG8_MMA(1, 0, At, B0); PG8_MMA(1, 1, At, B1); PG8_BAR; PG8_SCHED;
	s_setprio 0
	s_add_i32 s56, 0, 0x18000
	s_add_i32 s57, 0, 0x1c000
	v_add_u32_e32 v128, s56, v163
	v_add_u32_e32 v176, s57, v163
	ds_read_b128 v[64:67], v128
	ds_read_b128 v[108:111], v128 offset:1024
	ds_read_b128 v[116:119], v128 offset:2048
	ds_read_b128 v[128:131], v128 offset:3072
	ds_read_b128 v[156:159], v176
	ds_read_b128 v[168:171], v176 offset:1024
	ds_read_b128 v[172:175], v176 offset:2048
	ds_read_b128 v[176:179], v176 offset:3072
	s_add_u32 s30, s30, 0x200000
	s_addc_u32 s31, s31, 0
	s_mov_b32 m0, s37
	v_lshl_add_u64 v[218:219], s[30:31], 0, v[144:145]
	ds_read_b128 v[180:183], v167 offset:32768
	ds_read_b128 v[184:187], v167 offset:33792
	ds_read_b128 v[188:191], v167 offset:34816
	ds_read_b128 v[192:195], v167 offset:35840
	ds_read_b128 v[196:199], v167 offset:36864
	ds_read_b128 v[200:203], v167 offset:37888
	ds_read_b128 v[204:207], v167 offset:38912
	ds_read_b128 v[208:211], v167 offset:39936
	global_load_lds_dwordx4 v[218:219], off
	v_lshl_add_u64 v[218:219], s[30:31], 0, v[146:147]
	s_mov_b32 m0, s38
	s_nop 0
	global_load_lds_dwordx4 v[218:219], off
	s_setprio 1
	s_waitcnt vmcnt(8)
	s_waitcnt lgkmcnt(0)
	s_barrier
	v_mfma_f32_16x16x32_bf16 v[140:143], v[64:67], v[180:183], v[140:143]
	v_mfma_f32_16x16x32_bf16 v[136:139], v[116:119], v[180:183], v[136:139]
	v_mfma_f32_16x16x32_bf16 v[120:123], v[64:67], v[188:191], v[120:123]
	v_mfma_f32_16x16x32_bf16 v[112:115], v[116:119], v[188:191], v[112:115]
	v_mfma_f32_16x16x32_bf16 v[96:99], v[64:67], v[196:199], v[96:99]
	v_mfma_f32_16x16x32_bf16 v[92:95], v[116:119], v[196:199], v[92:95]
	v_mfma_f32_16x16x32_bf16 v[80:83], v[64:67], v[204:207], v[80:83]
	v_mfma_f32_16x16x32_bf16 v[76:79], v[116:119], v[204:207], v[76:79]
	v_mfma_f32_16x16x32_bf16 v[140:143], v[108:111], v[184:187], v[140:143]
	v_mfma_f32_16x16x32_bf16 v[136:139], v[128:131], v[184:187], v[136:139]
	v_mfma_f32_16x16x32_bf16 v[120:123], v[108:111], v[192:195], v[120:123]
	v_mfma_f32_16x16x32_bf16 v[112:115], v[128:131], v[192:195], v[112:115]
	v_mfma_f32_16x16x32_bf16 v[96:99], v[108:111], v[200:203], v[96:99]
	v_mfma_f32_16x16x32_bf16 v[92:95], v[128:131], v[200:203], v[92:95]
	v_mfma_f32_16x16x32_bf16 v[80:83], v[108:111], v[208:211], v[80:83]
	v_mfma_f32_16x16x32_bf16 v[76:79], v[128:131], v[208:211], v[76:79]
	s_setprio 0
	s_setprio 1
	v_mfma_f32_16x16x32_bf16 v[132:135], v[156:159], v[180:183], v[132:135]
	v_mfma_f32_16x16x32_bf16 v[124:127], v[172:175], v[180:183], v[124:127]
	v_mfma_f32_16x16x32_bf16 v[104:107], v[156:159], v[188:191], v[104:107]
	v_mfma_f32_16x16x32_bf16 v[100:103], v[172:175], v[188:191], v[100:103]
	v_mfma_f32_16x16x32_bf16 v[88:91], v[156:159], v[196:199], v[88:91]
	v_mfma_f32_16x16x32_bf16 v[84:87], v[172:175], v[196:199], v[84:87]
	v_mfma_f32_16x16x32_bf16 v[72:75], v[156:159], v[204:207], v[72:75]
	v_mfma_f32_16x16x32_bf16 v[68:71], v[172:175], v[204:207], v[68:71]
	v_mfma_f32_16x16x32_bf16 v[132:135], v[168:171], v[184:187], v[132:135]
	v_mfma_f32_16x16x32_bf16 v[124:127], v[176:179], v[184:187], v[124:127]
	v_mfma_f32_16x16x32_bf16 v[104:107], v[168:171], v[192:195], v[104:107]
	v_mfma_f32_16x16x32_bf16 v[100:103], v[176:179], v[192:195], v[100:103]
	v_mfma_f32_16x16x32_bf16 v[88:91], v[168:171], v[200:203], v[88:91]
	v_mfma_f32_16x16x32_bf16 v[84:87], v[176:179], v[200:203], v[84:87]
	v_mfma_f32_16x16x32_bf16 v[72:75], v[168:171], v[208:211], v[72:75]
	v_mfma_f32_16x16x32_bf16 v[68:71], v[176:179], v[208:211], v[68:71]
	s_barrier
; #define PG8_STAGE(bufoff, gbase, voff) do { _Pragma("unroll") for (int _i = 0; _i < 2; ++_i) \
;         __builtin_amdgcn_global_load_lds((const unsigned*)((const char*)(gbase) + (voff)[_i]), (PG8_LAS unsigned*)(lds + (bufoff) + ldsw + _i * 8192), 16, 0, 0); } while (0)
; #define PG8_LDA(dst, b, h) do { _Pragma("unroll") for (int m = 0; m < 4; ++m) _Pragma("unroll") for (int k = 0; k < 2; ++k) dst[m][k] = *(const PG8_LAS bf16x8*)(lds + PG8_SA(b, h) + aoff + m * 2048 + k * 1024); } while (0)
; #define PG8_LDB(dst, b, h) do { _Pragma("unroll") for (int n = 0; n < 2; ++n) _Pragma("unroll") for (int k = 0; k < 2; ++k) dst[n][k] = *(const PG8_LAS bf16x8*)(lds + PG8_SB(b, h) + boff + n * 2048 + k * 1024); } while (0)
; #define PG8_MMA(ai, bj, At, Bt) do { __builtin_amdgcn_s_setprio(1); _Pragma("unroll") for (int m = 0; m < 4; ++m) _Pragma("unroll") for (int n = 0; n < 2; ++n) _Pragma("unroll") for (int k = 0; k < 2; ++k) \
;         acc[ai][bj][m][n] = __builtin_amdgcn_mfma_f32_16x16x32_bf16(Bt[n][k], At[m][k], acc[ai][bj][m][n], 0, 0, 0); __builtin_amdgcn_s_setprio(0); } while (0)
; template <class Epi, class Sched, bool ALIGN_EPI = false, bool SP2 = false>
; __device__ __forceinline__ void gemm_phase(PG8_LAS unsigned char* lds, const Gemm g, const Sched& S, const Epi& E) {
;     ...
;             PG8_LDB(B0, 0, 0); PG8_LDB(B1, 0, 1); PG8_SCHED; PG8_LDA(At, 0, 0); PG8_STAGE(PG8_SA(1, 1), a1 + hstep, voffA);
;             PG8_WAIT_V(8); PG8_WAIT_L(0); PG8_BAR; PG8_MMA(0, 0, At, B0); PG8_MMA(0, 1, At, B1); PG8_BAR; PG8_SCHED;
;             PG8_LDA(At, 0, 1); PG8_STAGE(PG8_SB(0, 0), b2, voffB); PG8_STAGE(PG8_SB(0, 1), b2 + hstep, voffB); PG8_STAGE(PG8_SA(0, 0), a2, voffA);
;             PG8_WAIT_V(8); PG8_WAIT_L(0); PG8_BAR; PG8_MMA(1, 0, At, B0); PG8_MMA(1, 1, At, B1); PG8_BAR; PG8_SCHED;
;             PG8_LDB(B0, 1, 0); PG8_LDB(B1, 1, 1); PG8_SCHED; PG8_LDA(At, 1, 0); PG8_STAGE(PG8_SA(0, 1), a2 + hstep, voffA);
;             PG8_WAIT_V(8); PG8_WAIT_L(0); PG8_BAR; PG8_MMA(0, 0, At, B0); PG8_MMA(0, 1, At, B1); PG8_BAR; PG8_SCHED;
;             PG8_LDA(At, 1, 1); PG8_STAGE(PG8_SB(1, 0), b3, voffB); PG8_STAGE(PG8_SB(1, 1), b3 + hstep, voffB); PG8_STAGE(PG8_SA(1, 0), a3, voffA);
;             PG8_WAIT_V(8); PG8_WAIT_L(0); PG8_BAR; PG8_MMA(1, 0, At, B0); PG8_MMA(1, 1, At, B1); PG8_BAR; PG8_SCHED;
;     ...
;         if constexpr (ALIGN_EPI) { if (wr == 0) PG8_BAR; }
	s_setprio 0
	s_add_i32 s30, s56, s34
	v_lshl_add_u64 v[160:161], v[160:161], 0, s[4:5]
	s_mov_b32 m0, s30
	ds_read_b128 v[180:183], v167 offset:49152
	ds_read_b128 v[184:187], v167 offset:50176
	ds_read_b128 v[188:191], v167 offset:51200
	ds_read_b128 v[192:195], v167 offset:52224
	ds_read_b128 v[196:199], v167 offset:53248
	ds_read_b128 v[200:203], v167 offset:54272
	ds_read_b128 v[204:207], v167 offset:55296
	ds_read_b128 v[208:211], v167 offset:56320
	global_load_lds_dwordx4 v[160:161], off
	s_add_i32 m0, s30, 0x2000
	s_add_u32 s28, s28, 0x200080
	v_lshl_add_u64 v[160:161], v[212:213], 0, s[4:5]
	s_addc_u32 s29, s29, 0
	s_add_i32 s30, s57, s34
	global_load_lds_dwordx4 v[160:161], off
	v_lshl_add_u64 v[160:161], s[28:29], 0, v[144:145]
	s_mov_b32 m0, s30
	s_nop 0
	global_load_lds_dwordx4 v[160:161], off
	v_lshl_add_u64 v[160:161], s[28:29], 0, v[146:147]
	s_add_i32 m0, s30, 0x2000
	s_nop 0
	global_load_lds_dwordx4 v[160:161], off
	v_lshl_add_u64 v[160:161], v[214:215], 0, s[4:5]
	s_mov_b32 m0, s42
	s_nop 0
	global_load_lds_dwordx4 v[160:161], off
	v_lshl_add_u64 v[160:161], v[216:217], 0, s[4:5]
	s_mov_b32 m0, s43
	s_nop 0
	global_load_lds_dwordx4 v[160:161], off
	s_setprio 1
	s_waitcnt vmcnt(8)
	s_waitcnt lgkmcnt(0)
	s_barrier
	v_mfma_f32_16x16x32_bf16 v[60:63], v[64:67], v[180:183], v[60:63]
	v_mfma_f32_16x16x32_bf16 v[56:59], v[116:119], v[180:183], v[56:59]
	v_mfma_f32_16x16x32_bf16 v[44:47], v[64:67], v[188:191], v[44:47]
	v_mfma_f32_16x16x32_bf16 v[40:43], v[116:119], v[188:191], v[40:43]
	v_mfma_f32_16x16x32_bf16 v[28:31], v[64:67], v[196:199], v[28:31]
	v_mfma_f32_16x16x32_bf16 v[24:27], v[116:119], v[196:199], v[24:27]
	v_mfma_f32_16x16x32_bf16 v[12:15], v[64:67], v[204:207], v[12:15]
	v_mfma_f32_16x16x32_bf16 v[8:11], v[116:119], v[204:207], v[8:11]
	v_mfma_f32_16x16x32_bf16 v[60:63], v[108:111], v[184:187], v[60:63]
	v_mfma_f32_16x16x32_bf16 v[56:59], v[128:131], v[184:187], v[56:59]
	v_mfma_f32_16x16x32_bf16 v[44:47], v[108:111], v[192:195], v[44:47]
	v_mfma_f32_16x16x32_bf16 v[40:43], v[128:131], v[192:195], v[40:43]
	v_mfma_f32_16x16x32_bf16 v[28:31], v[108:111], v[200:203], v[28:31]
	v_mfma_f32_16x16x32_bf16 v[24:27], v[128:131], v[200:203], v[24:27]
	v_mfma_f32_16x16x32_bf16 v[12:15], v[108:111], v[208:211], v[12:15]
	v_mfma_f32_16x16x32_bf16 v[8:11], v[128:131], v[208:211], v[8:11]
	s_setprio 0
	s_setprio 1
	v_mfma_f32_16x16x32_bf16 v[52:55], v[156:159], v[180:183], v[52:55]
	v_mfma_f32_16x16x32_bf16 v[48:51], v[172:175], v[180:183], v[48:51]
	v_mfma_f32_16x16x32_bf16 v[36:39], v[156:159], v[188:191], v[36:39]
	v_mfma_f32_16x16x32_bf16 v[32:35], v[172:175], v[188:191], v[32:35]
	v_mfma_f32_16x16x32_bf16 v[20:23], v[156:159], v[196:199], v[20:23]
	v_mfma_f32_16x16x32_bf16 v[16:19], v[172:175], v[196:199], v[16:19]
	v_mfma_f32_16x16x32_bf16 v[4:7], v[156:159], v[204:207], v[4:7]
	v_mfma_f32_16x16x32_bf16 v[0:3], v[172:175], v[204:207], v[0:3]
	v_mfma_f32_16x16x32_bf16 v[52:55], v[168:171], v[184:187], v[52:55]
	v_mfma_f32_16x16x32_bf16 v[48:51], v[176:179], v[184:187], v[48:51]
	v_mfma_f32_16x16x32_bf16 v[36:39], v[168:171], v[192:195], v[36:39]
	v_mfma_f32_16x16x32_bf16 v[32:35], v[176:179], v[192:195], v[32:35]
	v_mfma_f32_16x16x32_bf16 v[20:23], v[168:171], v[200:203], v[20:23]
	v_mfma_f32_16x16x32_bf16 v[16:19], v[176:179], v[200:203], v[16:19]
	v_mfma_f32_16x16x32_bf16 v[4:7], v[168:171], v[208:211], v[4:7]
	v_mfma_f32_16x16x32_bf16 v[0:3], v[176:179], v[208:211], v[0:3]
	s_barrier
	s_setprio 0
	s_add_i32 s55, s55, 2
	s_add_u32 s26, s26, 0x100
	s_addc_u32 s27, s27, 0
	s_add_u32 s53, s53, 0x100
	s_addc_u32 s54, s54, 0
	s_cmpk_gt_u32 s55, 0x7d
	s_cbranch_scc0 .LBB0_1071
	s_and_b64 vcc, exec, s[6:7]
	s_cbranch_vccz .LBB0_1074
	s_barrier
